# baseline (speedup 1.0000x reference)
; #define BIG_SYNC(N)                                              \
;   asm volatile("s_waitcnt vmcnt(%0)" ::"n"(N) : "memory");       \
;   __builtin_amdgcn_s_barrier();                                  \
;   asm volatile("" ::: "memory");                                 \
;   __builtin_amdgcn_sched_barrier(0);
; template <int NK, bool BNT = false> ...
;     ...
;   auto kstep = [&](int T, int cur, int nxt, bool do_stage) {
;     const unsigned char* sa = smem + cur * BIG_STAGE;
;     bf16x8 af[4], bfr[4];
; #pragma unroll
;     for (int m = 0; m < 4; ++m) af[m] = *reinterpret_cast<const bf16x8*>(sa + aoff + m * 1024);
; #pragma unroll
;     for (int n = 0; n < 4; ++n) bfr[n] = *reinterpret_cast<const bf16x8*>(sa + boff + n * 1024);
;     __builtin_amdgcn_sched_barrier(0);
;     if (do_stage) stage(T + 3, nxt);
; #pragma unroll
;     for (int m = 0; m < 4; ++m)
; #pragma unroll
;       for (int n = 0; n < 4; ++n) acc[m][n] = __builtin_amdgcn_mfma_f32_16x16x32_bf16(af[m], bfr[n], acc[m][n], 0, 0, 0);
;     if (do_stage) {
; #pragma unroll
;       for (int q = 0; q < NG; ++q) {
;         __builtin_amdgcn_sched_group_barrier(0x008, 3, 0);
;         __builtin_amdgcn_sched_group_barrier(0x010, 1, 0);
;       }
;       __builtin_amdgcn_sched_group_barrier(0x008, 16 - 3 * NG, 0);
;     }
;     __builtin_amdgcn_sched_barrier(0);
; #pragma unroll
;     for (int n = 0; n < 4; ++n) bfr[n] = *reinterpret_cast<const bf16x8*>(sa + boff + (4 + n) * 1024);
; #pragma unroll
;     for (int m = 0; m < 4; ++m)
; #pragma unroll
;       for (int n = 0; n < 4; ++n)
;         acc[m][4 + n] = __builtin_amdgcn_mfma_f32_16x16x32_bf16(af[m], bfr[n], acc[m][4 + n], 0, 0, 0);
;     __builtin_amdgcn_sched_barrier(0);
;   };
;     ...
;   stage(0, 0);
;   stage(1, 1);
;   stage(2, 2);
;   for (int it = 0; it < NK / 4 - 1; ++it) {
;     const int t = it * 4;
;     BIG_SYNC(2 * NG); kstep(t, 0, 3, true);
;     BIG_SYNC(2 * NG); kstep(t + 1, 1, 0, true);
;     BIG_SYNC(2 * NG); kstep(t + 2, 2, 1, true);
;     BIG_SYNC(2 * NG); kstep(t + 3, 3, 2, true);
;   }
.LBB0_68:
	v_add_u32_e32 v158, 0x18000, v166
	v_lshl_add_u64 v[144:145], v[138:139], 0, s[36:37]
	v_readfirstlane_b32 s9, v158
	v_add_u32_e32 v159, 0x1a000, v166
	v_lshl_add_u64 v[160:161], v[144:145], 0, s[60:61]
	s_mov_b32 m0, s9
	v_readfirstlane_b32 s9, v159
	s_waitcnt lgkmcnt(3)
	v_mfma_f32_16x16x32_bf16 v[124:127], v[216:219], v[232:235], v[124:127]
	v_lshl_add_u64 v[142:143], v[140:141], 0, s[36:37]
	v_lshl_add_u64 v[182:183], v[142:143], 0, s[60:61]
	v_mfma_f32_16x16x32_bf16 v[108:111], v[220:223], v[232:235], v[108:111]
	v_mfma_f32_16x16x32_bf16 v[88:91], v[224:227], v[232:235], v[88:91]
	s_waitcnt vmcnt(4)
	s_barrier
	global_load_lds_dwordx4 v[160:161], off
	v_lshl_add_u64 v[160:161], v[144:145], 0, s[80:81]
	s_mov_b32 m0, s9
	v_mfma_f32_16x16x32_bf16 v[44:47], v[228:231], v[232:235], v[44:47]
	s_waitcnt lgkmcnt(2)
	v_mfma_f32_16x16x32_bf16 v[120:123], v[216:219], v[236:239], v[120:123]
	ds_read_b128 v[232:235], v168 offset:20480
	v_mfma_f32_16x16x32_bf16 v[104:107], v[220:223], v[236:239], v[104:107]
	ds_read_b128 v[186:189], v167 offset:32768
	global_load_lds_dwordx4 v[160:161], off
	v_add_u32_e32 v160, 0x1c000, v166
	v_add_u32_e32 v161, 0x1e000, v166
	v_readfirstlane_b32 s9, v160
	s_mov_b32 m0, s9
	v_readfirstlane_b32 s9, v161
	v_mfma_f32_16x16x32_bf16 v[76:79], v[224:227], v[236:239], v[76:79]
	ds_read_b128 v[190:193], v167 offset:33792
	v_mfma_f32_16x16x32_bf16 v[40:43], v[228:231], v[236:239], v[40:43]
	ds_read_b128 v[194:197], v167 offset:34816
	s_waitcnt lgkmcnt(5)
	v_mfma_f32_16x16x32_bf16 v[116:119], v[216:219], v[240:243], v[116:119]
	ds_read_b128 v[236:239], v168 offset:21504
	global_load_lds_dwordx4 v[182:183], off
	v_lshl_add_u64 v[182:183], v[142:143], 0, s[80:81]
	s_mov_b32 m0, s9
	v_mfma_f32_16x16x32_bf16 v[100:103], v[220:223], v[240:243], v[100:103]
	ds_read_b128 v[202:205], v167 offset:35840
	v_mfma_f32_16x16x32_bf16 v[68:71], v[224:227], v[240:243], v[68:71]
	v_mfma_f32_16x16x32_bf16 v[36:39], v[228:231], v[240:243], v[36:39]
	global_load_lds_dwordx4 v[182:183], off
	s_waitcnt lgkmcnt(6)
	v_mfma_f32_16x16x32_bf16 v[112:115], v[216:219], v[244:247], v[112:115]
	ds_read_b128 v[240:243], v168 offset:22528
	v_mfma_f32_16x16x32_bf16 v[96:99], v[220:223], v[244:247], v[96:99]
	v_mfma_f32_16x16x32_bf16 v[64:67], v[224:227], v[244:247], v[64:67]
	v_mfma_f32_16x16x32_bf16 v[32:35], v[228:231], v[244:247], v[32:35]
	s_waitcnt lgkmcnt(6)
	v_mfma_f32_16x16x32_bf16 v[92:95], v[216:219], v[232:235], v[92:95]
	ds_read_b128 v[244:247], v168 offset:23552
	v_mfma_f32_16x16x32_bf16 v[60:63], v[220:223], v[232:235], v[60:63]
	v_mfma_f32_16x16x32_bf16 v[28:31], v[224:227], v[232:235], v[28:31]
	v_mfma_f32_16x16x32_bf16 v[12:15], v[228:231], v[232:235], v[12:15]
	s_waitcnt lgkmcnt(3)
	v_mfma_f32_16x16x32_bf16 v[84:87], v[216:219], v[236:239], v[84:87]
	ds_read_b128 v[232:235], v168 offset:49152
	v_mfma_f32_16x16x32_bf16 v[56:59], v[220:223], v[236:239], v[56:59]
	v_mfma_f32_16x16x32_bf16 v[24:27], v[224:227], v[236:239], v[24:27]
	v_mfma_f32_16x16x32_bf16 v[8:11], v[228:231], v[236:239], v[8:11]
	s_waitcnt lgkmcnt(2)
	v_mfma_f32_16x16x32_bf16 v[80:83], v[216:219], v[240:243], v[80:83]
	ds_read_b128 v[236:239], v168 offset:50176
	v_mfma_f32_16x16x32_bf16 v[52:55], v[220:223], v[240:243], v[52:55]
	v_mfma_f32_16x16x32_bf16 v[20:23], v[224:227], v[240:243], v[20:23]
	v_mfma_f32_16x16x32_bf16 v[4:7], v[228:231], v[240:243], v[4:7]
	s_waitcnt lgkmcnt(2)
	v_mfma_f32_16x16x32_bf16 v[72:75], v[216:219], v[244:247], v[72:75]
	ds_read_b128 v[240:243], v168 offset:51200
	v_mfma_f32_16x16x32_bf16 v[48:51], v[220:223], v[244:247], v[48:51]
	v_mfma_f32_16x16x32_bf16 v[16:19], v[224:227], v[244:247], v[16:19]
	v_mfma_f32_16x16x32_bf16 v[0:3], v[228:231], v[244:247], v[0:3]
	ds_read_b128 v[244:247], v168 offset:52224
	v_readfirstlane_b32 s9, v166
	v_lshl_add_u64 v[182:183], v[144:145], 0, s[62:63]
	s_mov_b32 m0, s9
	v_readfirstlane_b32 s9, v146
	s_waitcnt lgkmcnt(3)
	v_mfma_f32_16x16x32_bf16 v[124:127], v[186:189], v[232:235], v[124:127]
	v_lshl_add_u64 v[198:199], v[142:143], 0, s[62:63]
	v_mfma_f32_16x16x32_bf16 v[108:111], v[190:193], v[232:235], v[108:111]
	v_mfma_f32_16x16x32_bf16 v[88:91], v[194:197], v[232:235], v[88:91]
	s_waitcnt vmcnt(4)
	s_barrier
	global_load_lds_dwordx4 v[182:183], off
	v_lshl_add_u64 v[182:183], v[144:145], 0, s[0:1]
	s_mov_b32 m0, s9
	v_readfirstlane_b32 s9, v147
	v_mfma_f32_16x16x32_bf16 v[44:47], v[202:205], v[232:235], v[44:47]
	s_waitcnt lgkmcnt(2)
	v_mfma_f32_16x16x32_bf16 v[120:123], v[186:189], v[236:239], v[120:123]
	ds_read_b128 v[232:235], v168 offset:53248
	v_mfma_f32_16x16x32_bf16 v[104:107], v[190:193], v[236:239], v[104:107]
	v_add_u32_e32 v162, 0x10000, v167
	ds_read_b128 v[216:219], v162
	global_load_lds_dwordx4 v[182:183], off
	s_mov_b32 m0, s9
	v_readfirstlane_b32 s9, v148
	v_lshl_add_u64 v[182:183], v[142:143], 0, s[0:1]
	v_mfma_f32_16x16x32_bf16 v[76:79], v[194:197], v[236:239], v[76:79]
	ds_read_b128 v[220:223], v162 offset:1024
	v_mfma_f32_16x16x32_bf16 v[40:43], v[202:205], v[236:239], v[40:43]
	ds_read_b128 v[224:227], v162 offset:2048
	s_waitcnt lgkmcnt(5)
	v_mfma_f32_16x16x32_bf16 v[116:119], v[186:189], v[240:243], v[116:119]
	ds_read_b128 v[236:239], v168 offset:54272
	global_load_lds_dwordx4 v[198:199], off
	s_mov_b32 m0, s9
	v_mfma_f32_16x16x32_bf16 v[100:103], v[190:193], v[240:243], v[100:103]
	ds_read_b128 v[228:231], v162 offset:3072
	v_mfma_f32_16x16x32_bf16 v[68:71], v[194:197], v[240:243], v[68:71]
	v_mfma_f32_16x16x32_bf16 v[36:39], v[202:205], v[240:243], v[36:39]
	global_load_lds_dwordx4 v[182:183], off
	s_waitcnt lgkmcnt(6)
; #define BIG_SYNC(N)                                              \
;   asm volatile("s_waitcnt vmcnt(%0)" ::"n"(N) : "memory");       \
;   __builtin_amdgcn_s_barrier();                                  \
;   asm volatile("" ::: "memory");                                 \
;   __builtin_amdgcn_sched_barrier(0);
; template <int NK, bool BNT = false> ...
;     ...
;   auto kstep = [&](int T, int cur, int nxt, bool do_stage) {
;     const unsigned char* sa = smem + cur * BIG_STAGE;
;     bf16x8 af[4], bfr[4];
; #pragma unroll
;     for (int m = 0; m < 4; ++m) af[m] = *reinterpret_cast<const bf16x8*>(sa + aoff + m * 1024);
; #pragma unroll
;     for (int n = 0; n < 4; ++n) bfr[n] = *reinterpret_cast<const bf16x8*>(sa + boff + n * 1024);
;     __builtin_amdgcn_sched_barrier(0);
;     if (do_stage) stage(T + 3, nxt);
; #pragma unroll
;     for (int m = 0; m < 4; ++m)
; #pragma unroll
;       for (int n = 0; n < 4; ++n) acc[m][n] = __builtin_amdgcn_mfma_f32_16x16x32_bf16(af[m], bfr[n], acc[m][n], 0, 0, 0);
;     if (do_stage) {
; #pragma unroll
;       for (int q = 0; q < NG; ++q) {
;         __builtin_amdgcn_sched_group_barrier(0x008, 3, 0);
;         __builtin_amdgcn_sched_group_barrier(0x010, 1, 0);
;       }
;       __builtin_amdgcn_sched_group_barrier(0x008, 16 - 3 * NG, 0);
;     }
;     __builtin_amdgcn_sched_barrier(0);
; #pragma unroll
;     for (int n = 0; n < 4; ++n) bfr[n] = *reinterpret_cast<const bf16x8*>(sa + boff + (4 + n) * 1024);
; #pragma unroll
;     for (int m = 0; m < 4; ++m)
; #pragma unroll
;       for (int n = 0; n < 4; ++n)
;         acc[m][4 + n] = __builtin_amdgcn_mfma_f32_16x16x32_bf16(af[m], bfr[n], acc[m][4 + n], 0, 0, 0);
;     __builtin_amdgcn_sched_barrier(0);
;   };
;     ...
;   stage(0, 0);
;   stage(1, 1);
;   stage(2, 2);
;   for (int it = 0; it < NK / 4 - 1; ++it) {
;     const int t = it * 4;
;     BIG_SYNC(2 * NG); kstep(t, 0, 3, true);
;     BIG_SYNC(2 * NG); kstep(t + 1, 1, 0, true);
;     BIG_SYNC(2 * NG); kstep(t + 2, 2, 1, true);
;     BIG_SYNC(2 * NG); kstep(t + 3, 3, 2, true);
;   }
	v_mfma_f32_16x16x32_bf16 v[112:115], v[186:189], v[244:247], v[112:115]
	ds_read_b128 v[240:243], v168 offset:55296
	v_mfma_f32_16x16x32_bf16 v[96:99], v[190:193], v[244:247], v[96:99]
	v_mfma_f32_16x16x32_bf16 v[64:67], v[194:197], v[244:247], v[64:67]
	v_mfma_f32_16x16x32_bf16 v[32:35], v[202:205], v[244:247], v[32:35]
	v_or_b32_e32 v163, 0x10000, v169
	s_waitcnt lgkmcnt(6)
	v_mfma_f32_16x16x32_bf16 v[92:95], v[186:189], v[232:235], v[92:95]
	ds_read_b128 v[244:247], v168 offset:56320
	v_mfma_f32_16x16x32_bf16 v[60:63], v[190:193], v[232:235], v[60:63]
	v_mfma_f32_16x16x32_bf16 v[28:31], v[194:197], v[232:235], v[28:31]
	v_mfma_f32_16x16x32_bf16 v[12:15], v[202:205], v[232:235], v[12:15]
	s_waitcnt lgkmcnt(3)
	v_mfma_f32_16x16x32_bf16 v[84:87], v[186:189], v[236:239], v[84:87]
	ds_read_b128 v[232:235], v163
	v_mfma_f32_16x16x32_bf16 v[56:59], v[190:193], v[236:239], v[56:59]
	v_mfma_f32_16x16x32_bf16 v[24:27], v[194:197], v[236:239], v[24:27]
	v_mfma_f32_16x16x32_bf16 v[8:11], v[202:205], v[236:239], v[8:11]
	s_waitcnt lgkmcnt(2)
	v_mfma_f32_16x16x32_bf16 v[80:83], v[186:189], v[240:243], v[80:83]
	ds_read_b128 v[236:239], v163 offset:1024
	v_mfma_f32_16x16x32_bf16 v[52:55], v[190:193], v[240:243], v[52:55]
	v_mfma_f32_16x16x32_bf16 v[20:23], v[194:197], v[240:243], v[20:23]
	v_mfma_f32_16x16x32_bf16 v[4:7], v[202:205], v[240:243], v[4:7]
	s_waitcnt lgkmcnt(2)
	v_mfma_f32_16x16x32_bf16 v[72:75], v[186:189], v[244:247], v[72:75]
	ds_read_b128 v[240:243], v163 offset:2048
	v_mfma_f32_16x16x32_bf16 v[48:51], v[190:193], v[244:247], v[48:51]
	v_mfma_f32_16x16x32_bf16 v[16:19], v[194:197], v[244:247], v[16:19]
	v_mfma_f32_16x16x32_bf16 v[0:3], v[202:205], v[244:247], v[0:3]
	ds_read_b128 v[244:247], v163 offset:3072
	v_add_u32_e32 v162, 0x10000, v167
	v_or_b32_e32 v163, 0x10000, v169
	v_add_u32_e32 v164, 0x10400, v169
	v_add_u32_e32 v165, 0x10800, v169
	v_add_u32_e32 v172, 0x10c00, v169
	v_readfirstlane_b32 s9, v149
	v_lshl_add_u64 v[174:175], v[144:145], 0, s[2:3]
	s_mov_b32 m0, s9
	v_readfirstlane_b32 s9, v150
	s_waitcnt lgkmcnt(3)
	v_mfma_f32_16x16x32_bf16 v[124:127], v[216:219], v[232:235], v[124:127]
	v_lshl_add_u64 v[178:179], v[142:143], 0, s[2:3]
	v_mfma_f32_16x16x32_bf16 v[108:111], v[220:223], v[232:235], v[108:111]
	v_mfma_f32_16x16x32_bf16 v[88:91], v[224:227], v[232:235], v[88:91]
	s_waitcnt vmcnt(4)
	s_barrier
	global_load_lds_dwordx4 v[174:175], off
	v_lshl_add_u64 v[174:175], v[144:145], 0, s[52:53]
	s_mov_b32 m0, s9
	v_readfirstlane_b32 s9, v151
	v_mfma_f32_16x16x32_bf16 v[44:47], v[228:231], v[232:235], v[44:47]
	s_waitcnt lgkmcnt(2)
	v_mfma_f32_16x16x32_bf16 v[120:123], v[216:219], v[236:239], v[120:123]
	ds_read_b128 v[232:235], v163 offset:4096
	v_mfma_f32_16x16x32_bf16 v[104:107], v[220:223], v[236:239], v[104:107]
	v_add_u32_e32 v162, 0x10000, v167
	ds_read_b128 v[186:189], v162 offset:32768
	global_load_lds_dwordx4 v[174:175], off
	s_mov_b32 m0, s9
	v_readfirstlane_b32 s9, v152
	v_lshl_add_u64 v[174:175], v[142:143], 0, s[52:53]
	v_mfma_f32_16x16x32_bf16 v[76:79], v[224:227], v[236:239], v[76:79]
	ds_read_b128 v[190:193], v162 offset:33792
	v_mfma_f32_16x16x32_bf16 v[40:43], v[228:231], v[236:239], v[40:43]
	ds_read_b128 v[194:197], v162 offset:34816
	s_waitcnt lgkmcnt(5)
	v_mfma_f32_16x16x32_bf16 v[116:119], v[216:219], v[240:243], v[116:119]
	ds_read_b128 v[236:239], v163 offset:5120
	global_load_lds_dwordx4 v[178:179], off
	s_mov_b32 m0, s9
	v_mfma_f32_16x16x32_bf16 v[100:103], v[220:223], v[240:243], v[100:103]
	ds_read_b128 v[202:205], v162 offset:35840
	v_mfma_f32_16x16x32_bf16 v[68:71], v[224:227], v[240:243], v[68:71]
	v_mfma_f32_16x16x32_bf16 v[36:39], v[228:231], v[240:243], v[36:39]
	global_load_lds_dwordx4 v[174:175], off
	s_waitcnt lgkmcnt(6)
	v_mfma_f32_16x16x32_bf16 v[112:115], v[216:219], v[244:247], v[112:115]
	ds_read_b128 v[240:243], v163 offset:6144
	v_mfma_f32_16x16x32_bf16 v[96:99], v[220:223], v[244:247], v[96:99]
	v_mfma_f32_16x16x32_bf16 v[64:67], v[224:227], v[244:247], v[64:67]
	v_mfma_f32_16x16x32_bf16 v[32:35], v[228:231], v[244:247], v[32:35]
	v_add_u32_e32 v173, 0x11000, v169
	v_add_u32_e32 v174, 0x11400, v169
	v_add_u32_e32 v175, 0x11800, v169
	v_add_u32_e32 v178, 0x11c00, v169
	v_or_b32_e32 v163, 0x10000, v169
	s_waitcnt lgkmcnt(6)
	v_mfma_f32_16x16x32_bf16 v[92:95], v[216:219], v[232:235], v[92:95]
	ds_read_b128 v[244:247], v163 offset:7168
	v_mfma_f32_16x16x32_bf16 v[60:63], v[220:223], v[232:235], v[60:63]
	v_mfma_f32_16x16x32_bf16 v[28:31], v[224:227], v[232:235], v[28:31]
	v_mfma_f32_16x16x32_bf16 v[12:15], v[228:231], v[232:235], v[12:15]
	s_waitcnt lgkmcnt(3)
	v_mfma_f32_16x16x32_bf16 v[84:87], v[216:219], v[236:239], v[84:87]
	ds_read_b128 v[232:235], v163 offset:32768
	v_mfma_f32_16x16x32_bf16 v[56:59], v[220:223], v[236:239], v[56:59]
	v_mfma_f32_16x16x32_bf16 v[24:27], v[224:227], v[236:239], v[24:27]
	v_mfma_f32_16x16x32_bf16 v[8:11], v[228:231], v[236:239], v[8:11]
	s_waitcnt lgkmcnt(2)
	v_mfma_f32_16x16x32_bf16 v[80:83], v[216:219], v[240:243], v[80:83]
	ds_read_b128 v[236:239], v163 offset:33792
	v_mfma_f32_16x16x32_bf16 v[52:55], v[220:223], v[240:243], v[52:55]
	v_mfma_f32_16x16x32_bf16 v[20:23], v[224:227], v[240:243], v[20:23]
	v_mfma_f32_16x16x32_bf16 v[4:7], v[228:231], v[240:243], v[4:7]
	s_waitcnt lgkmcnt(2)
	v_mfma_f32_16x16x32_bf16 v[72:75], v[216:219], v[244:247], v[72:75]
	ds_read_b128 v[240:243], v163 offset:34816
	v_mfma_f32_16x16x32_bf16 v[48:51], v[220:223], v[244:247], v[48:51]
	v_mfma_f32_16x16x32_bf16 v[16:19], v[224:227], v[244:247], v[16:19]
	v_mfma_f32_16x16x32_bf16 v[0:3], v[228:231], v[244:247], v[0:3]
	ds_read_b128 v[244:247], v163 offset:35840
	v_add_u32_e32 v176, 0x18000, v167
	v_or_b32_e32 v179, 0x18000, v169
	v_add_u32_e32 v180, 0x18400, v169
	v_add_u32_e32 v181, 0x18800, v169
	v_add_u32_e32 v182, 0x18c00, v169
	v_readfirstlane_b32 s9, v154
	v_lshl_add_u64 v[248:249], v[144:145], 0, s[54:55]
	s_mov_b32 m0, s9
	v_readfirstlane_b32 s9, v155
	v_lshl_add_u64 v[144:145], v[144:145], 0, s[56:57]
	s_waitcnt lgkmcnt(3)
	v_mfma_f32_16x16x32_bf16 v[124:127], v[186:189], v[232:235], v[124:127]
	v_lshl_add_u64 v[250:251], v[142:143], 0, s[54:55]
	v_lshl_add_u64 v[142:143], v[142:143], 0, s[56:57]
	v_mfma_f32_16x16x32_bf16 v[108:111], v[190:193], v[232:235], v[108:111]
	v_mfma_f32_16x16x32_bf16 v[88:91], v[194:197], v[232:235], v[88:91]
	s_waitcnt vmcnt(4)
	s_barrier
; #define BIG_SYNC(N)                                              \
;   asm volatile("s_waitcnt vmcnt(%0)" ::"n"(N) : "memory");       \
;   __builtin_amdgcn_s_barrier();                                  \
;   asm volatile("" ::: "memory");                                 \
;   __builtin_amdgcn_sched_barrier(0);
; template <int NK, bool BNT = false> ...
;     ...
;   auto kstep = [&](int T, int cur, int nxt, bool do_stage) {
;     const unsigned char* sa = smem + cur * BIG_STAGE;
;     bf16x8 af[4], bfr[4];
; #pragma unroll
;     for (int m = 0; m < 4; ++m) af[m] = *reinterpret_cast<const bf16x8*>(sa + aoff + m * 1024);
; #pragma unroll
;     for (int n = 0; n < 4; ++n) bfr[n] = *reinterpret_cast<const bf16x8*>(sa + boff + n * 1024);
;     __builtin_amdgcn_sched_barrier(0);
;     if (do_stage) stage(T + 3, nxt);
; #pragma unroll
;     for (int m = 0; m < 4; ++m)
; #pragma unroll
;       for (int n = 0; n < 4; ++n) acc[m][n] = __builtin_amdgcn_mfma_f32_16x16x32_bf16(af[m], bfr[n], acc[m][n], 0, 0, 0);
;     if (do_stage) {
; #pragma unroll
;       for (int q = 0; q < NG; ++q) {
;         __builtin_amdgcn_sched_group_barrier(0x008, 3, 0);
;         __builtin_amdgcn_sched_group_barrier(0x010, 1, 0);
;       }
;       __builtin_amdgcn_sched_group_barrier(0x008, 16 - 3 * NG, 0);
;     }
;     __builtin_amdgcn_sched_barrier(0);
; #pragma unroll
;     for (int n = 0; n < 4; ++n) bfr[n] = *reinterpret_cast<const bf16x8*>(sa + boff + (4 + n) * 1024);
; #pragma unroll
;     for (int m = 0; m < 4; ++m)
; #pragma unroll
;       for (int n = 0; n < 4; ++n)
;         acc[m][4 + n] = __builtin_amdgcn_mfma_f32_16x16x32_bf16(af[m], bfr[n], acc[m][4 + n], 0, 0, 0);
;     __builtin_amdgcn_sched_barrier(0);
;   };
;     ...
;   stage(0, 0);
;   stage(1, 1);
;   stage(2, 2);
;   for (int it = 0; it < NK / 4 - 1; ++it) {
;     const int t = it * 4;
;     BIG_SYNC(2 * NG); kstep(t, 0, 3, true);
;     BIG_SYNC(2 * NG); kstep(t + 1, 1, 0, true);
;     BIG_SYNC(2 * NG); kstep(t + 2, 2, 1, true);
;     BIG_SYNC(2 * NG); kstep(t + 3, 3, 2, true);
;   }
;   BIG_SYNC(2 * NG); kstep(NK - 4, 0, 3, true);
	global_load_lds_dwordx4 v[248:249], off
	s_mov_b32 m0, s9
	v_readfirstlane_b32 s9, v156
	v_mfma_f32_16x16x32_bf16 v[44:47], v[202:205], v[232:235], v[44:47]
	s_waitcnt lgkmcnt(2)
	v_mfma_f32_16x16x32_bf16 v[120:123], v[186:189], v[236:239], v[120:123]
	ds_read_b128 v[232:235], v163 offset:36864
	v_mfma_f32_16x16x32_bf16 v[104:107], v[190:193], v[236:239], v[104:107]
	ds_read_b128 v[216:219], v167
	global_load_lds_dwordx4 v[144:145], off
	s_mov_b32 m0, s9
	v_readfirstlane_b32 s9, v157
	v_mfma_f32_16x16x32_bf16 v[76:79], v[194:197], v[236:239], v[76:79]
	ds_read_b128 v[220:223], v167 offset:1024
	v_mfma_f32_16x16x32_bf16 v[40:43], v[202:205], v[236:239], v[40:43]
	ds_read_b128 v[224:227], v167 offset:2048
	s_waitcnt lgkmcnt(5)
	v_mfma_f32_16x16x32_bf16 v[116:119], v[186:189], v[240:243], v[116:119]
	ds_read_b128 v[236:239], v163 offset:37888
	global_load_lds_dwordx4 v[250:251], off
	s_mov_b32 m0, s9
	v_mfma_f32_16x16x32_bf16 v[100:103], v[190:193], v[240:243], v[100:103]
	ds_read_b128 v[228:231], v167 offset:3072
	v_mfma_f32_16x16x32_bf16 v[68:71], v[194:197], v[240:243], v[68:71]
	v_mfma_f32_16x16x32_bf16 v[36:39], v[202:205], v[240:243], v[36:39]
	global_load_lds_dwordx4 v[142:143], off
	s_waitcnt lgkmcnt(6)
	v_mfma_f32_16x16x32_bf16 v[112:115], v[186:189], v[244:247], v[112:115]
	ds_read_b128 v[240:243], v163 offset:38912
	v_mfma_f32_16x16x32_bf16 v[96:99], v[190:193], v[244:247], v[96:99]
	v_mfma_f32_16x16x32_bf16 v[64:67], v[194:197], v[244:247], v[64:67]
	v_mfma_f32_16x16x32_bf16 v[32:35], v[202:205], v[244:247], v[32:35]
	v_add_u32_e32 v142, 0x19000, v169
	v_add_u32_e32 v143, 0x19400, v169
	v_add_u32_e32 v144, 0x19800, v169
	v_add_u32_e32 v145, 0x19c00, v169
	s_waitcnt lgkmcnt(6)
	v_mfma_f32_16x16x32_bf16 v[92:95], v[186:189], v[232:235], v[92:95]
	ds_read_b128 v[244:247], v163 offset:39936
	v_mfma_f32_16x16x32_bf16 v[60:63], v[190:193], v[232:235], v[60:63]
	v_mfma_f32_16x16x32_bf16 v[28:31], v[194:197], v[232:235], v[28:31]
	v_mfma_f32_16x16x32_bf16 v[12:15], v[202:205], v[232:235], v[12:15]
	s_waitcnt lgkmcnt(3)
	v_mfma_f32_16x16x32_bf16 v[84:87], v[186:189], v[236:239], v[84:87]
	ds_read_b128 v[232:235], v168 offset:16384
	v_mfma_f32_16x16x32_bf16 v[56:59], v[190:193], v[236:239], v[56:59]
	v_mfma_f32_16x16x32_bf16 v[24:27], v[194:197], v[236:239], v[24:27]
	v_mfma_f32_16x16x32_bf16 v[8:11], v[202:205], v[236:239], v[8:11]
	s_waitcnt lgkmcnt(2)
	v_mfma_f32_16x16x32_bf16 v[80:83], v[186:189], v[240:243], v[80:83]
	ds_read_b128 v[236:239], v168 offset:17408
	v_mfma_f32_16x16x32_bf16 v[52:55], v[190:193], v[240:243], v[52:55]
	v_mfma_f32_16x16x32_bf16 v[20:23], v[194:197], v[240:243], v[20:23]
	v_mfma_f32_16x16x32_bf16 v[4:7], v[202:205], v[240:243], v[4:7]
	s_waitcnt lgkmcnt(2)
	v_mfma_f32_16x16x32_bf16 v[72:75], v[186:189], v[244:247], v[72:75]
	ds_read_b128 v[240:243], v168 offset:18432
	v_mfma_f32_16x16x32_bf16 v[48:51], v[190:193], v[244:247], v[48:51]
	v_mfma_f32_16x16x32_bf16 v[16:19], v[194:197], v[244:247], v[16:19]
	v_mfma_f32_16x16x32_bf16 v[0:3], v[202:205], v[244:247], v[0:3]
	ds_read_b128 v[244:247], v168 offset:19456
	s_add_u32 s36, s36, 0x8000
	s_addc_u32 s37, s37, 0
	s_cmp_lg_u32 s36, 0x38000
	s_cbranch_scc1 .LBB0_68
	s_sext_i32_i8 s9, s14
	s_mov_b64 s[18:19], 0x3e000
	v_readfirstlane_b32 s11, v158
	v_lshl_add_u64 v[150:151], v[130:131], 0, s[18:19]
	v_lshl_add_u64 v[198:199], v[128:129], 0, s[18:19]
	s_mov_b32 m0, s11
	s_mov_b64 s[18:19], 0x7e000
	v_readfirstlane_b32 s11, v159
	v_lshl_add_u64 v[130:131], v[130:131], 0, s[18:19]
	s_waitcnt lgkmcnt(3)
	v_mfma_f32_16x16x32_bf16 v[124:127], v[216:219], v[232:235], v[124:127]
	v_lshl_add_u64 v[128:129], v[128:129], 0, s[18:19]
	v_mfma_f32_16x16x32_bf16 v[108:111], v[220:223], v[232:235], v[108:111]
	v_mfma_f32_16x16x32_bf16 v[88:91], v[224:227], v[232:235], v[88:91]
	s_waitcnt vmcnt(4)
	s_barrier
	global_load_lds_dwordx4 v[150:151], off
	s_mov_b32 m0, s11
	v_readfirstlane_b32 s11, v160
	v_mfma_f32_16x16x32_bf16 v[44:47], v[228:231], v[232:235], v[44:47]
	s_waitcnt lgkmcnt(2)
	v_mfma_f32_16x16x32_bf16 v[120:123], v[216:219], v[236:239], v[120:123]
	ds_read_b128 v[232:235], v168 offset:20480
	v_mfma_f32_16x16x32_bf16 v[104:107], v[220:223], v[236:239], v[104:107]
	ds_read_b128 v[186:189], v167 offset:32768
	global_load_lds_dwordx4 v[130:131], off
	s_mov_b32 m0, s11
	v_readfirstlane_b32 s11, v161
	v_mfma_f32_16x16x32_bf16 v[76:79], v[224:227], v[236:239], v[76:79]
	ds_read_b128 v[190:193], v167 offset:33792
	v_mfma_f32_16x16x32_bf16 v[40:43], v[228:231], v[236:239], v[40:43]
	ds_read_b128 v[194:197], v167 offset:34816
	s_waitcnt lgkmcnt(5)
	v_mfma_f32_16x16x32_bf16 v[116:119], v[216:219], v[240:243], v[116:119]
	ds_read_b128 v[236:239], v168 offset:21504
	global_load_lds_dwordx4 v[198:199], off
	s_mov_b32 m0, s11
	v_mfma_f32_16x16x32_bf16 v[100:103], v[220:223], v[240:243], v[100:103]
	ds_read_b128 v[202:205], v167 offset:35840
	v_mfma_f32_16x16x32_bf16 v[68:71], v[224:227], v[240:243], v[68:71]
	v_mfma_f32_16x16x32_bf16 v[36:39], v[228:231], v[240:243], v[36:39]
	global_load_lds_dwordx4 v[128:129], off
	s_waitcnt lgkmcnt(6)
	v_mfma_f32_16x16x32_bf16 v[112:115], v[216:219], v[244:247], v[112:115]
	ds_read_b128 v[240:243], v168 offset:22528
	v_mfma_f32_16x16x32_bf16 v[96:99], v[220:223], v[244:247], v[96:99]
	v_mfma_f32_16x16x32_bf16 v[64:67], v[224:227], v[244:247], v[64:67]
	v_mfma_f32_16x16x32_bf16 v[32:35], v[228:231], v[244:247], v[32:35]
	s_waitcnt lgkmcnt(6)
	v_mfma_f32_16x16x32_bf16 v[92:95], v[216:219], v[232:235], v[92:95]
	ds_read_b128 v[244:247], v168 offset:23552
	v_mfma_f32_16x16x32_bf16 v[60:63], v[220:223], v[232:235], v[60:63]
	v_mfma_f32_16x16x32_bf16 v[28:31], v[224:227], v[232:235], v[28:31]
	v_mfma_f32_16x16x32_bf16 v[12:15], v[228:231], v[232:235], v[12:15]
	s_waitcnt lgkmcnt(3)
; #define BIG_SYNC(N)                                              \
;   asm volatile("s_waitcnt vmcnt(%0)" ::"n"(N) : "memory");       \
;   __builtin_amdgcn_s_barrier();                                  \
;   asm volatile("" ::: "memory");                                 \
;   __builtin_amdgcn_sched_barrier(0);
; template <int NK, bool BNT = false> ...
;     ...
;   auto kstep = [&](int T, int cur, int nxt, bool do_stage) {
;     const unsigned char* sa = smem + cur * BIG_STAGE;
;     bf16x8 af[4], bfr[4];
; #pragma unroll
;     for (int m = 0; m < 4; ++m) af[m] = *reinterpret_cast<const bf16x8*>(sa + aoff + m * 1024);
; #pragma unroll
;     for (int n = 0; n < 4; ++n) bfr[n] = *reinterpret_cast<const bf16x8*>(sa + boff + n * 1024);
;     __builtin_amdgcn_sched_barrier(0);
;     if (do_stage) stage(T + 3, nxt);
; #pragma unroll
;     for (int m = 0; m < 4; ++m)
; #pragma unroll
;       for (int n = 0; n < 4; ++n) acc[m][n] = __builtin_amdgcn_mfma_f32_16x16x32_bf16(af[m], bfr[n], acc[m][n], 0, 0, 0);
;     if (do_stage) {
; #pragma unroll
;       for (int q = 0; q < NG; ++q) {
;         __builtin_amdgcn_sched_group_barrier(0x008, 3, 0);
;         __builtin_amdgcn_sched_group_barrier(0x010, 1, 0);
;       }
;       __builtin_amdgcn_sched_group_barrier(0x008, 16 - 3 * NG, 0);
;     }
;     __builtin_amdgcn_sched_barrier(0);
; #pragma unroll
;     for (int n = 0; n < 4; ++n) bfr[n] = *reinterpret_cast<const bf16x8*>(sa + boff + (4 + n) * 1024);
; #pragma unroll
;     for (int m = 0; m < 4; ++m)
; #pragma unroll
;       for (int n = 0; n < 4; ++n)
;         acc[m][4 + n] = __builtin_amdgcn_mfma_f32_16x16x32_bf16(af[m], bfr[n], acc[m][4 + n], 0, 0, 0);
;     __builtin_amdgcn_sched_barrier(0);
;   };
;     ...
;   stage(0, 0);
;   stage(1, 1);
;   stage(2, 2);
;   for (int it = 0; it < NK / 4 - 1; ++it) {
;     const int t = it * 4;
;     BIG_SYNC(2 * NG); kstep(t, 0, 3, true);
;     BIG_SYNC(2 * NG); kstep(t + 1, 1, 0, true);
;     BIG_SYNC(2 * NG); kstep(t + 2, 2, 1, true);
;     BIG_SYNC(2 * NG); kstep(t + 3, 3, 2, true);
;   }
;   BIG_SYNC(2 * NG); kstep(NK - 4, 0, 3, true);
;   BIG_SYNC(2 * NG); kstep(NK - 3, 1, 0, false);
;   BIG_SYNC(NG);     kstep(NK - 2, 2, 0, false);
;   BIG_SYNC(0);      kstep(NK - 1, 3, 0, false);
	v_mfma_f32_16x16x32_bf16 v[84:87], v[216:219], v[236:239], v[84:87]
	ds_read_b128 v[232:235], v168 offset:49152
	v_mfma_f32_16x16x32_bf16 v[56:59], v[220:223], v[236:239], v[56:59]
	v_mfma_f32_16x16x32_bf16 v[24:27], v[224:227], v[236:239], v[24:27]
	v_mfma_f32_16x16x32_bf16 v[8:11], v[228:231], v[236:239], v[8:11]
	s_waitcnt lgkmcnt(2)
	v_mfma_f32_16x16x32_bf16 v[80:83], v[216:219], v[240:243], v[80:83]
	ds_read_b128 v[236:239], v168 offset:50176
	v_mfma_f32_16x16x32_bf16 v[52:55], v[220:223], v[240:243], v[52:55]
	v_mfma_f32_16x16x32_bf16 v[20:23], v[224:227], v[240:243], v[20:23]
	v_mfma_f32_16x16x32_bf16 v[4:7], v[228:231], v[240:243], v[4:7]
	s_waitcnt lgkmcnt(2)
	v_mfma_f32_16x16x32_bf16 v[72:75], v[216:219], v[244:247], v[72:75]
	ds_read_b128 v[240:243], v168 offset:51200
	v_mfma_f32_16x16x32_bf16 v[48:51], v[220:223], v[244:247], v[48:51]
	v_mfma_f32_16x16x32_bf16 v[16:19], v[224:227], v[244:247], v[16:19]
	v_mfma_f32_16x16x32_bf16 v[0:3], v[228:231], v[244:247], v[0:3]
	ds_read_b128 v[244:247], v168 offset:52224
	s_waitcnt lgkmcnt(3)
	v_mfma_f32_16x16x32_bf16 v[124:127], v[186:189], v[232:235], v[124:127]
	v_mfma_f32_16x16x32_bf16 v[108:111], v[190:193], v[232:235], v[108:111]
	v_mfma_f32_16x16x32_bf16 v[88:91], v[194:197], v[232:235], v[88:91]
	v_mfma_f32_16x16x32_bf16 v[44:47], v[202:205], v[232:235], v[44:47]
	s_waitcnt vmcnt(4)
	s_barrier
	s_waitcnt lgkmcnt(2)
	v_mfma_f32_16x16x32_bf16 v[120:123], v[186:189], v[236:239], v[120:123]
	ds_read_b128 v[232:235], v168 offset:53248
	v_mfma_f32_16x16x32_bf16 v[104:107], v[190:193], v[236:239], v[104:107]
	v_mfma_f32_16x16x32_bf16 v[76:79], v[194:197], v[236:239], v[76:79]
	v_mfma_f32_16x16x32_bf16 v[40:43], v[202:205], v[236:239], v[40:43]
	s_waitcnt lgkmcnt(2)
	v_mfma_f32_16x16x32_bf16 v[116:119], v[186:189], v[240:243], v[116:119]
	ds_read_b128 v[236:239], v168 offset:54272
	v_mfma_f32_16x16x32_bf16 v[100:103], v[190:193], v[240:243], v[100:103]
	v_mfma_f32_16x16x32_bf16 v[68:71], v[194:197], v[240:243], v[68:71]
	v_mfma_f32_16x16x32_bf16 v[36:39], v[202:205], v[240:243], v[36:39]
	s_waitcnt lgkmcnt(2)
	v_mfma_f32_16x16x32_bf16 v[112:115], v[186:189], v[244:247], v[112:115]
	ds_read_b128 v[240:243], v168 offset:55296
	v_mfma_f32_16x16x32_bf16 v[96:99], v[190:193], v[244:247], v[96:99]
	v_mfma_f32_16x16x32_bf16 v[64:67], v[194:197], v[244:247], v[64:67]
	v_mfma_f32_16x16x32_bf16 v[32:35], v[202:205], v[244:247], v[32:35]
	s_waitcnt lgkmcnt(2)
	v_mfma_f32_16x16x32_bf16 v[92:95], v[186:189], v[232:235], v[92:95]
	ds_read_b128 v[244:247], v168 offset:56320
	v_mfma_f32_16x16x32_bf16 v[60:63], v[190:193], v[232:235], v[60:63]
	v_mfma_f32_16x16x32_bf16 v[28:31], v[194:197], v[232:235], v[28:31]
	v_mfma_f32_16x16x32_bf16 v[12:15], v[202:205], v[232:235], v[12:15]
	s_waitcnt lgkmcnt(2)
	v_mfma_f32_16x16x32_bf16 v[84:87], v[186:189], v[236:239], v[84:87]
	v_mfma_f32_16x16x32_bf16 v[56:59], v[190:193], v[236:239], v[56:59]
	v_mfma_f32_16x16x32_bf16 v[24:27], v[194:197], v[236:239], v[24:27]
	v_mfma_f32_16x16x32_bf16 v[8:11], v[202:205], v[236:239], v[8:11]
	s_waitcnt lgkmcnt(1)
	v_mfma_f32_16x16x32_bf16 v[80:83], v[186:189], v[240:243], v[80:83]
	v_mfma_f32_16x16x32_bf16 v[52:55], v[190:193], v[240:243], v[52:55]
	v_mfma_f32_16x16x32_bf16 v[20:23], v[194:197], v[240:243], v[20:23]
	v_mfma_f32_16x16x32_bf16 v[4:7], v[202:205], v[240:243], v[4:7]
	s_waitcnt lgkmcnt(0)
	v_mfma_f32_16x16x32_bf16 v[72:75], v[186:189], v[244:247], v[72:75]
	v_mfma_f32_16x16x32_bf16 v[48:51], v[190:193], v[244:247], v[48:51]
	v_mfma_f32_16x16x32_bf16 v[16:19], v[194:197], v[244:247], v[16:19]
	v_mfma_f32_16x16x32_bf16 v[0:3], v[202:205], v[244:247], v[0:3]
	v_mov_b32_e32 v186, 0xf149f2ca
	v_mov_b32_e32 v187, 0x3c0881c4
	v_mov_b32_e32 v188, 0xbab64f3b
	v_mov_b32_e32 v189, 0x24800
	v_mov_b32_e32 v190, 1
	v_mov_b32_e32 v191, 0x24804
	v_mov_b32_e32 v192, 0xfcf
	v_mov_b32_e32 v193, 0x7cf
	v_mov_b32_e32 v194, 0xfdf
	v_mov_b32_e32 v195, 0x7df
	v_mov_b32_e32 v196, 0xfef
	v_mov_b32_e32 v197, 0x7ef
	v_mov_b32_e32 v198, 0xfff
	v_mov_b32_e32 v199, 0x7ff
	v_mov_b32_e32 v200, 0x20000
	v_mov_b32_e32 v201, 0xf8f
	v_mov_b32_e32 v202, 0x78f
	v_mov_b32_e32 v203, 0xf9f
	v_mov_b32_e32 v204, 0x79f
	v_mov_b32_e32 v205, 0xfaf
	s_waitcnt vmcnt(4)
	s_barrier
	ds_read_b128 v[128:131], v162
	ds_read_b128 v[138:141], v162 offset:1024
	ds_read_b128 v[146:149], v162 offset:2048
	ds_read_b128 v[154:157], v162 offset:3072
	ds_read_b128 v[158:161], v163
	ds_read_b128 v[216:219], v164
	ds_read_b128 v[162:165], v165
	ds_read_b128 v[220:223], v172
	s_waitcnt lgkmcnt(0)
	v_mfma_f32_16x16x32_bf16 v[124:127], v[128:131], v[158:161], v[124:127]
	v_mfma_f32_16x16x32_bf16 v[116:119], v[128:131], v[162:165], v[116:119]
	v_mfma_f32_16x16x32_bf16 v[112:115], v[128:131], v[220:223], v[112:115]
	v_mfma_f32_16x16x32_bf16 v[104:107], v[138:141], v[216:219], v[104:107]
	v_mfma_f32_16x16x32_bf16 v[100:103], v[138:141], v[162:165], v[100:103]
	v_mfma_f32_16x16x32_bf16 v[96:99], v[138:141], v[220:223], v[96:99]
	v_mfma_f32_16x16x32_bf16 v[68:71], v[146:149], v[162:165], v[68:71]
	v_mfma_f32_16x16x32_bf16 v[64:67], v[146:149], v[220:223], v[64:67]
	v_mfma_f32_16x16x32_bf16 v[44:47], v[154:157], v[158:161], v[44:47]
	v_mfma_f32_16x16x32_bf16 v[40:43], v[154:157], v[216:219], v[40:43]
	v_mfma_f32_16x16x32_bf16 v[36:39], v[154:157], v[162:165], v[36:39]
	v_mfma_f32_16x16x32_bf16 v[32:35], v[154:157], v[220:223], v[32:35]
	v_mfma_f32_16x16x32_bf16 v[120:123], v[128:131], v[216:219], v[120:123]
	v_mfma_f32_16x16x32_bf16 v[224:227], v[138:141], v[158:161], v[108:111]
	v_mfma_f32_16x16x32_bf16 v[228:231], v[146:149], v[158:161], v[88:91]
	v_mfma_f32_16x16x32_bf16 v[232:235], v[146:149], v[216:219], v[76:79]
	s_nop 2
	ds_read_b128 v[76:79], v173
	ds_read_b128 v[88:91], v174
	s_waitcnt lgkmcnt(0)
	v_mfma_f32_16x16x32_bf16 v[158:161], v[128:131], v[76:79], v[92:95]
	s_nop 2
	ds_read_b128 v[92:95], v178
	v_mfma_f32_16x16x32_bf16 v[162:165], v[128:131], v[88:91], v[84:87]
	s_nop 2
	ds_read_b128 v[84:87], v175
	s_waitcnt lgkmcnt(0)
	v_mfma_f32_16x16x32_bf16 v[172:175], v[128:131], v[84:87], v[80:83]
	v_mfma_f32_16x16x32_bf16 v[128:131], v[128:131], v[92:95], v[72:75]
	v_mfma_f32_16x16x32_bf16 v[216:219], v[138:141], v[76:79], v[60:63]
	v_mfma_f32_16x16x32_bf16 v[220:223], v[138:141], v[88:91], v[56:59]
	v_mfma_f32_16x16x32_bf16 v[52:55], v[138:141], v[84:87], v[52:55]
	v_mfma_f32_16x16x32_bf16 v[48:51], v[138:141], v[92:95], v[48:51]
	v_mfma_f32_16x16x32_bf16 v[138:141], v[146:149], v[76:79], v[28:31]
	v_mfma_f32_16x16x32_bf16 v[236:239], v[146:149], v[88:91], v[24:27]
	v_mfma_f32_16x16x32_bf16 v[20:23], v[146:149], v[84:87], v[20:23]
	v_mfma_f32_16x16x32_bf16 v[16:19], v[146:149], v[92:95], v[16:19]
	v_mfma_f32_16x16x32_bf16 v[146:149], v[154:157], v[76:79], v[12:15]
	v_mfma_f32_16x16x32_bf16 v[0:3], v[154:157], v[92:95], v[0:3]
	v_mfma_f32_16x16x32_bf16 v[240:243], v[154:157], v[88:91], v[8:11]
	v_mfma_f32_16x16x32_bf16 v[244:247], v[154:157], v[84:87], v[4:7]
	s_waitcnt vmcnt(0)
	s_barrier
; template <int NK, bool BNT = false> ...
;     ...
;   auto kstep = [&](int T, int cur, int nxt, bool do_stage) {
;     const unsigned char* sa = smem + cur * BIG_STAGE;
;     bf16x8 af[4], bfr[4];
; #pragma unroll
;     for (int m = 0; m < 4; ++m) af[m] = *reinterpret_cast<const bf16x8*>(sa + aoff + m * 1024);
; #pragma unroll
;     for (int n = 0; n < 4; ++n) bfr[n] = *reinterpret_cast<const bf16x8*>(sa + boff + n * 1024);
;     __builtin_amdgcn_sched_barrier(0);
;     if (do_stage) stage(T + 3, nxt);
; #pragma unroll
;     for (int m = 0; m < 4; ++m)
; #pragma unroll
;       for (int n = 0; n < 4; ++n) acc[m][n] = __builtin_amdgcn_mfma_f32_16x16x32_bf16(af[m], bfr[n], acc[m][n], 0, 0, 0);
;     if (do_stage) {
; #pragma unroll
;       for (int q = 0; q < NG; ++q) {
;         __builtin_amdgcn_sched_group_barrier(0x008, 3, 0);
;         __builtin_amdgcn_sched_group_barrier(0x010, 1, 0);
;       }
;       __builtin_amdgcn_sched_group_barrier(0x008, 16 - 3 * NG, 0);
;     }
;     __builtin_amdgcn_sched_barrier(0);
; #pragma unroll
;     for (int n = 0; n < 4; ++n) bfr[n] = *reinterpret_cast<const bf16x8*>(sa + boff + (4 + n) * 1024);
; #pragma unroll
;     for (int m = 0; m < 4; ++m)
; #pragma unroll
;       for (int n = 0; n < 4; ++n)
;         acc[m][4 + n] = __builtin_amdgcn_mfma_f32_16x16x32_bf16(af[m], bfr[n], acc[m][4 + n], 0, 0, 0);
;     __builtin_amdgcn_sched_barrier(0);
;   };
;     ...
;   stage(0, 0);
;   stage(1, 1);
;   stage(2, 2);
;   for (int it = 0; it < NK / 4 - 1; ++it) {
;     const int t = it * 4;
;     BIG_SYNC(2 * NG); kstep(t, 0, 3, true);
;     BIG_SYNC(2 * NG); kstep(t + 1, 1, 0, true);
;     BIG_SYNC(2 * NG); kstep(t + 2, 2, 1, true);
;     BIG_SYNC(2 * NG); kstep(t + 3, 3, 2, true);
;   }
;   BIG_SYNC(2 * NG); kstep(NK - 4, 0, 3, true);
;   BIG_SYNC(2 * NG); kstep(NK - 3, 1, 0, false);
;   BIG_SYNC(NG);     kstep(NK - 2, 2, 0, false);
;   BIG_SYNC(0);      kstep(NK - 1, 3, 0, false);
; template <int MODE, int NSUB>
; __device__ __forceinline__ void epilogue(const Params& p, int layer, f32x4 (&acc)[4][NSUB], int tm, int tn, int g,
;                                          const float* s_rstd, const int tid_in) {
;     ...
;   } else if constexpr (MODE == EPI_RES) {
;     const int fb = tm * 128 + wr * 64 + fq * 4;
;     const int tb = tn * (NSUB * 32) + wc * (NSUB * 16) + fr;
;     const int fw = tm * 128 + wr * 64 + widen_off(fq);
	s_nop 1
	ds_read_b128 v[4:7], v176
	ds_read_b128 v[8:11], v176 offset:1024
	ds_read_b128 v[154:157], v176 offset:2048
	ds_read_b128 v[12:15], v179
	ds_read_b128 v[24:27], v180
	ds_read_b128 v[28:31], v181
	ds_read_b128 v[56:59], v182
	ds_read_b128 v[248:251], v176 offset:3072
	s_waitcnt lgkmcnt(0)
	v_mfma_f32_16x16x32_bf16 v[108:111], v[4:7], v[24:27], v[120:123]
	v_mfma_f32_16x16x32_bf16 v[92:95], v[4:7], v[28:31], v[116:119]
	v_mfma_f32_16x16x32_bf16 v[76:79], v[4:7], v[56:59], v[112:115]
	v_mfma_f32_16x16x32_bf16 v[104:107], v[8:11], v[24:27], v[104:107]
	v_mfma_f32_16x16x32_bf16 v[88:91], v[8:11], v[28:31], v[100:103]
	v_mfma_f32_16x16x32_bf16 v[72:75], v[8:11], v[56:59], v[96:99]
	v_mfma_f32_16x16x32_bf16 v[100:103], v[154:157], v[24:27], v[232:235]
	v_mfma_f32_16x16x32_bf16 v[84:87], v[154:157], v[28:31], v[68:71]
	v_mfma_f32_16x16x32_bf16 v[68:71], v[154:157], v[56:59], v[64:67]
	v_mfma_f32_16x16x32_bf16 v[116:119], v[248:251], v[12:15], v[44:47]
	v_mfma_f32_16x16x32_bf16 v[96:99], v[248:251], v[24:27], v[40:43]
	v_mfma_f32_16x16x32_bf16 v[80:83], v[248:251], v[28:31], v[36:39]
	v_mfma_f32_16x16x32_bf16 v[64:67], v[248:251], v[56:59], v[32:35]
	v_mfma_f32_16x16x32_bf16 v[178:181], v[4:7], v[12:15], v[124:127]
	v_mfma_f32_16x16x32_bf16 v[224:227], v[8:11], v[12:15], v[224:227]
	v_mfma_f32_16x16x32_bf16 v[120:123], v[154:157], v[12:15], v[228:231]
	ds_read_b128 v[32:35], v142
	ds_read_b128 v[112:115], v143
	ds_read_b128 v[124:127], v144
	ds_read_b128 v[142:145], v145
	s_waitcnt lgkmcnt(0)
	v_mfma_f32_16x16x32_bf16 v[60:63], v[4:7], v[32:35], v[158:161]
	v_mfma_f32_16x16x32_bf16 v[44:47], v[4:7], v[112:115], v[162:165]
	v_mfma_f32_16x16x32_bf16 v[28:31], v[4:7], v[124:127], v[172:175]
	v_mfma_f32_16x16x32_bf16 v[12:15], v[4:7], v[142:145], v[128:131]
	v_mfma_f32_16x16x32_bf16 v[56:59], v[8:11], v[32:35], v[216:219]
	v_mfma_f32_16x16x32_bf16 v[40:43], v[8:11], v[112:115], v[220:223]
	v_mfma_f32_16x16x32_bf16 v[24:27], v[8:11], v[124:127], v[52:55]
	v_mfma_f32_16x16x32_bf16 v[8:11], v[8:11], v[142:145], v[48:51]
	v_mfma_f32_16x16x32_bf16 v[52:55], v[154:157], v[32:35], v[138:141]
	v_mfma_f32_16x16x32_bf16 v[36:39], v[154:157], v[112:115], v[236:239]
	v_mfma_f32_16x16x32_bf16 v[20:23], v[154:157], v[124:127], v[20:23]
	v_mfma_f32_16x16x32_bf16 v[4:7], v[154:157], v[142:145], v[16:19]
	v_mfma_f32_16x16x32_bf16 v[48:51], v[248:251], v[32:35], v[146:149]
	v_mfma_f32_16x16x32_bf16 v[32:35], v[248:251], v[112:115], v[240:243]
	v_mfma_f32_16x16x32_bf16 v[16:19], v[248:251], v[124:127], v[244:247]
	v_mfma_f32_16x16x32_bf16 v[0:3], v[248:251], v[142:145], v[0:3]
	v_lshl_add_u32 v124, s9, 1, v170
	v_mov_b32_e32 v112, v215
	v_lshlrev_b32_e32 v113, 7, v124
	v_ashrrev_i32_e32 v138, 7, v112
	v_lshl_add_u32 v114, v138, 6, v113
	v_lshlrev_b32_e32 v113, 1, v112
	v_and_b32_e32 v113, 0x80, v113
	v_lshl_or_b32 v127, s10, 8, v113
	v_lshrrev_b32_e32 v113, 2, v112
	v_and_b32_e32 v125, 15, v112
	v_and_b32_e32 v113, 8, v113
	v_ashrrev_i32_e32 v115, 2, v127
	v_readlane_b32 s80, v253, 25
	v_ashrrev_i32_e32 v114, 5, v114
	v_bfe_u32 v126, v112, 4, 2
	v_and_or_b32 v112, v112, 16, v113
	v_lshlrev_b32_e32 v156, 6, v125
	v_mov_b32_e32 v157, v153
	v_readlane_b32 s84, v253, 29
	v_readlane_b32 s85, v253, 30
	v_add_u32_e32 v114, v114, v115
	v_lshlrev_b32_e32 v152, 1, v112
	v_lshl_add_u64 v[144:145], s[84:85], 0, v[156:157]
	v_ashrrev_i32_e32 v115, 31, v114
	v_lshl_add_u64 v[112:113], v[144:145], 0, v[152:153]
	v_lshlrev_b64 v[146:147], 13, v[114:115]
	v_or_b32_e32 v114, 1, v114
	v_lshl_add_u64 v[150:151], v[112:113], 0, v[146:147]
	v_ashrrev_i32_e32 v115, 31, v114
	global_load_dwordx4 v[158:161], v[150:151], off
	v_lshlrev_b64 v[148:149], 13, v[114:115]
	v_lshl_add_u64 v[154:155], v[112:113], 0, v[148:149]
	global_load_dwordx4 v[128:131], v[154:155], off
	v_and_b32_e32 v113, 64, v185
	v_xor_b32_e32 v112, 16, v185
	v_add_u32_e32 v113, 64, v113
	v_cmp_lt_i32_e32 vcc, v112, v113
	v_or_b32_e32 v142, v127, v125
	v_lshlrev_b32_e32 v140, 1, v124
	v_cndmask_b32_e32 v112, v185, v112, vcc
	v_lshlrev_b32_e32 v172, 2, v112
	v_xor_b32_e32 v112, 32, v185
	v_cmp_lt_i32_e32 vcc, v112, v113
	v_ashrrev_i32_e32 v141, 31, v140
	v_ashrrev_i32_e32 v139, 31, v138
	v_cndmask_b32_e32 v112, v185, v112, vcc
	v_lshlrev_b32_e32 v173, 2, v112
	v_cmp_eq_u32_e32 vcc, 0, v126
	global_load_dwordx4 v[124:127], v[150:151], off offset:1024
	global_load_dwordx4 v[112:115], v[154:155], off offset:1024
	v_readlane_b32 s81, v253, 26
	v_readlane_b32 s82, v253, 27
	v_readlane_b32 s83, v253, 28
	v_readlane_b32 s86, v253, 31
	v_readlane_b32 s87, v253, 32
	v_readlane_b32 s88, v253, 33
	v_readlane_b32 s89, v253, 34
	v_readlane_b32 s90, v253, 35
	v_readlane_b32 s91, v253, 36
	v_readlane_b32 s92, v253, 37
	v_readlane_b32 s93, v253, 38
	v_readlane_b32 s94, v253, 39
	v_readlane_b32 s95, v253, 40
	s_waitcnt vmcnt(0)
; __device__ __forceinline__ float bf2f(bf16_t b) { return __uint_as_float(((unsigned)b) << 16); }
; __device__ __forceinline__ int widen_off(int fq) { return ((fq & 1) << 4) + ((fq >> 1) << 3); }
; template <int MODE, int NSUB>
; __device__ __forceinline__ void epilogue(const Params& p, int layer, f32x4 (&acc)[4][NSUB], int tm, int tn, int g,
;                                          const float* s_rstd, const int tid_in) {
;     ...
;       bf16x4 cur[4];
;       unwiden_pair(curw[0], cur[0], cur[1]);
;       unwiden_pair(curw[1], cur[2], cur[3]);
;       const int t = tb + n * 16;
;       float ss = 0.f;
; #pragma unroll
;       for (int mp = 0; mp < 2; ++mp) {
;         bf16x4 pk[2];
; #pragma unroll
;         for (int h2 = 0; h2 < 2; ++h2) {
;           const int m = mp * 2 + h2;
;           const float x0 = bf2f((bf16_t)cur[m][0]) + acc[m][n][0], x1 = bf2f((bf16_t)cur[m][1]) + acc[m][n][1];
;           const float x2 = bf2f((bf16_t)cur[m][2]) + acc[m][n][2], x3 = bf2f((bf16_t)cur[m][3]) + acc[m][n][3];
;           ss += x0 * x0 + x1 * x1 + x2 * x2 + x3 * x3;
;           pk[h2] = pack4(x0, x1, x2, x3);
;         }
;         const int f = tm * 128 + wr * 64 + mp * 32 + widen_off(fq);
;         *reinterpret_cast<u32x4*>(p.xb + blk(t, f, 32)) = widen_pair(pk[0], pk[1]);
;       }
;       ss = red_fq(ss);
;       if (fq == 0) p.part[(long)t * 16 + tm * 2 + wr] = ss;
	v_mov_b32_e32 v143, v160
	s_nop 1
	v_permlane16_swap_b32_e32 v158, v143
	v_mov_b32_e32 v164, v161
	s_nop 1
	v_permlane16_swap_b32_e32 v159, v164
	v_mov_b32_e32 v176, v130
	v_mov_b32_e32 v182, v131
	v_and_b32_e32 v131, 0xffff0000, v158
	v_lshlrev_b32_e32 v130, 16, v158
	v_pk_add_f32 v[130:131], v[178:179], v[130:131]
	v_and_b32_e32 v161, 0xffff0000, v159
	v_lshlrev_b32_e32 v160, 16, v159
	v_pk_add_f32 v[162:163], v[180:181], v[160:161]
	v_pk_mul_f32 v[160:161], v[130:131], v[130:131]
	v_cvt_pk_bf16_f32 v178, v130, v131
	v_and_b32_e32 v131, 0xffff0000, v143
	v_lshlrev_b32_e32 v130, 16, v143
	v_pk_mul_f32 v[158:159], v[162:163], v[162:163]
	v_cvt_pk_bf16_f32 v179, v162, v163
	v_pk_add_f32 v[130:131], v[224:225], v[130:131]
	v_and_b32_e32 v163, 0xffff0000, v164
	v_lshlrev_b32_e32 v162, 16, v164
	v_pk_add_f32 v[174:175], v[226:227], v[162:163]
	v_pk_mul_f32 v[164:165], v[130:131], v[130:131]
	v_cvt_pk_bf16_f32 v180, v130, v131
	v_lshl_add_u64 v[130:131], s[84:85], 0, v[146:147]
	v_pk_mul_f32 v[162:163], v[174:175], v[174:175]
	v_cvt_pk_bf16_f32 v181, v174, v175
	v_lshl_add_u64 v[174:175], v[130:131], 0, v[156:157]
	v_permlane16_swap_b32_e32 v128, v176
	v_permlane16_swap_b32_e32 v178, v180
	v_permlane16_swap_b32_e32 v179, v181
	v_lshl_add_u64 v[174:175], v[174:175], 0, v[152:153]
	v_permlane16_swap_b32_e32 v129, v182
	global_store_dwordx4 v[174:175], v[178:181], off
	v_and_b32_e32 v175, 0xffff0000, v128
	v_lshlrev_b32_e32 v174, 16, v128
	v_pk_add_f32 v[120:121], v[120:121], v[174:175]
	v_and_b32_e32 v175, 0xffff0000, v129
	v_lshlrev_b32_e32 v174, 16, v129
	v_pk_add_f32 v[122:123], v[122:123], v[174:175]
	v_pk_mul_f32 v[128:129], v[120:121], v[120:121]
	v_pk_mul_f32 v[174:175], v[122:123], v[122:123]
	v_cvt_pk_bf16_f32 v120, v120, v121
	v_cvt_pk_bf16_f32 v121, v122, v123
	v_and_b32_e32 v123, 0xffff0000, v176
	v_lshlrev_b32_e32 v122, 16, v176
	v_pk_add_f32 v[116:117], v[116:117], v[122:123]
	v_and_b32_e32 v123, 0xffff0000, v182
	v_lshlrev_b32_e32 v122, 16, v182
	v_add_f32_e32 v143, v164, v165
	v_add_f32_e32 v160, v160, v161
	v_pk_add_f32 v[118:119], v[118:119], v[122:123]
	v_pk_mul_f32 v[122:123], v[116:117], v[116:117]
	v_add_f32_e32 v143, v162, v143
	v_add_f32_e32 v158, v158, v160
	v_add_f32_e32 v128, v128, v129
	v_pk_mul_f32 v[178:179], v[118:119], v[118:119]
	v_add_f32_e32 v143, v163, v143
	v_add_f32_e32 v158, v159, v158
	v_add_f32_e32 v128, v174, v128
	v_add_f32_e32 v122, v122, v123
	v_add_f32_e32 v143, v158, v143
	v_add_f32_e32 v128, v175, v128
	v_add_f32_e32 v122, v178, v122
	v_add_f32_e32 v128, v143, v128
	v_add_f32_e32 v122, v179, v122
	v_add_f32_e32 v143, v122, v128
	v_lshl_add_u64 v[128:129], s[84:85], 0, v[148:149]
	v_cvt_pk_bf16_f32 v122, v116, v117
	v_cvt_pk_bf16_f32 v123, v118, v119
	v_lshl_add_u64 v[116:117], v[128:129], 0, v[156:157]
	v_permlane16_swap_b32_e32 v120, v122
	v_permlane16_swap_b32_e32 v121, v123
	v_lshl_add_u64 v[116:117], v[116:117], 0, v[152:153]
	global_store_dwordx4 v[116:117], v[120:123], off
	ds_bpermute_b32 v116, v172, v143
	s_waitcnt lgkmcnt(0)
	v_add_f32_e32 v116, v143, v116
	ds_bpermute_b32 v117, v173, v116
	s_and_saveexec_b64 s[10:11], vcc
	s_cbranch_execz .LBB0_71
	v_ashrrev_i32_e32 v143, 31, v142
	v_readlane_b32 s64, v253, 25
	v_lshlrev_b64 v[118:119], 6, v[142:143]
	v_readlane_b32 s70, v253, 31
	v_readlane_b32 s71, v253, 32
	s_waitcnt lgkmcnt(0)
	v_add_f32_e32 v116, v116, v117
	v_readlane_b32 s65, v253, 26
	v_lshl_add_u64 v[118:119], s[70:71], 0, v[118:119]
	v_lshl_add_u64 v[118:119], v[140:141], 2, v[118:119]
	v_lshl_add_u64 v[118:119], v[138:139], 2, v[118:119]
	v_readlane_b32 s66, v253, 27
	v_readlane_b32 s67, v253, 28
	v_readlane_b32 s68, v253, 29
	v_readlane_b32 s69, v253, 30
	v_readlane_b32 s72, v253, 33
	v_readlane_b32 s73, v253, 34
	v_readlane_b32 s74, v253, 35
	v_readlane_b32 s75, v253, 36
	v_readlane_b32 s76, v253, 37
	v_readlane_b32 s77, v253, 38
	v_readlane_b32 s78, v253, 39
	v_readlane_b32 s79, v253, 40
	global_store_dword v[118:119], v116, off

; #define BIG_SYNC(N)                                              \
;   asm volatile("s_waitcnt vmcnt(%0)" ::"n"(N) : "memory");       \
;   __builtin_amdgcn_s_barrier();                                  \
;   asm volatile("" ::: "memory");                                 \
;   __builtin_amdgcn_sched_barrier(0);
; template <int NK, bool BNT = false> ...
;     ...
;   auto kstep = [&](int T, int cur, int nxt, bool do_stage) {
;     const unsigned char* sa = smem + cur * BIG_STAGE;
;     bf16x8 af[4], bfr[4];
; #pragma unroll
;     for (int m = 0; m < 4; ++m) af[m] = *reinterpret_cast<const bf16x8*>(sa + aoff + m * 1024);
; #pragma unroll
;     for (int n = 0; n < 4; ++n) bfr[n] = *reinterpret_cast<const bf16x8*>(sa + boff + n * 1024);
;     __builtin_amdgcn_sched_barrier(0);
;     if (do_stage) stage(T + 3, nxt);
; #pragma unroll
;     for (int m = 0; m < 4; ++m)
; #pragma unroll
;       for (int n = 0; n < 4; ++n) acc[m][n] = __builtin_amdgcn_mfma_f32_16x16x32_bf16(af[m], bfr[n], acc[m][n], 0, 0, 0);
;     if (do_stage) {
; #pragma unroll
;       for (int q = 0; q < NG; ++q) {
;         __builtin_amdgcn_sched_group_barrier(0x008, 3, 0);
;         __builtin_amdgcn_sched_group_barrier(0x010, 1, 0);
;       }
;       __builtin_amdgcn_sched_group_barrier(0x008, 16 - 3 * NG, 0);
;     }
;     __builtin_amdgcn_sched_barrier(0);
; #pragma unroll
;     for (int n = 0; n < 4; ++n) bfr[n] = *reinterpret_cast<const bf16x8*>(sa + boff + (4 + n) * 1024);
; #pragma unroll
;     for (int m = 0; m < 4; ++m)
; #pragma unroll
;       for (int n = 0; n < 4; ++n)
;         acc[m][4 + n] = __builtin_amdgcn_mfma_f32_16x16x32_bf16(af[m], bfr[n], acc[m][4 + n], 0, 0, 0);
;     __builtin_amdgcn_sched_barrier(0);
;   };
;     ...
;   stage(0, 0);
;   stage(1, 1);
;   stage(2, 2);
;   for (int it = 0; it < NK / 4 - 1; ++it) {
;     const int t = it * 4;
;     BIG_SYNC(2 * NG); kstep(t, 0, 3, true);
;     BIG_SYNC(2 * NG); kstep(t + 1, 1, 0, true);
;     BIG_SYNC(2 * NG); kstep(t + 2, 2, 1, true);
;     BIG_SYNC(2 * NG); kstep(t + 3, 3, 2, true);
;   }
.LBB0_264:
	v_add_u32_e32 v158, 0x18000, v166
	v_lshl_add_u64 v[144:145], v[138:139], 0, s[36:37]
	v_readfirstlane_b32 s13, v158
	v_add_u32_e32 v159, 0x1a000, v166
	v_lshl_add_u64 v[160:161], v[144:145], 0, s[60:61]
	s_mov_b32 m0, s13
	v_readfirstlane_b32 s13, v159
	s_waitcnt lgkmcnt(3)
	v_mfma_f32_16x16x32_bf16 v[124:127], v[216:219], v[232:235], v[124:127]
	v_lshl_add_u64 v[142:143], v[140:141], 0, s[36:37]
	v_lshl_add_u64 v[182:183], v[142:143], 0, s[60:61]
	v_mfma_f32_16x16x32_bf16 v[108:111], v[220:223], v[232:235], v[108:111]
	v_mfma_f32_16x16x32_bf16 v[88:91], v[224:227], v[232:235], v[88:91]
	s_waitcnt vmcnt(4)
	s_barrier
	global_load_lds_dwordx4 v[160:161], off
	v_lshl_add_u64 v[160:161], v[144:145], 0, s[18:19]
	s_mov_b32 m0, s13
	v_mfma_f32_16x16x32_bf16 v[44:47], v[228:231], v[232:235], v[44:47]
	s_waitcnt lgkmcnt(2)
	v_mfma_f32_16x16x32_bf16 v[120:123], v[216:219], v[236:239], v[120:123]
	ds_read_b128 v[232:235], v168 offset:20480
	v_mfma_f32_16x16x32_bf16 v[104:107], v[220:223], v[236:239], v[104:107]
	ds_read_b128 v[186:189], v167 offset:32768
	global_load_lds_dwordx4 v[160:161], off
	v_add_u32_e32 v160, 0x1c000, v166
	v_add_u32_e32 v161, 0x1e000, v166
	v_readfirstlane_b32 s13, v160
	s_mov_b32 m0, s13
	v_readfirstlane_b32 s13, v161
	v_mfma_f32_16x16x32_bf16 v[76:79], v[224:227], v[236:239], v[76:79]
	ds_read_b128 v[190:193], v167 offset:33792
	v_mfma_f32_16x16x32_bf16 v[40:43], v[228:231], v[236:239], v[40:43]
	ds_read_b128 v[194:197], v167 offset:34816
	s_waitcnt lgkmcnt(5)
	v_mfma_f32_16x16x32_bf16 v[116:119], v[216:219], v[240:243], v[116:119]
	ds_read_b128 v[236:239], v168 offset:21504
	global_load_lds_dwordx4 v[182:183], off nt
	v_lshl_add_u64 v[182:183], v[142:143], 0, s[18:19]
	s_mov_b32 m0, s13
	v_mfma_f32_16x16x32_bf16 v[100:103], v[220:223], v[240:243], v[100:103]
	ds_read_b128 v[202:205], v167 offset:35840
	v_mfma_f32_16x16x32_bf16 v[68:71], v[224:227], v[240:243], v[68:71]
	v_mfma_f32_16x16x32_bf16 v[36:39], v[228:231], v[240:243], v[36:39]
	global_load_lds_dwordx4 v[182:183], off nt
	s_waitcnt lgkmcnt(6)
	v_mfma_f32_16x16x32_bf16 v[112:115], v[216:219], v[244:247], v[112:115]
	ds_read_b128 v[240:243], v168 offset:22528
	v_mfma_f32_16x16x32_bf16 v[96:99], v[220:223], v[244:247], v[96:99]
	v_mfma_f32_16x16x32_bf16 v[64:67], v[224:227], v[244:247], v[64:67]
	v_mfma_f32_16x16x32_bf16 v[32:35], v[228:231], v[244:247], v[32:35]
	s_waitcnt lgkmcnt(6)
	v_mfma_f32_16x16x32_bf16 v[92:95], v[216:219], v[232:235], v[92:95]
	ds_read_b128 v[244:247], v168 offset:23552
	v_mfma_f32_16x16x32_bf16 v[60:63], v[220:223], v[232:235], v[60:63]
	v_mfma_f32_16x16x32_bf16 v[28:31], v[224:227], v[232:235], v[28:31]
	v_mfma_f32_16x16x32_bf16 v[12:15], v[228:231], v[232:235], v[12:15]
	s_waitcnt lgkmcnt(3)
	v_mfma_f32_16x16x32_bf16 v[84:87], v[216:219], v[236:239], v[84:87]
	ds_read_b128 v[232:235], v168 offset:49152
	v_mfma_f32_16x16x32_bf16 v[56:59], v[220:223], v[236:239], v[56:59]
	v_mfma_f32_16x16x32_bf16 v[24:27], v[224:227], v[236:239], v[24:27]
	v_mfma_f32_16x16x32_bf16 v[8:11], v[228:231], v[236:239], v[8:11]
	s_waitcnt lgkmcnt(2)
	v_mfma_f32_16x16x32_bf16 v[80:83], v[216:219], v[240:243], v[80:83]
	ds_read_b128 v[236:239], v168 offset:50176
	v_mfma_f32_16x16x32_bf16 v[52:55], v[220:223], v[240:243], v[52:55]
	v_mfma_f32_16x16x32_bf16 v[20:23], v[224:227], v[240:243], v[20:23]
	v_mfma_f32_16x16x32_bf16 v[4:7], v[228:231], v[240:243], v[4:7]
	s_waitcnt lgkmcnt(2)
	v_mfma_f32_16x16x32_bf16 v[72:75], v[216:219], v[244:247], v[72:75]
	ds_read_b128 v[240:243], v168 offset:51200
	v_mfma_f32_16x16x32_bf16 v[48:51], v[220:223], v[244:247], v[48:51]
	v_mfma_f32_16x16x32_bf16 v[16:19], v[224:227], v[244:247], v[16:19]
	v_mfma_f32_16x16x32_bf16 v[0:3], v[228:231], v[244:247], v[0:3]
	ds_read_b128 v[244:247], v168 offset:52224
	v_readfirstlane_b32 s13, v166
	v_lshl_add_u64 v[182:183], v[144:145], 0, s[62:63]
	s_mov_b32 m0, s13
	v_readfirstlane_b32 s13, v146
	s_waitcnt lgkmcnt(3)
	v_mfma_f32_16x16x32_bf16 v[124:127], v[186:189], v[232:235], v[124:127]
	v_lshl_add_u64 v[198:199], v[142:143], 0, s[62:63]
	v_mfma_f32_16x16x32_bf16 v[108:111], v[190:193], v[232:235], v[108:111]
	v_mfma_f32_16x16x32_bf16 v[88:91], v[194:197], v[232:235], v[88:91]
	s_waitcnt vmcnt(4)
	s_barrier
; #define BIG_SYNC(N)                                              \
;   asm volatile("s_waitcnt vmcnt(%0)" ::"n"(N) : "memory");       \
;   __builtin_amdgcn_s_barrier();                                  \
;   asm volatile("" ::: "memory");                                 \
;   __builtin_amdgcn_sched_barrier(0);
; template <int NK, bool BNT = false> ...
;     ...
;   auto kstep = [&](int T, int cur, int nxt, bool do_stage) {
;     const unsigned char* sa = smem + cur * BIG_STAGE;
;     bf16x8 af[4], bfr[4];
; #pragma unroll
;     for (int m = 0; m < 4; ++m) af[m] = *reinterpret_cast<const bf16x8*>(sa + aoff + m * 1024);
; #pragma unroll
;     for (int n = 0; n < 4; ++n) bfr[n] = *reinterpret_cast<const bf16x8*>(sa + boff + n * 1024);
;     __builtin_amdgcn_sched_barrier(0);
;     if (do_stage) stage(T + 3, nxt);
; #pragma unroll
;     for (int m = 0; m < 4; ++m)
; #pragma unroll
;       for (int n = 0; n < 4; ++n) acc[m][n] = __builtin_amdgcn_mfma_f32_16x16x32_bf16(af[m], bfr[n], acc[m][n], 0, 0, 0);
;     if (do_stage) {
; #pragma unroll
;       for (int q = 0; q < NG; ++q) {
;         __builtin_amdgcn_sched_group_barrier(0x008, 3, 0);
;         __builtin_amdgcn_sched_group_barrier(0x010, 1, 0);
;       }
;       __builtin_amdgcn_sched_group_barrier(0x008, 16 - 3 * NG, 0);
;     }
;     __builtin_amdgcn_sched_barrier(0);
; #pragma unroll
;     for (int n = 0; n < 4; ++n) bfr[n] = *reinterpret_cast<const bf16x8*>(sa + boff + (4 + n) * 1024);
; #pragma unroll
;     for (int m = 0; m < 4; ++m)
; #pragma unroll
;       for (int n = 0; n < 4; ++n)
;         acc[m][4 + n] = __builtin_amdgcn_mfma_f32_16x16x32_bf16(af[m], bfr[n], acc[m][4 + n], 0, 0, 0);
;     __builtin_amdgcn_sched_barrier(0);
;   };
;     ...
;   stage(0, 0);
;   stage(1, 1);
;   stage(2, 2);
;   for (int it = 0; it < NK / 4 - 1; ++it) {
;     const int t = it * 4;
;     BIG_SYNC(2 * NG); kstep(t, 0, 3, true);
;     BIG_SYNC(2 * NG); kstep(t + 1, 1, 0, true);
;     BIG_SYNC(2 * NG); kstep(t + 2, 2, 1, true);
;     BIG_SYNC(2 * NG); kstep(t + 3, 3, 2, true);
;   }
	global_load_lds_dwordx4 v[182:183], off
	v_lshl_add_u64 v[182:183], v[144:145], 0, s[20:21]
	s_mov_b32 m0, s13
	v_readfirstlane_b32 s13, v147
	v_mfma_f32_16x16x32_bf16 v[44:47], v[202:205], v[232:235], v[44:47]
	s_waitcnt lgkmcnt(2)
	v_mfma_f32_16x16x32_bf16 v[120:123], v[186:189], v[236:239], v[120:123]
	ds_read_b128 v[232:235], v168 offset:53248
	v_mfma_f32_16x16x32_bf16 v[104:107], v[190:193], v[236:239], v[104:107]
	v_add_u32_e32 v162, 0x10000, v167
	ds_read_b128 v[216:219], v162
	global_load_lds_dwordx4 v[182:183], off
	s_mov_b32 m0, s13
	v_readfirstlane_b32 s13, v148
	v_lshl_add_u64 v[182:183], v[142:143], 0, s[20:21]
	v_mfma_f32_16x16x32_bf16 v[76:79], v[194:197], v[236:239], v[76:79]
	ds_read_b128 v[220:223], v162 offset:1024
	v_mfma_f32_16x16x32_bf16 v[40:43], v[202:205], v[236:239], v[40:43]
	ds_read_b128 v[224:227], v162 offset:2048
	s_waitcnt lgkmcnt(5)
	v_mfma_f32_16x16x32_bf16 v[116:119], v[186:189], v[240:243], v[116:119]
	ds_read_b128 v[236:239], v168 offset:54272
	global_load_lds_dwordx4 v[198:199], off nt
	s_mov_b32 m0, s13
	v_mfma_f32_16x16x32_bf16 v[100:103], v[190:193], v[240:243], v[100:103]
	ds_read_b128 v[228:231], v162 offset:3072
	v_mfma_f32_16x16x32_bf16 v[68:71], v[194:197], v[240:243], v[68:71]
	v_mfma_f32_16x16x32_bf16 v[36:39], v[202:205], v[240:243], v[36:39]
	global_load_lds_dwordx4 v[182:183], off nt
	s_waitcnt lgkmcnt(6)
	v_mfma_f32_16x16x32_bf16 v[112:115], v[186:189], v[244:247], v[112:115]
	ds_read_b128 v[240:243], v168 offset:55296
	v_mfma_f32_16x16x32_bf16 v[96:99], v[190:193], v[244:247], v[96:99]
	v_mfma_f32_16x16x32_bf16 v[64:67], v[194:197], v[244:247], v[64:67]
	v_mfma_f32_16x16x32_bf16 v[32:35], v[202:205], v[244:247], v[32:35]
	v_or_b32_e32 v163, 0x10000, v169
	s_waitcnt lgkmcnt(6)
	v_mfma_f32_16x16x32_bf16 v[92:95], v[186:189], v[232:235], v[92:95]
	ds_read_b128 v[244:247], v168 offset:56320
	v_mfma_f32_16x16x32_bf16 v[60:63], v[190:193], v[232:235], v[60:63]
	v_mfma_f32_16x16x32_bf16 v[28:31], v[194:197], v[232:235], v[28:31]
	v_mfma_f32_16x16x32_bf16 v[12:15], v[202:205], v[232:235], v[12:15]
	s_waitcnt lgkmcnt(3)
	v_mfma_f32_16x16x32_bf16 v[84:87], v[186:189], v[236:239], v[84:87]
	ds_read_b128 v[232:235], v163
	v_mfma_f32_16x16x32_bf16 v[56:59], v[190:193], v[236:239], v[56:59]
	v_mfma_f32_16x16x32_bf16 v[24:27], v[194:197], v[236:239], v[24:27]
	v_mfma_f32_16x16x32_bf16 v[8:11], v[202:205], v[236:239], v[8:11]
	s_waitcnt lgkmcnt(2)
	v_mfma_f32_16x16x32_bf16 v[80:83], v[186:189], v[240:243], v[80:83]
	ds_read_b128 v[236:239], v163 offset:1024
	v_mfma_f32_16x16x32_bf16 v[52:55], v[190:193], v[240:243], v[52:55]
	v_mfma_f32_16x16x32_bf16 v[20:23], v[194:197], v[240:243], v[20:23]
	v_mfma_f32_16x16x32_bf16 v[4:7], v[202:205], v[240:243], v[4:7]
	s_waitcnt lgkmcnt(2)
	v_mfma_f32_16x16x32_bf16 v[72:75], v[186:189], v[244:247], v[72:75]
	ds_read_b128 v[240:243], v163 offset:2048
	v_mfma_f32_16x16x32_bf16 v[48:51], v[190:193], v[244:247], v[48:51]
	v_mfma_f32_16x16x32_bf16 v[16:19], v[194:197], v[244:247], v[16:19]
	v_mfma_f32_16x16x32_bf16 v[0:3], v[202:205], v[244:247], v[0:3]
	ds_read_b128 v[244:247], v163 offset:3072
	v_add_u32_e32 v162, 0x10000, v167
	v_or_b32_e32 v163, 0x10000, v169
	v_add_u32_e32 v164, 0x10400, v169
	v_add_u32_e32 v165, 0x10800, v169
	v_add_u32_e32 v172, 0x10c00, v169
	v_readfirstlane_b32 s13, v149
	v_lshl_add_u64 v[174:175], v[144:145], 0, s[2:3]
	s_mov_b32 m0, s13
	v_readfirstlane_b32 s13, v150
	s_waitcnt lgkmcnt(3)
	v_mfma_f32_16x16x32_bf16 v[124:127], v[216:219], v[232:235], v[124:127]
	v_lshl_add_u64 v[178:179], v[142:143], 0, s[2:3]
	v_mfma_f32_16x16x32_bf16 v[108:111], v[220:223], v[232:235], v[108:111]
	v_mfma_f32_16x16x32_bf16 v[88:91], v[224:227], v[232:235], v[88:91]
	s_waitcnt vmcnt(4)
	s_barrier
	global_load_lds_dwordx4 v[174:175], off
	v_lshl_add_u64 v[174:175], v[144:145], 0, s[22:23]
	s_mov_b32 m0, s13
	v_readfirstlane_b32 s13, v151
	v_mfma_f32_16x16x32_bf16 v[44:47], v[228:231], v[232:235], v[44:47]
	s_waitcnt lgkmcnt(2)
	v_mfma_f32_16x16x32_bf16 v[120:123], v[216:219], v[236:239], v[120:123]
	ds_read_b128 v[232:235], v163 offset:4096
	v_mfma_f32_16x16x32_bf16 v[104:107], v[220:223], v[236:239], v[104:107]
	v_add_u32_e32 v162, 0x10000, v167
	ds_read_b128 v[186:189], v162 offset:32768
	global_load_lds_dwordx4 v[174:175], off
	s_mov_b32 m0, s13
	v_readfirstlane_b32 s13, v152
	v_lshl_add_u64 v[174:175], v[142:143], 0, s[22:23]
	v_mfma_f32_16x16x32_bf16 v[76:79], v[224:227], v[236:239], v[76:79]
	ds_read_b128 v[190:193], v162 offset:33792
	v_mfma_f32_16x16x32_bf16 v[40:43], v[228:231], v[236:239], v[40:43]
	ds_read_b128 v[194:197], v162 offset:34816
	s_waitcnt lgkmcnt(5)
	v_mfma_f32_16x16x32_bf16 v[116:119], v[216:219], v[240:243], v[116:119]
	ds_read_b128 v[236:239], v163 offset:5120
	global_load_lds_dwordx4 v[178:179], off nt
	s_mov_b32 m0, s13
	v_mfma_f32_16x16x32_bf16 v[100:103], v[220:223], v[240:243], v[100:103]
	ds_read_b128 v[202:205], v162 offset:35840
	v_mfma_f32_16x16x32_bf16 v[68:71], v[224:227], v[240:243], v[68:71]
	v_mfma_f32_16x16x32_bf16 v[36:39], v[228:231], v[240:243], v[36:39]
	global_load_lds_dwordx4 v[174:175], off nt
	s_waitcnt lgkmcnt(6)
	v_mfma_f32_16x16x32_bf16 v[112:115], v[216:219], v[244:247], v[112:115]
	ds_read_b128 v[240:243], v163 offset:6144
	v_mfma_f32_16x16x32_bf16 v[96:99], v[220:223], v[244:247], v[96:99]
	v_mfma_f32_16x16x32_bf16 v[64:67], v[224:227], v[244:247], v[64:67]
	v_mfma_f32_16x16x32_bf16 v[32:35], v[228:231], v[244:247], v[32:35]
	v_add_u32_e32 v173, 0x11000, v169
	v_add_u32_e32 v174, 0x11400, v169
	v_add_u32_e32 v175, 0x11800, v169
	v_add_u32_e32 v178, 0x11c00, v169
	v_or_b32_e32 v163, 0x10000, v169
	s_waitcnt lgkmcnt(6)
; #define BIG_SYNC(N)                                              \
;   asm volatile("s_waitcnt vmcnt(%0)" ::"n"(N) : "memory");       \
;   __builtin_amdgcn_s_barrier();                                  \
;   asm volatile("" ::: "memory");                                 \
;   __builtin_amdgcn_sched_barrier(0);
; template <int NK, bool BNT = false> ...
;     ...
;   auto kstep = [&](int T, int cur, int nxt, bool do_stage) {
;     const unsigned char* sa = smem + cur * BIG_STAGE;
;     bf16x8 af[4], bfr[4];
; #pragma unroll
;     for (int m = 0; m < 4; ++m) af[m] = *reinterpret_cast<const bf16x8*>(sa + aoff + m * 1024);
; #pragma unroll
;     for (int n = 0; n < 4; ++n) bfr[n] = *reinterpret_cast<const bf16x8*>(sa + boff + n * 1024);
;     __builtin_amdgcn_sched_barrier(0);
;     if (do_stage) stage(T + 3, nxt);
; #pragma unroll
;     for (int m = 0; m < 4; ++m)
; #pragma unroll
;       for (int n = 0; n < 4; ++n) acc[m][n] = __builtin_amdgcn_mfma_f32_16x16x32_bf16(af[m], bfr[n], acc[m][n], 0, 0, 0);
;     if (do_stage) {
; #pragma unroll
;       for (int q = 0; q < NG; ++q) {
;         __builtin_amdgcn_sched_group_barrier(0x008, 3, 0);
;         __builtin_amdgcn_sched_group_barrier(0x010, 1, 0);
;       }
;       __builtin_amdgcn_sched_group_barrier(0x008, 16 - 3 * NG, 0);
;     }
;     __builtin_amdgcn_sched_barrier(0);
; #pragma unroll
;     for (int n = 0; n < 4; ++n) bfr[n] = *reinterpret_cast<const bf16x8*>(sa + boff + (4 + n) * 1024);
; #pragma unroll
;     for (int m = 0; m < 4; ++m)
; #pragma unroll
;       for (int n = 0; n < 4; ++n)
;         acc[m][4 + n] = __builtin_amdgcn_mfma_f32_16x16x32_bf16(af[m], bfr[n], acc[m][4 + n], 0, 0, 0);
;     __builtin_amdgcn_sched_barrier(0);
;   };
;     ...
;   stage(0, 0);
;   stage(1, 1);
;   stage(2, 2);
;   for (int it = 0; it < NK / 4 - 1; ++it) {
;     const int t = it * 4;
;     BIG_SYNC(2 * NG); kstep(t, 0, 3, true);
;     BIG_SYNC(2 * NG); kstep(t + 1, 1, 0, true);
;     BIG_SYNC(2 * NG); kstep(t + 2, 2, 1, true);
;     BIG_SYNC(2 * NG); kstep(t + 3, 3, 2, true);
;   }
	v_mfma_f32_16x16x32_bf16 v[92:95], v[216:219], v[232:235], v[92:95]
	ds_read_b128 v[244:247], v163 offset:7168
	v_mfma_f32_16x16x32_bf16 v[60:63], v[220:223], v[232:235], v[60:63]
	v_mfma_f32_16x16x32_bf16 v[28:31], v[224:227], v[232:235], v[28:31]
	v_mfma_f32_16x16x32_bf16 v[12:15], v[228:231], v[232:235], v[12:15]
	s_waitcnt lgkmcnt(3)
	v_mfma_f32_16x16x32_bf16 v[84:87], v[216:219], v[236:239], v[84:87]
	ds_read_b128 v[232:235], v163 offset:32768
	v_mfma_f32_16x16x32_bf16 v[56:59], v[220:223], v[236:239], v[56:59]
	v_mfma_f32_16x16x32_bf16 v[24:27], v[224:227], v[236:239], v[24:27]
	v_mfma_f32_16x16x32_bf16 v[8:11], v[228:231], v[236:239], v[8:11]
	s_waitcnt lgkmcnt(2)
	v_mfma_f32_16x16x32_bf16 v[80:83], v[216:219], v[240:243], v[80:83]
	ds_read_b128 v[236:239], v163 offset:33792
	v_mfma_f32_16x16x32_bf16 v[52:55], v[220:223], v[240:243], v[52:55]
	v_mfma_f32_16x16x32_bf16 v[20:23], v[224:227], v[240:243], v[20:23]
	v_mfma_f32_16x16x32_bf16 v[4:7], v[228:231], v[240:243], v[4:7]
	s_waitcnt lgkmcnt(2)
	v_mfma_f32_16x16x32_bf16 v[72:75], v[216:219], v[244:247], v[72:75]
	ds_read_b128 v[240:243], v163 offset:34816
	v_mfma_f32_16x16x32_bf16 v[48:51], v[220:223], v[244:247], v[48:51]
	v_mfma_f32_16x16x32_bf16 v[16:19], v[224:227], v[244:247], v[16:19]
	v_mfma_f32_16x16x32_bf16 v[0:3], v[228:231], v[244:247], v[0:3]
	ds_read_b128 v[244:247], v163 offset:35840
	v_add_u32_e32 v176, 0x18000, v167
	v_or_b32_e32 v179, 0x18000, v169
	v_add_u32_e32 v180, 0x18400, v169
	v_add_u32_e32 v181, 0x18800, v169
	v_add_u32_e32 v182, 0x18c00, v169
	v_readfirstlane_b32 s13, v154
	v_lshl_add_u64 v[248:249], v[144:145], 0, s[54:55]
	s_mov_b32 m0, s13
	v_readfirstlane_b32 s13, v155
	v_lshl_add_u64 v[144:145], v[144:145], 0, s[24:25]
	s_waitcnt lgkmcnt(3)
	v_mfma_f32_16x16x32_bf16 v[124:127], v[186:189], v[232:235], v[124:127]
	v_lshl_add_u64 v[250:251], v[142:143], 0, s[54:55]
	v_lshl_add_u64 v[142:143], v[142:143], 0, s[24:25]
	v_mfma_f32_16x16x32_bf16 v[108:111], v[190:193], v[232:235], v[108:111]
	v_mfma_f32_16x16x32_bf16 v[88:91], v[194:197], v[232:235], v[88:91]
	s_waitcnt vmcnt(4)
	s_barrier
	global_load_lds_dwordx4 v[248:249], off
	s_mov_b32 m0, s13
	v_readfirstlane_b32 s13, v156
	v_mfma_f32_16x16x32_bf16 v[44:47], v[202:205], v[232:235], v[44:47]
	s_waitcnt lgkmcnt(2)
	v_mfma_f32_16x16x32_bf16 v[120:123], v[186:189], v[236:239], v[120:123]
	ds_read_b128 v[232:235], v163 offset:36864
	v_mfma_f32_16x16x32_bf16 v[104:107], v[190:193], v[236:239], v[104:107]
	ds_read_b128 v[216:219], v167
	global_load_lds_dwordx4 v[144:145], off
	s_mov_b32 m0, s13
	v_readfirstlane_b32 s13, v157
	v_mfma_f32_16x16x32_bf16 v[76:79], v[194:197], v[236:239], v[76:79]
	ds_read_b128 v[220:223], v167 offset:1024
	v_mfma_f32_16x16x32_bf16 v[40:43], v[202:205], v[236:239], v[40:43]
	ds_read_b128 v[224:227], v167 offset:2048
	s_waitcnt lgkmcnt(5)
	v_mfma_f32_16x16x32_bf16 v[116:119], v[186:189], v[240:243], v[116:119]
	ds_read_b128 v[236:239], v163 offset:37888
	global_load_lds_dwordx4 v[250:251], off nt
	s_mov_b32 m0, s13
	v_mfma_f32_16x16x32_bf16 v[100:103], v[190:193], v[240:243], v[100:103]
	ds_read_b128 v[228:231], v167 offset:3072
	v_mfma_f32_16x16x32_bf16 v[68:71], v[194:197], v[240:243], v[68:71]
	v_mfma_f32_16x16x32_bf16 v[36:39], v[202:205], v[240:243], v[36:39]
	global_load_lds_dwordx4 v[142:143], off nt
	s_waitcnt lgkmcnt(6)
	v_mfma_f32_16x16x32_bf16 v[112:115], v[186:189], v[244:247], v[112:115]
	ds_read_b128 v[240:243], v163 offset:38912
	v_mfma_f32_16x16x32_bf16 v[96:99], v[190:193], v[244:247], v[96:99]
	v_mfma_f32_16x16x32_bf16 v[64:67], v[194:197], v[244:247], v[64:67]
	v_mfma_f32_16x16x32_bf16 v[32:35], v[202:205], v[244:247], v[32:35]
	v_add_u32_e32 v142, 0x19000, v169
	v_add_u32_e32 v143, 0x19400, v169
	v_add_u32_e32 v144, 0x19800, v169
	v_add_u32_e32 v145, 0x19c00, v169
	s_waitcnt lgkmcnt(6)
	v_mfma_f32_16x16x32_bf16 v[92:95], v[186:189], v[232:235], v[92:95]
	ds_read_b128 v[244:247], v163 offset:39936
	v_mfma_f32_16x16x32_bf16 v[60:63], v[190:193], v[232:235], v[60:63]
	v_mfma_f32_16x16x32_bf16 v[28:31], v[194:197], v[232:235], v[28:31]
	v_mfma_f32_16x16x32_bf16 v[12:15], v[202:205], v[232:235], v[12:15]
	s_waitcnt lgkmcnt(3)
	v_mfma_f32_16x16x32_bf16 v[84:87], v[186:189], v[236:239], v[84:87]
	ds_read_b128 v[232:235], v168 offset:16384
	v_mfma_f32_16x16x32_bf16 v[56:59], v[190:193], v[236:239], v[56:59]
	v_mfma_f32_16x16x32_bf16 v[24:27], v[194:197], v[236:239], v[24:27]
	v_mfma_f32_16x16x32_bf16 v[8:11], v[202:205], v[236:239], v[8:11]
	s_waitcnt lgkmcnt(2)
	v_mfma_f32_16x16x32_bf16 v[80:83], v[186:189], v[240:243], v[80:83]
	ds_read_b128 v[236:239], v168 offset:17408
	v_mfma_f32_16x16x32_bf16 v[52:55], v[190:193], v[240:243], v[52:55]
	v_mfma_f32_16x16x32_bf16 v[20:23], v[194:197], v[240:243], v[20:23]
	v_mfma_f32_16x16x32_bf16 v[4:7], v[202:205], v[240:243], v[4:7]
	s_waitcnt lgkmcnt(2)
	v_mfma_f32_16x16x32_bf16 v[72:75], v[186:189], v[244:247], v[72:75]
	ds_read_b128 v[240:243], v168 offset:18432
	v_mfma_f32_16x16x32_bf16 v[48:51], v[190:193], v[244:247], v[48:51]
	v_mfma_f32_16x16x32_bf16 v[16:19], v[194:197], v[244:247], v[16:19]
	v_mfma_f32_16x16x32_bf16 v[0:3], v[202:205], v[244:247], v[0:3]
	ds_read_b128 v[244:247], v168 offset:19456
	s_add_u32 s36, s36, 0x8000
	s_addc_u32 s37, s37, 0
	s_cmp_lg_u32 s36, 0xf8000
	s_cbranch_scc1 .LBB0_264
; #define BIG_SYNC(N)                                              \
;   asm volatile("s_waitcnt vmcnt(%0)" ::"n"(N) : "memory");       \
;   __builtin_amdgcn_s_barrier();                                  \
;   asm volatile("" ::: "memory");                                 \
;   __builtin_amdgcn_sched_barrier(0);
; template <int NK, bool BNT = false> ...
;     ...
;   auto kstep = [&](int T, int cur, int nxt, bool do_stage) {
;     const unsigned char* sa = smem + cur * BIG_STAGE;
;     bf16x8 af[4], bfr[4];
; #pragma unroll
;     for (int m = 0; m < 4; ++m) af[m] = *reinterpret_cast<const bf16x8*>(sa + aoff + m * 1024);
; #pragma unroll
;     for (int n = 0; n < 4; ++n) bfr[n] = *reinterpret_cast<const bf16x8*>(sa + boff + n * 1024);
;     __builtin_amdgcn_sched_barrier(0);
;     if (do_stage) stage(T + 3, nxt);
; #pragma unroll
;     for (int m = 0; m < 4; ++m)
; #pragma unroll
;       for (int n = 0; n < 4; ++n) acc[m][n] = __builtin_amdgcn_mfma_f32_16x16x32_bf16(af[m], bfr[n], acc[m][n], 0, 0, 0);
;     if (do_stage) {
; #pragma unroll
;       for (int q = 0; q < NG; ++q) {
;         __builtin_amdgcn_sched_group_barrier(0x008, 3, 0);
;         __builtin_amdgcn_sched_group_barrier(0x010, 1, 0);
;       }
;       __builtin_amdgcn_sched_group_barrier(0x008, 16 - 3 * NG, 0);
;     }
;     __builtin_amdgcn_sched_barrier(0);
; #pragma unroll
;     for (int n = 0; n < 4; ++n) bfr[n] = *reinterpret_cast<const bf16x8*>(sa + boff + (4 + n) * 1024);
; #pragma unroll
;     for (int m = 0; m < 4; ++m)
; #pragma unroll
;       for (int n = 0; n < 4; ++n)
;         acc[m][4 + n] = __builtin_amdgcn_mfma_f32_16x16x32_bf16(af[m], bfr[n], acc[m][4 + n], 0, 0, 0);
;     __builtin_amdgcn_sched_barrier(0);
;   };
;     ...
;   stage(0, 0);
;   stage(1, 1);
;   stage(2, 2);
;   for (int it = 0; it < NK / 4 - 1; ++it) {
;     const int t = it * 4;
;     BIG_SYNC(2 * NG); kstep(t, 0, 3, true);
;     BIG_SYNC(2 * NG); kstep(t + 1, 1, 0, true);
;     BIG_SYNC(2 * NG); kstep(t + 2, 2, 1, true);
;     BIG_SYNC(2 * NG); kstep(t + 3, 3, 2, true);
;   }
;   BIG_SYNC(2 * NG); kstep(NK - 4, 0, 3, true);
;   BIG_SYNC(2 * NG); kstep(NK - 3, 1, 0, false);
;   BIG_SYNC(NG);     kstep(NK - 2, 2, 0, false);
;   BIG_SYNC(0);      kstep(NK - 1, 3, 0, false);
	s_sext_i32_i8 s13, s14
	s_mov_b64 s[18:19], 0xfe000
	v_readfirstlane_b32 s14, v158
	v_lshl_add_u64 v[150:151], v[130:131], 0, s[18:19]
	v_lshl_add_u64 v[198:199], v[128:129], 0, s[18:19]
	s_mov_b32 m0, s14
	s_mov_b64 s[18:19], 0x1fe000
	v_readfirstlane_b32 s14, v159
	v_lshl_add_u64 v[130:131], v[130:131], 0, s[18:19]
	s_waitcnt lgkmcnt(3)
	v_mfma_f32_16x16x32_bf16 v[124:127], v[216:219], v[232:235], v[124:127]
	v_lshl_add_u64 v[128:129], v[128:129], 0, s[18:19]
	v_mfma_f32_16x16x32_bf16 v[108:111], v[220:223], v[232:235], v[108:111]
	v_mfma_f32_16x16x32_bf16 v[88:91], v[224:227], v[232:235], v[88:91]
	s_waitcnt vmcnt(4)
	s_barrier
	global_load_lds_dwordx4 v[150:151], off
	s_mov_b32 m0, s14
	v_readfirstlane_b32 s14, v160
	v_mfma_f32_16x16x32_bf16 v[44:47], v[228:231], v[232:235], v[44:47]
	s_waitcnt lgkmcnt(2)
	v_mfma_f32_16x16x32_bf16 v[120:123], v[216:219], v[236:239], v[120:123]
	ds_read_b128 v[232:235], v168 offset:20480
	v_mfma_f32_16x16x32_bf16 v[104:107], v[220:223], v[236:239], v[104:107]
	ds_read_b128 v[186:189], v167 offset:32768
	global_load_lds_dwordx4 v[130:131], off
	s_mov_b32 m0, s14
	v_readfirstlane_b32 s14, v161
	v_mfma_f32_16x16x32_bf16 v[76:79], v[224:227], v[236:239], v[76:79]
	ds_read_b128 v[190:193], v167 offset:33792
	v_mfma_f32_16x16x32_bf16 v[40:43], v[228:231], v[236:239], v[40:43]
	ds_read_b128 v[194:197], v167 offset:34816
	s_waitcnt lgkmcnt(5)
	v_mfma_f32_16x16x32_bf16 v[116:119], v[216:219], v[240:243], v[116:119]
	ds_read_b128 v[236:239], v168 offset:21504
	global_load_lds_dwordx4 v[198:199], off nt
	s_mov_b32 m0, s14
	v_mfma_f32_16x16x32_bf16 v[100:103], v[220:223], v[240:243], v[100:103]
	ds_read_b128 v[202:205], v167 offset:35840
	v_mfma_f32_16x16x32_bf16 v[68:71], v[224:227], v[240:243], v[68:71]
	v_mfma_f32_16x16x32_bf16 v[36:39], v[228:231], v[240:243], v[36:39]
	global_load_lds_dwordx4 v[128:129], off nt
	s_waitcnt lgkmcnt(6)
	v_mfma_f32_16x16x32_bf16 v[112:115], v[216:219], v[244:247], v[112:115]
	ds_read_b128 v[240:243], v168 offset:22528
	v_mfma_f32_16x16x32_bf16 v[96:99], v[220:223], v[244:247], v[96:99]
	v_mfma_f32_16x16x32_bf16 v[64:67], v[224:227], v[244:247], v[64:67]
	v_mfma_f32_16x16x32_bf16 v[32:35], v[228:231], v[244:247], v[32:35]
	s_waitcnt lgkmcnt(6)
	v_mfma_f32_16x16x32_bf16 v[92:95], v[216:219], v[232:235], v[92:95]
	ds_read_b128 v[244:247], v168 offset:23552
	v_mfma_f32_16x16x32_bf16 v[60:63], v[220:223], v[232:235], v[60:63]
	v_mfma_f32_16x16x32_bf16 v[28:31], v[224:227], v[232:235], v[28:31]
	v_mfma_f32_16x16x32_bf16 v[12:15], v[228:231], v[232:235], v[12:15]
	s_waitcnt lgkmcnt(3)
	v_mfma_f32_16x16x32_bf16 v[84:87], v[216:219], v[236:239], v[84:87]
	ds_read_b128 v[232:235], v168 offset:49152
	v_mfma_f32_16x16x32_bf16 v[56:59], v[220:223], v[236:239], v[56:59]
	v_mfma_f32_16x16x32_bf16 v[24:27], v[224:227], v[236:239], v[24:27]
	v_mfma_f32_16x16x32_bf16 v[8:11], v[228:231], v[236:239], v[8:11]
	s_waitcnt lgkmcnt(2)
	v_mfma_f32_16x16x32_bf16 v[80:83], v[216:219], v[240:243], v[80:83]
	ds_read_b128 v[236:239], v168 offset:50176
	v_mfma_f32_16x16x32_bf16 v[52:55], v[220:223], v[240:243], v[52:55]
	v_mfma_f32_16x16x32_bf16 v[20:23], v[224:227], v[240:243], v[20:23]
	v_mfma_f32_16x16x32_bf16 v[4:7], v[228:231], v[240:243], v[4:7]
	s_waitcnt lgkmcnt(2)
	v_mfma_f32_16x16x32_bf16 v[72:75], v[216:219], v[244:247], v[72:75]
	ds_read_b128 v[240:243], v168 offset:51200
	v_mfma_f32_16x16x32_bf16 v[48:51], v[220:223], v[244:247], v[48:51]
	v_mfma_f32_16x16x32_bf16 v[16:19], v[224:227], v[244:247], v[16:19]
	v_mfma_f32_16x16x32_bf16 v[0:3], v[228:231], v[244:247], v[0:3]
	ds_read_b128 v[244:247], v168 offset:52224
	s_waitcnt lgkmcnt(3)
	v_mfma_f32_16x16x32_bf16 v[124:127], v[186:189], v[232:235], v[124:127]
	v_mfma_f32_16x16x32_bf16 v[108:111], v[190:193], v[232:235], v[108:111]
	v_mfma_f32_16x16x32_bf16 v[88:91], v[194:197], v[232:235], v[88:91]
	v_mfma_f32_16x16x32_bf16 v[44:47], v[202:205], v[232:235], v[44:47]
	s_waitcnt vmcnt(4)
	s_barrier
	s_waitcnt lgkmcnt(2)
	v_mfma_f32_16x16x32_bf16 v[120:123], v[186:189], v[236:239], v[120:123]
	ds_read_b128 v[232:235], v168 offset:53248
	v_mfma_f32_16x16x32_bf16 v[104:107], v[190:193], v[236:239], v[104:107]
	v_mfma_f32_16x16x32_bf16 v[76:79], v[194:197], v[236:239], v[76:79]
	v_mfma_f32_16x16x32_bf16 v[40:43], v[202:205], v[236:239], v[40:43]
	s_waitcnt lgkmcnt(2)
	v_mfma_f32_16x16x32_bf16 v[116:119], v[186:189], v[240:243], v[116:119]
	ds_read_b128 v[236:239], v168 offset:54272
	v_mfma_f32_16x16x32_bf16 v[100:103], v[190:193], v[240:243], v[100:103]
	v_mfma_f32_16x16x32_bf16 v[68:71], v[194:197], v[240:243], v[68:71]
	v_mfma_f32_16x16x32_bf16 v[36:39], v[202:205], v[240:243], v[36:39]
	s_waitcnt lgkmcnt(2)
	v_mfma_f32_16x16x32_bf16 v[112:115], v[186:189], v[244:247], v[112:115]
	ds_read_b128 v[240:243], v168 offset:55296
	v_mfma_f32_16x16x32_bf16 v[96:99], v[190:193], v[244:247], v[96:99]
	v_mfma_f32_16x16x32_bf16 v[64:67], v[194:197], v[244:247], v[64:67]
	v_mfma_f32_16x16x32_bf16 v[32:35], v[202:205], v[244:247], v[32:35]
	s_waitcnt lgkmcnt(2)
	v_mfma_f32_16x16x32_bf16 v[92:95], v[186:189], v[232:235], v[92:95]
	ds_read_b128 v[244:247], v168 offset:56320
	v_mfma_f32_16x16x32_bf16 v[60:63], v[190:193], v[232:235], v[60:63]
	v_mfma_f32_16x16x32_bf16 v[28:31], v[194:197], v[232:235], v[28:31]
	v_mfma_f32_16x16x32_bf16 v[12:15], v[202:205], v[232:235], v[12:15]
	s_waitcnt lgkmcnt(2)
	v_mfma_f32_16x16x32_bf16 v[84:87], v[186:189], v[236:239], v[84:87]
	v_mfma_f32_16x16x32_bf16 v[56:59], v[190:193], v[236:239], v[56:59]
	v_mfma_f32_16x16x32_bf16 v[24:27], v[194:197], v[236:239], v[24:27]
	v_mfma_f32_16x16x32_bf16 v[8:11], v[202:205], v[236:239], v[8:11]
	s_waitcnt lgkmcnt(1)
	v_mfma_f32_16x16x32_bf16 v[80:83], v[186:189], v[240:243], v[80:83]
	v_mfma_f32_16x16x32_bf16 v[52:55], v[190:193], v[240:243], v[52:55]
	v_mfma_f32_16x16x32_bf16 v[20:23], v[194:197], v[240:243], v[20:23]
	v_mfma_f32_16x16x32_bf16 v[4:7], v[202:205], v[240:243], v[4:7]
	s_waitcnt lgkmcnt(0)
	v_mfma_f32_16x16x32_bf16 v[72:75], v[186:189], v[244:247], v[72:75]
	v_mfma_f32_16x16x32_bf16 v[48:51], v[190:193], v[244:247], v[48:51]
	v_mfma_f32_16x16x32_bf16 v[16:19], v[194:197], v[244:247], v[16:19]
	v_mfma_f32_16x16x32_bf16 v[0:3], v[202:205], v[244:247], v[0:3]
	v_mov_b32_e32 v186, 0xf149f2ca
	v_mov_b32_e32 v187, 0x3c0881c4
	v_mov_b32_e32 v188, 0xbab64f3b
	v_mov_b32_e32 v189, 0x24800
	v_mov_b32_e32 v190, 1
	v_mov_b32_e32 v191, 0x24804
	v_mov_b32_e32 v192, 0xfcf
	v_mov_b32_e32 v193, 0x7cf
	v_mov_b32_e32 v194, 0xfdf
	v_mov_b32_e32 v195, 0x7df
	v_mov_b32_e32 v196, 0xfef
	v_mov_b32_e32 v197, 0x7ef
	v_mov_b32_e32 v198, 0xfff
	v_mov_b32_e32 v199, 0x7ff
	v_mov_b32_e32 v200, 0x20000
	v_mov_b32_e32 v201, 0xf8f
	v_mov_b32_e32 v202, 0x78f
	v_mov_b32_e32 v203, 0xf9f
	v_mov_b32_e32 v204, 0x79f
	v_mov_b32_e32 v205, 0xfaf
	s_waitcnt vmcnt(4)
	s_barrier
; #define BIG_SYNC(N)                                              \
;   asm volatile("s_waitcnt vmcnt(%0)" ::"n"(N) : "memory");       \
;   __builtin_amdgcn_s_barrier();                                  \
;   asm volatile("" ::: "memory");                                 \
;   __builtin_amdgcn_sched_barrier(0);
; template <int NK, bool BNT = false> ...
;     ...
;   auto kstep = [&](int T, int cur, int nxt, bool do_stage) {
;     const unsigned char* sa = smem + cur * BIG_STAGE;
;     bf16x8 af[4], bfr[4];
; #pragma unroll
;     for (int m = 0; m < 4; ++m) af[m] = *reinterpret_cast<const bf16x8*>(sa + aoff + m * 1024);
; #pragma unroll
;     for (int n = 0; n < 4; ++n) bfr[n] = *reinterpret_cast<const bf16x8*>(sa + boff + n * 1024);
;     __builtin_amdgcn_sched_barrier(0);
;     if (do_stage) stage(T + 3, nxt);
; #pragma unroll
;     for (int m = 0; m < 4; ++m)
; #pragma unroll
;       for (int n = 0; n < 4; ++n) acc[m][n] = __builtin_amdgcn_mfma_f32_16x16x32_bf16(af[m], bfr[n], acc[m][n], 0, 0, 0);
;     if (do_stage) {
; #pragma unroll
;       for (int q = 0; q < NG; ++q) {
;         __builtin_amdgcn_sched_group_barrier(0x008, 3, 0);
;         __builtin_amdgcn_sched_group_barrier(0x010, 1, 0);
;       }
;       __builtin_amdgcn_sched_group_barrier(0x008, 16 - 3 * NG, 0);
;     }
;     __builtin_amdgcn_sched_barrier(0);
; #pragma unroll
;     for (int n = 0; n < 4; ++n) bfr[n] = *reinterpret_cast<const bf16x8*>(sa + boff + (4 + n) * 1024);
; #pragma unroll
;     for (int m = 0; m < 4; ++m)
; #pragma unroll
;       for (int n = 0; n < 4; ++n)
;         acc[m][4 + n] = __builtin_amdgcn_mfma_f32_16x16x32_bf16(af[m], bfr[n], acc[m][4 + n], 0, 0, 0);
;     __builtin_amdgcn_sched_barrier(0);
;   };
;     ...
;   stage(0, 0);
;   stage(1, 1);
;   stage(2, 2);
;   for (int it = 0; it < NK / 4 - 1; ++it) {
;     const int t = it * 4;
;     BIG_SYNC(2 * NG); kstep(t, 0, 3, true);
;     BIG_SYNC(2 * NG); kstep(t + 1, 1, 0, true);
;     BIG_SYNC(2 * NG); kstep(t + 2, 2, 1, true);
;     BIG_SYNC(2 * NG); kstep(t + 3, 3, 2, true);
;   }
;   BIG_SYNC(2 * NG); kstep(NK - 4, 0, 3, true);
;   BIG_SYNC(2 * NG); kstep(NK - 3, 1, 0, false);
;   BIG_SYNC(NG);     kstep(NK - 2, 2, 0, false);
;   BIG_SYNC(0);      kstep(NK - 1, 3, 0, false);
	ds_read_b128 v[128:131], v162
	ds_read_b128 v[138:141], v162 offset:1024
	ds_read_b128 v[146:149], v162 offset:2048
	ds_read_b128 v[154:157], v162 offset:3072
	ds_read_b128 v[158:161], v163
	ds_read_b128 v[216:219], v164
	ds_read_b128 v[162:165], v165
	ds_read_b128 v[220:223], v172
	s_waitcnt lgkmcnt(0)
	v_mfma_f32_16x16x32_bf16 v[124:127], v[128:131], v[158:161], v[124:127]
	v_mfma_f32_16x16x32_bf16 v[116:119], v[128:131], v[162:165], v[116:119]
	v_mfma_f32_16x16x32_bf16 v[112:115], v[128:131], v[220:223], v[112:115]
	v_mfma_f32_16x16x32_bf16 v[104:107], v[138:141], v[216:219], v[104:107]
	v_mfma_f32_16x16x32_bf16 v[100:103], v[138:141], v[162:165], v[100:103]
	v_mfma_f32_16x16x32_bf16 v[96:99], v[138:141], v[220:223], v[96:99]
	v_mfma_f32_16x16x32_bf16 v[68:71], v[146:149], v[162:165], v[68:71]
	v_mfma_f32_16x16x32_bf16 v[64:67], v[146:149], v[220:223], v[64:67]
	v_mfma_f32_16x16x32_bf16 v[44:47], v[154:157], v[158:161], v[44:47]
	v_mfma_f32_16x16x32_bf16 v[40:43], v[154:157], v[216:219], v[40:43]
	v_mfma_f32_16x16x32_bf16 v[36:39], v[154:157], v[162:165], v[36:39]
	v_mfma_f32_16x16x32_bf16 v[32:35], v[154:157], v[220:223], v[32:35]
	v_mfma_f32_16x16x32_bf16 v[120:123], v[128:131], v[216:219], v[120:123]
	v_mfma_f32_16x16x32_bf16 v[224:227], v[138:141], v[158:161], v[108:111]
	v_mfma_f32_16x16x32_bf16 v[228:231], v[146:149], v[158:161], v[88:91]
	v_mfma_f32_16x16x32_bf16 v[232:235], v[146:149], v[216:219], v[76:79]
	s_nop 2
	ds_read_b128 v[76:79], v173
	ds_read_b128 v[88:91], v174
	s_waitcnt lgkmcnt(0)
	v_mfma_f32_16x16x32_bf16 v[158:161], v[128:131], v[76:79], v[92:95]
	s_nop 2
	ds_read_b128 v[92:95], v178
	v_mfma_f32_16x16x32_bf16 v[162:165], v[128:131], v[88:91], v[84:87]
	s_nop 2
	ds_read_b128 v[84:87], v175
	s_waitcnt lgkmcnt(0)
	v_mfma_f32_16x16x32_bf16 v[172:175], v[128:131], v[84:87], v[80:83]
	v_mfma_f32_16x16x32_bf16 v[128:131], v[128:131], v[92:95], v[72:75]
	v_mfma_f32_16x16x32_bf16 v[216:219], v[138:141], v[76:79], v[60:63]
	v_mfma_f32_16x16x32_bf16 v[220:223], v[138:141], v[88:91], v[56:59]
	v_mfma_f32_16x16x32_bf16 v[52:55], v[138:141], v[84:87], v[52:55]
	v_mfma_f32_16x16x32_bf16 v[48:51], v[138:141], v[92:95], v[48:51]
	v_mfma_f32_16x16x32_bf16 v[138:141], v[146:149], v[76:79], v[28:31]
	v_mfma_f32_16x16x32_bf16 v[236:239], v[146:149], v[88:91], v[24:27]
	v_mfma_f32_16x16x32_bf16 v[20:23], v[146:149], v[84:87], v[20:23]
	v_mfma_f32_16x16x32_bf16 v[16:19], v[146:149], v[92:95], v[16:19]
	v_mfma_f32_16x16x32_bf16 v[146:149], v[154:157], v[76:79], v[12:15]
	v_mfma_f32_16x16x32_bf16 v[0:3], v[154:157], v[92:95], v[0:3]
	v_mfma_f32_16x16x32_bf16 v[240:243], v[154:157], v[88:91], v[8:11]
	v_mfma_f32_16x16x32_bf16 v[244:247], v[154:157], v[84:87], v[4:7]
	s_waitcnt vmcnt(0)
	s_barrier
	s_nop 1
	ds_read_b128 v[4:7], v176
	ds_read_b128 v[8:11], v176 offset:1024
	ds_read_b128 v[154:157], v176 offset:2048
	ds_read_b128 v[12:15], v179
	ds_read_b128 v[24:27], v180
	ds_read_b128 v[28:31], v181
	ds_read_b128 v[56:59], v182
	ds_read_b128 v[248:251], v176 offset:3072
	s_waitcnt lgkmcnt(0)
	v_mfma_f32_16x16x32_bf16 v[108:111], v[4:7], v[24:27], v[120:123]
	v_mfma_f32_16x16x32_bf16 v[92:95], v[4:7], v[28:31], v[116:119]
	v_mfma_f32_16x16x32_bf16 v[76:79], v[4:7], v[56:59], v[112:115]
	v_mfma_f32_16x16x32_bf16 v[104:107], v[8:11], v[24:27], v[104:107]
	v_mfma_f32_16x16x32_bf16 v[88:91], v[8:11], v[28:31], v[100:103]
	v_mfma_f32_16x16x32_bf16 v[72:75], v[8:11], v[56:59], v[96:99]
	v_mfma_f32_16x16x32_bf16 v[100:103], v[154:157], v[24:27], v[232:235]
	v_mfma_f32_16x16x32_bf16 v[84:87], v[154:157], v[28:31], v[68:71]
	v_mfma_f32_16x16x32_bf16 v[68:71], v[154:157], v[56:59], v[64:67]
	v_mfma_f32_16x16x32_bf16 v[116:119], v[248:251], v[12:15], v[44:47]
	v_mfma_f32_16x16x32_bf16 v[96:99], v[248:251], v[24:27], v[40:43]
	v_mfma_f32_16x16x32_bf16 v[80:83], v[248:251], v[28:31], v[36:39]
	v_mfma_f32_16x16x32_bf16 v[64:67], v[248:251], v[56:59], v[32:35]
	v_mfma_f32_16x16x32_bf16 v[178:181], v[4:7], v[12:15], v[124:127]
	v_mfma_f32_16x16x32_bf16 v[224:227], v[8:11], v[12:15], v[224:227]
	v_mfma_f32_16x16x32_bf16 v[120:123], v[154:157], v[12:15], v[228:231]
	ds_read_b128 v[32:35], v142
	ds_read_b128 v[112:115], v143
	ds_read_b128 v[124:127], v144
	ds_read_b128 v[142:145], v145
	s_waitcnt lgkmcnt(0)
; template <int NK, bool BNT = false> ...
;     ...
;   auto kstep = [&](int T, int cur, int nxt, bool do_stage) {
;     const unsigned char* sa = smem + cur * BIG_STAGE;
;     bf16x8 af[4], bfr[4];
; #pragma unroll
;     for (int m = 0; m < 4; ++m) af[m] = *reinterpret_cast<const bf16x8*>(sa + aoff + m * 1024);
; #pragma unroll
;     for (int n = 0; n < 4; ++n) bfr[n] = *reinterpret_cast<const bf16x8*>(sa + boff + n * 1024);
;     __builtin_amdgcn_sched_barrier(0);
;     if (do_stage) stage(T + 3, nxt);
; #pragma unroll
;     for (int m = 0; m < 4; ++m)
; #pragma unroll
;       for (int n = 0; n < 4; ++n) acc[m][n] = __builtin_amdgcn_mfma_f32_16x16x32_bf16(af[m], bfr[n], acc[m][n], 0, 0, 0);
;     if (do_stage) {
; #pragma unroll
;       for (int q = 0; q < NG; ++q) {
;         __builtin_amdgcn_sched_group_barrier(0x008, 3, 0);
;         __builtin_amdgcn_sched_group_barrier(0x010, 1, 0);
;       }
;       __builtin_amdgcn_sched_group_barrier(0x008, 16 - 3 * NG, 0);
;     }
;     __builtin_amdgcn_sched_barrier(0);
; #pragma unroll
;     for (int n = 0; n < 4; ++n) bfr[n] = *reinterpret_cast<const bf16x8*>(sa + boff + (4 + n) * 1024);
; #pragma unroll
;     for (int m = 0; m < 4; ++m)
; #pragma unroll
;       for (int n = 0; n < 4; ++n)
;         acc[m][4 + n] = __builtin_amdgcn_mfma_f32_16x16x32_bf16(af[m], bfr[n], acc[m][4 + n], 0, 0, 0);
;     __builtin_amdgcn_sched_barrier(0);
;   };
;     ...
;   stage(0, 0);
;   stage(1, 1);
;   stage(2, 2);
;   for (int it = 0; it < NK / 4 - 1; ++it) {
;     const int t = it * 4;
;     BIG_SYNC(2 * NG); kstep(t, 0, 3, true);
;     BIG_SYNC(2 * NG); kstep(t + 1, 1, 0, true);
;     BIG_SYNC(2 * NG); kstep(t + 2, 2, 1, true);
;     BIG_SYNC(2 * NG); kstep(t + 3, 3, 2, true);
;   }
;   BIG_SYNC(2 * NG); kstep(NK - 4, 0, 3, true);
;   BIG_SYNC(2 * NG); kstep(NK - 3, 1, 0, false);
;   BIG_SYNC(NG);     kstep(NK - 2, 2, 0, false);
;   BIG_SYNC(0);      kstep(NK - 1, 3, 0, false);
; template <int MODE, int NSUB>
; __device__ __forceinline__ void epilogue(const Params& p, int layer, f32x4 (&acc)[4][NSUB], int tm, int tn, int g,
;                                          const float* s_rstd, const int tid_in) {
;     ...
;   } else if constexpr (MODE == EPI_RES) {
;     const int fb = tm * 128 + wr * 64 + fq * 4;
;     const int tb = tn * (NSUB * 32) + wc * (NSUB * 16) + fr;
;     const int fw = tm * 128 + wr * 64 + widen_off(fq);
	v_mfma_f32_16x16x32_bf16 v[60:63], v[4:7], v[32:35], v[158:161]
	v_mfma_f32_16x16x32_bf16 v[44:47], v[4:7], v[112:115], v[162:165]
	v_mfma_f32_16x16x32_bf16 v[28:31], v[4:7], v[124:127], v[172:175]
	v_mfma_f32_16x16x32_bf16 v[12:15], v[4:7], v[142:145], v[128:131]
	v_mfma_f32_16x16x32_bf16 v[56:59], v[8:11], v[32:35], v[216:219]
	v_mfma_f32_16x16x32_bf16 v[40:43], v[8:11], v[112:115], v[220:223]
	v_mfma_f32_16x16x32_bf16 v[24:27], v[8:11], v[124:127], v[52:55]
	v_mfma_f32_16x16x32_bf16 v[8:11], v[8:11], v[142:145], v[48:51]
	v_mfma_f32_16x16x32_bf16 v[52:55], v[154:157], v[32:35], v[138:141]
	v_mfma_f32_16x16x32_bf16 v[36:39], v[154:157], v[112:115], v[236:239]
	v_mfma_f32_16x16x32_bf16 v[20:23], v[154:157], v[124:127], v[20:23]
	v_mfma_f32_16x16x32_bf16 v[4:7], v[154:157], v[142:145], v[16:19]
	v_mfma_f32_16x16x32_bf16 v[48:51], v[248:251], v[32:35], v[146:149]
	v_mfma_f32_16x16x32_bf16 v[32:35], v[248:251], v[112:115], v[240:243]
	v_mfma_f32_16x16x32_bf16 v[16:19], v[248:251], v[124:127], v[244:247]
	v_mfma_f32_16x16x32_bf16 v[0:3], v[248:251], v[142:145], v[0:3]
	v_lshl_add_u32 v124, s13, 1, v170
	v_mov_b32_e32 v112, v215
	v_lshlrev_b32_e32 v113, 7, v124
	v_ashrrev_i32_e32 v138, 7, v112
	s_mul_i32 s13, s15, 0x140
	v_lshl_add_u32 v114, v138, 6, v113
	v_lshlrev_b32_e32 v113, 1, v112
	s_add_i32 s12, s12, s13
	v_and_b32_e32 v113, 0x80, v113
	v_lshl_or_b32 v127, s12, 8, v113
	v_lshrrev_b32_e32 v113, 2, v112
	v_and_b32_e32 v125, 15, v112
	v_and_b32_e32 v113, 8, v113
	v_ashrrev_i32_e32 v115, 2, v127
	v_readlane_b32 s80, v253, 25
	v_ashrrev_i32_e32 v114, 5, v114
	v_bfe_u32 v126, v112, 4, 2
	v_and_or_b32 v112, v112, 16, v113
	v_lshlrev_b32_e32 v156, 6, v125
	v_mov_b32_e32 v157, v153
	v_readlane_b32 s84, v253, 29
	v_readlane_b32 s85, v253, 30
	v_add_u32_e32 v114, v114, v115
	v_lshlrev_b32_e32 v152, 1, v112
	v_lshl_add_u64 v[144:145], s[84:85], 0, v[156:157]
	v_ashrrev_i32_e32 v115, 31, v114
	v_lshl_add_u64 v[112:113], v[144:145], 0, v[152:153]
	v_lshlrev_b64 v[146:147], 13, v[114:115]
	v_or_b32_e32 v114, 1, v114
	v_lshl_add_u64 v[150:151], v[112:113], 0, v[146:147]
	v_ashrrev_i32_e32 v115, 31, v114
	global_load_dwordx4 v[158:161], v[150:151], off
	v_lshlrev_b64 v[148:149], 13, v[114:115]
	v_lshl_add_u64 v[154:155], v[112:113], 0, v[148:149]
	global_load_dwordx4 v[128:131], v[154:155], off
	v_and_b32_e32 v113, 64, v185
	v_xor_b32_e32 v112, 16, v185
	v_add_u32_e32 v113, 64, v113
	v_cmp_lt_i32_e32 vcc, v112, v113
	v_or_b32_e32 v142, v127, v125
	v_lshlrev_b32_e32 v140, 1, v124
	v_cndmask_b32_e32 v112, v185, v112, vcc
	v_lshlrev_b32_e32 v172, 2, v112
	v_xor_b32_e32 v112, 32, v185
	v_cmp_lt_i32_e32 vcc, v112, v113
	v_ashrrev_i32_e32 v141, 31, v140
	v_ashrrev_i32_e32 v139, 31, v138
	v_cndmask_b32_e32 v112, v185, v112, vcc
	v_lshlrev_b32_e32 v173, 2, v112
	v_cmp_eq_u32_e32 vcc, 0, v126
	global_load_dwordx4 v[124:127], v[150:151], off offset:1024
	global_load_dwordx4 v[112:115], v[154:155], off offset:1024
	v_readlane_b32 s81, v253, 26
	v_readlane_b32 s82, v253, 27
	v_readlane_b32 s83, v253, 28
	v_readlane_b32 s86, v253, 31
	v_readlane_b32 s87, v253, 32
	v_readlane_b32 s88, v253, 33
	v_readlane_b32 s89, v253, 34
	v_readlane_b32 s90, v253, 35
	v_readlane_b32 s91, v253, 36
	v_readlane_b32 s92, v253, 37
	v_readlane_b32 s93, v253, 38
	v_readlane_b32 s94, v253, 39
	v_readlane_b32 s95, v253, 40
	s_waitcnt vmcnt(0)
	v_mov_b32_e32 v143, v160
	s_nop 1
	v_permlane16_swap_b32_e32 v158, v143
	v_mov_b32_e32 v164, v161
	s_nop 1
	v_permlane16_swap_b32_e32 v159, v164
	v_mov_b32_e32 v176, v130
	v_mov_b32_e32 v182, v131
	v_and_b32_e32 v131, 0xffff0000, v158
	v_lshlrev_b32_e32 v130, 16, v158
	v_pk_add_f32 v[130:131], v[178:179], v[130:131]
	v_and_b32_e32 v161, 0xffff0000, v159
	v_lshlrev_b32_e32 v160, 16, v159
	v_pk_add_f32 v[162:163], v[180:181], v[160:161]
	v_pk_mul_f32 v[160:161], v[130:131], v[130:131]
	v_cvt_pk_bf16_f32 v178, v130, v131
	v_and_b32_e32 v131, 0xffff0000, v143
	v_lshlrev_b32_e32 v130, 16, v143
	v_pk_mul_f32 v[158:159], v[162:163], v[162:163]
	v_cvt_pk_bf16_f32 v179, v162, v163
	v_pk_add_f32 v[130:131], v[224:225], v[130:131]
	v_and_b32_e32 v163, 0xffff0000, v164
	v_lshlrev_b32_e32 v162, 16, v164
	v_pk_add_f32 v[174:175], v[226:227], v[162:163]
	v_pk_mul_f32 v[164:165], v[130:131], v[130:131]
	v_cvt_pk_bf16_f32 v180, v130, v131
	v_lshl_add_u64 v[130:131], s[84:85], 0, v[146:147]
	v_pk_mul_f32 v[162:163], v[174:175], v[174:175]
	v_cvt_pk_bf16_f32 v181, v174, v175
	v_lshl_add_u64 v[174:175], v[130:131], 0, v[156:157]
	v_permlane16_swap_b32_e32 v128, v176
	v_permlane16_swap_b32_e32 v178, v180
	v_permlane16_swap_b32_e32 v179, v181
	v_lshl_add_u64 v[174:175], v[174:175], 0, v[152:153]
	v_permlane16_swap_b32_e32 v129, v182
	global_store_dwordx4 v[174:175], v[178:181], off
	v_and_b32_e32 v175, 0xffff0000, v128
	v_lshlrev_b32_e32 v174, 16, v128
	v_pk_add_f32 v[120:121], v[120:121], v[174:175]
	v_and_b32_e32 v175, 0xffff0000, v129
	v_lshlrev_b32_e32 v174, 16, v129
	v_pk_add_f32 v[122:123], v[122:123], v[174:175]
	v_pk_mul_f32 v[128:129], v[120:121], v[120:121]
	v_pk_mul_f32 v[174:175], v[122:123], v[122:123]
	v_cvt_pk_bf16_f32 v120, v120, v121
	v_cvt_pk_bf16_f32 v121, v122, v123
	v_and_b32_e32 v123, 0xffff0000, v176
	v_lshlrev_b32_e32 v122, 16, v176
	v_pk_add_f32 v[116:117], v[116:117], v[122:123]
	v_and_b32_e32 v123, 0xffff0000, v182
	v_lshlrev_b32_e32 v122, 16, v182
	v_add_f32_e32 v143, v164, v165
	v_add_f32_e32 v160, v160, v161
	v_pk_add_f32 v[118:119], v[118:119], v[122:123]
	v_pk_mul_f32 v[122:123], v[116:117], v[116:117]
	v_add_f32_e32 v143, v162, v143
	v_add_f32_e32 v158, v158, v160
	v_add_f32_e32 v128, v128, v129
	v_pk_mul_f32 v[178:179], v[118:119], v[118:119]
	v_add_f32_e32 v143, v163, v143
	v_add_f32_e32 v158, v159, v158
	v_add_f32_e32 v128, v174, v128
	v_add_f32_e32 v122, v122, v123
	v_add_f32_e32 v143, v158, v143
	v_add_f32_e32 v128, v175, v128
	v_add_f32_e32 v122, v178, v122
	v_add_f32_e32 v128, v143, v128
	v_add_f32_e32 v122, v179, v122
	v_add_f32_e32 v143, v122, v128
	v_lshl_add_u64 v[128:129], s[84:85], 0, v[148:149]
	v_cvt_pk_bf16_f32 v122, v116, v117
	v_cvt_pk_bf16_f32 v123, v118, v119
	v_lshl_add_u64 v[116:117], v[128:129], 0, v[156:157]
	v_permlane16_swap_b32_e32 v120, v122
	v_permlane16_swap_b32_e32 v121, v123
	v_lshl_add_u64 v[116:117], v[116:117], 0, v[152:153]
	global_store_dwordx4 v[116:117], v[120:123], off
	ds_bpermute_b32 v116, v172, v143
	s_waitcnt lgkmcnt(0)
	v_add_f32_e32 v116, v143, v116
	ds_bpermute_b32 v117, v173, v116
	s_and_saveexec_b64 s[12:13], vcc
	s_cbranch_execz .LBB0_267
; template <int MODE, int NSUB>
; __device__ __forceinline__ void epilogue(const Params& p, int layer, f32x4 (&acc)[4][NSUB], int tm, int tn, int g,
;                                          const float* s_rstd, const int tid_in) {
;     ...
;       ss = red_fq(ss);
;       if (fq == 0) p.part[(long)t * 16 + tm * 2 + wr] = ss;
	v_ashrrev_i32_e32 v143, 31, v142
	v_readlane_b32 s64, v253, 25
	v_lshlrev_b64 v[118:119], 6, v[142:143]
	v_readlane_b32 s70, v253, 31
	v_readlane_b32 s71, v253, 32
	s_waitcnt lgkmcnt(0)
	v_add_f32_e32 v116, v116, v117
	v_readlane_b32 s65, v253, 26
	v_lshl_add_u64 v[118:119], s[70:71], 0, v[118:119]
	v_lshl_add_u64 v[118:119], v[140:141], 2, v[118:119]
	v_lshl_add_u64 v[118:119], v[138:139], 2, v[118:119]
	v_readlane_b32 s66, v253, 27
	v_readlane_b32 s67, v253, 28
	v_readlane_b32 s68, v253, 29
	v_readlane_b32 s69, v253, 30
	v_readlane_b32 s72, v253, 33
	v_readlane_b32 s73, v253, 34
	v_readlane_b32 s74, v253, 35
	v_readlane_b32 s75, v253, 36
	v_readlane_b32 s76, v253, 37
	v_readlane_b32 s77, v253, 38
	v_readlane_b32 s78, v253, 39
	v_readlane_b32 s79, v253, 40
	global_store_dword v[118:119], v116, off

; #define BIG_SYNC(N)                                              \
;   asm volatile("s_waitcnt vmcnt(%0)" ::"n"(N) : "memory");       \
;   __builtin_amdgcn_s_barrier();                                  \
;   asm volatile("" ::: "memory");                                 \
;   __builtin_amdgcn_sched_barrier(0);
; template <int NK, bool BNT = false> ...
;     ...
;   auto kstep = [&](int T, int cur, int nxt, bool do_stage) {
;     const unsigned char* sa = smem + cur * BIG_STAGE;
;     bf16x8 af[4], bfr[4];
; #pragma unroll
;     for (int m = 0; m < 4; ++m) af[m] = *reinterpret_cast<const bf16x8*>(sa + aoff + m * 1024);
; #pragma unroll
;     for (int n = 0; n < 4; ++n) bfr[n] = *reinterpret_cast<const bf16x8*>(sa + boff + n * 1024);
;     __builtin_amdgcn_sched_barrier(0);
;     if (do_stage) stage(T + 3, nxt);
; #pragma unroll
;     for (int m = 0; m < 4; ++m)
; #pragma unroll
;       for (int n = 0; n < 4; ++n) acc[m][n] = __builtin_amdgcn_mfma_f32_16x16x32_bf16(af[m], bfr[n], acc[m][n], 0, 0, 0);
;     if (do_stage) {
; #pragma unroll
;       for (int q = 0; q < NG; ++q) {
;         __builtin_amdgcn_sched_group_barrier(0x008, 3, 0);
;         __builtin_amdgcn_sched_group_barrier(0x010, 1, 0);
;       }
;       __builtin_amdgcn_sched_group_barrier(0x008, 16 - 3 * NG, 0);
;     }
;     __builtin_amdgcn_sched_barrier(0);
; #pragma unroll
;     for (int n = 0; n < 4; ++n) bfr[n] = *reinterpret_cast<const bf16x8*>(sa + boff + (4 + n) * 1024);
; #pragma unroll
;     for (int m = 0; m < 4; ++m)
; #pragma unroll
;       for (int n = 0; n < 4; ++n)
;         acc[m][4 + n] = __builtin_amdgcn_mfma_f32_16x16x32_bf16(af[m], bfr[n], acc[m][4 + n], 0, 0, 0);
;     __builtin_amdgcn_sched_barrier(0);
;   };
;     ...
;   stage(0, 0);
;   stage(1, 1);
;   stage(2, 2);
;   for (int it = 0; it < NK / 4 - 1; ++it) {
;     const int t = it * 4;
;     BIG_SYNC(2 * NG); kstep(t, 0, 3, true);
;     BIG_SYNC(2 * NG); kstep(t + 1, 1, 0, true);
;     BIG_SYNC(2 * NG); kstep(t + 2, 2, 1, true);
;     BIG_SYNC(2 * NG); kstep(t + 3, 3, 2, true);
;   }
.LBB0_290:
	v_add_u32_e32 v163, 0x18000, v146
	v_lshl_add_u64 v[144:145], v[138:139], 0, s[12:13]
	v_readfirstlane_b32 s11, v163
	v_lshl_add_u64 v[164:165], v[144:145], 0, s[60:61]
	s_mov_b32 m0, s11
	s_waitcnt lgkmcnt(3)
	v_mfma_f32_16x16x32_bf16 v[124:127], v[216:219], v[232:235], v[124:127]
	v_lshl_add_u64 v[142:143], v[140:141], 0, s[12:13]
	v_lshl_add_u64 v[168:169], v[144:145], 0, s[80:81]
	v_lshl_add_u64 v[166:167], v[142:143], 0, s[60:61]
	v_mfma_f32_16x16x32_bf16 v[108:111], v[220:223], v[232:235], v[108:111]
	v_mfma_f32_16x16x32_bf16 v[88:91], v[224:227], v[232:235], v[88:91]
	s_waitcnt vmcnt(4)
	s_barrier
	global_load_lds_dwordx4 v[164:165], off
	v_add_u32_e32 v164, 0x1a000, v146
	v_add_u32_e32 v165, 0x1c000, v146
	v_readfirstlane_b32 s11, v164
	s_mov_b32 m0, s11
	v_readfirstlane_b32 s11, v165
	v_mfma_f32_16x16x32_bf16 v[44:47], v[228:231], v[232:235], v[44:47]
	s_waitcnt lgkmcnt(2)
	v_mfma_f32_16x16x32_bf16 v[120:123], v[216:219], v[236:239], v[120:123]
	ds_read_b128 v[232:235], v148 offset:20480
	v_mfma_f32_16x16x32_bf16 v[104:107], v[220:223], v[236:239], v[104:107]
	ds_read_b128 v[186:189], v147 offset:32768
	global_load_lds_dwordx4 v[168:169], off
	s_mov_b32 m0, s11
	v_mfma_f32_16x16x32_bf16 v[76:79], v[224:227], v[236:239], v[76:79]
	ds_read_b128 v[190:193], v147 offset:33792
	v_lshl_add_u64 v[168:169], v[142:143], 0, s[80:81]
	v_mfma_f32_16x16x32_bf16 v[40:43], v[228:231], v[236:239], v[40:43]
	ds_read_b128 v[194:197], v147 offset:34816
	s_waitcnt lgkmcnt(5)
	v_mfma_f32_16x16x32_bf16 v[116:119], v[216:219], v[240:243], v[116:119]
	ds_read_b128 v[236:239], v148 offset:21504
	global_load_lds_dwordx4 v[166:167], off
	v_add_u32_e32 v166, 0x1e000, v146
	v_mfma_f32_16x16x32_bf16 v[100:103], v[220:223], v[240:243], v[100:103]
	ds_read_b128 v[202:205], v147 offset:35840
	v_readfirstlane_b32 s11, v166
	s_mov_b32 m0, s11
	v_mfma_f32_16x16x32_bf16 v[68:71], v[224:227], v[240:243], v[68:71]
	v_mfma_f32_16x16x32_bf16 v[36:39], v[228:231], v[240:243], v[36:39]
	global_load_lds_dwordx4 v[168:169], off
	s_waitcnt lgkmcnt(6)
	v_mfma_f32_16x16x32_bf16 v[112:115], v[216:219], v[244:247], v[112:115]
	ds_read_b128 v[240:243], v148 offset:22528
	v_mfma_f32_16x16x32_bf16 v[96:99], v[220:223], v[244:247], v[96:99]
	v_mfma_f32_16x16x32_bf16 v[64:67], v[224:227], v[244:247], v[64:67]
	v_mfma_f32_16x16x32_bf16 v[32:35], v[228:231], v[244:247], v[32:35]
	s_waitcnt lgkmcnt(6)
	v_mfma_f32_16x16x32_bf16 v[92:95], v[216:219], v[232:235], v[92:95]
	ds_read_b128 v[244:247], v148 offset:23552
	v_mfma_f32_16x16x32_bf16 v[60:63], v[220:223], v[232:235], v[60:63]
	v_mfma_f32_16x16x32_bf16 v[28:31], v[224:227], v[232:235], v[28:31]
	v_mfma_f32_16x16x32_bf16 v[12:15], v[228:231], v[232:235], v[12:15]
	s_waitcnt lgkmcnt(3)
	v_mfma_f32_16x16x32_bf16 v[84:87], v[216:219], v[236:239], v[84:87]
	ds_read_b128 v[232:235], v148 offset:49152
	v_mfma_f32_16x16x32_bf16 v[56:59], v[220:223], v[236:239], v[56:59]
	v_mfma_f32_16x16x32_bf16 v[24:27], v[224:227], v[236:239], v[24:27]
	v_mfma_f32_16x16x32_bf16 v[8:11], v[228:231], v[236:239], v[8:11]
	s_waitcnt lgkmcnt(2)
	v_mfma_f32_16x16x32_bf16 v[80:83], v[216:219], v[240:243], v[80:83]
	ds_read_b128 v[236:239], v148 offset:50176
	v_mfma_f32_16x16x32_bf16 v[52:55], v[220:223], v[240:243], v[52:55]
	v_mfma_f32_16x16x32_bf16 v[20:23], v[224:227], v[240:243], v[20:23]
	v_mfma_f32_16x16x32_bf16 v[4:7], v[228:231], v[240:243], v[4:7]
	s_waitcnt lgkmcnt(2)
	v_mfma_f32_16x16x32_bf16 v[72:75], v[216:219], v[244:247], v[72:75]
	ds_read_b128 v[240:243], v148 offset:51200
	v_mfma_f32_16x16x32_bf16 v[48:51], v[220:223], v[244:247], v[48:51]
	v_mfma_f32_16x16x32_bf16 v[16:19], v[224:227], v[244:247], v[16:19]
	v_mfma_f32_16x16x32_bf16 v[0:3], v[228:231], v[244:247], v[0:3]
	ds_read_b128 v[244:247], v148 offset:52224
	v_readfirstlane_b32 s11, v146
	v_lshl_add_u64 v[168:169], v[144:145], 0, s[62:63]
	s_mov_b32 m0, s11
	v_readfirstlane_b32 s11, v151
	s_waitcnt lgkmcnt(3)
	v_mfma_f32_16x16x32_bf16 v[124:127], v[186:189], v[232:235], v[124:127]
	v_lshl_add_u64 v[182:183], v[142:143], 0, s[62:63]
	v_mfma_f32_16x16x32_bf16 v[108:111], v[190:193], v[232:235], v[108:111]
	v_mfma_f32_16x16x32_bf16 v[88:91], v[194:197], v[232:235], v[88:91]
	s_waitcnt vmcnt(4)
	s_barrier
; #define BIG_SYNC(N)                                              \
;   asm volatile("s_waitcnt vmcnt(%0)" ::"n"(N) : "memory");       \
;   __builtin_amdgcn_s_barrier();                                  \
;   asm volatile("" ::: "memory");                                 \
;   __builtin_amdgcn_sched_barrier(0);
; template <int NK, bool BNT = false> ...
;     ...
;   auto kstep = [&](int T, int cur, int nxt, bool do_stage) {
;     const unsigned char* sa = smem + cur * BIG_STAGE;
;     bf16x8 af[4], bfr[4];
; #pragma unroll
;     for (int m = 0; m < 4; ++m) af[m] = *reinterpret_cast<const bf16x8*>(sa + aoff + m * 1024);
; #pragma unroll
;     for (int n = 0; n < 4; ++n) bfr[n] = *reinterpret_cast<const bf16x8*>(sa + boff + n * 1024);
;     __builtin_amdgcn_sched_barrier(0);
;     if (do_stage) stage(T + 3, nxt);
; #pragma unroll
;     for (int m = 0; m < 4; ++m)
; #pragma unroll
;       for (int n = 0; n < 4; ++n) acc[m][n] = __builtin_amdgcn_mfma_f32_16x16x32_bf16(af[m], bfr[n], acc[m][n], 0, 0, 0);
;     if (do_stage) {
; #pragma unroll
;       for (int q = 0; q < NG; ++q) {
;         __builtin_amdgcn_sched_group_barrier(0x008, 3, 0);
;         __builtin_amdgcn_sched_group_barrier(0x010, 1, 0);
;       }
;       __builtin_amdgcn_sched_group_barrier(0x008, 16 - 3 * NG, 0);
;     }
;     __builtin_amdgcn_sched_barrier(0);
; #pragma unroll
;     for (int n = 0; n < 4; ++n) bfr[n] = *reinterpret_cast<const bf16x8*>(sa + boff + (4 + n) * 1024);
; #pragma unroll
;     for (int m = 0; m < 4; ++m)
; #pragma unroll
;       for (int n = 0; n < 4; ++n)
;         acc[m][4 + n] = __builtin_amdgcn_mfma_f32_16x16x32_bf16(af[m], bfr[n], acc[m][4 + n], 0, 0, 0);
;     __builtin_amdgcn_sched_barrier(0);
;   };
;     ...
;   for (int it = 0; it < NK / 4 - 1; ++it) {
;     const int t = it * 4;
;     BIG_SYNC(2 * NG); kstep(t, 0, 3, true);
;     BIG_SYNC(2 * NG); kstep(t + 1, 1, 0, true);
;     BIG_SYNC(2 * NG); kstep(t + 2, 2, 1, true);
;     BIG_SYNC(2 * NG); kstep(t + 3, 3, 2, true);
;   }
	global_load_lds_dwordx4 v[168:169], off
	v_lshl_add_u64 v[168:169], v[144:145], 0, s[0:1]
	s_mov_b32 m0, s11
	v_readfirstlane_b32 s11, v152
	v_mfma_f32_16x16x32_bf16 v[44:47], v[202:205], v[232:235], v[44:47]
	s_waitcnt lgkmcnt(2)
	v_mfma_f32_16x16x32_bf16 v[120:123], v[186:189], v[236:239], v[120:123]
	ds_read_b128 v[232:235], v148 offset:53248
	v_mfma_f32_16x16x32_bf16 v[104:107], v[190:193], v[236:239], v[104:107]
	v_add_u32_e32 v167, 0x10000, v147
	ds_read_b128 v[216:219], v167
	global_load_lds_dwordx4 v[168:169], off
	s_mov_b32 m0, s11
	v_readfirstlane_b32 s11, v154
	v_lshl_add_u64 v[168:169], v[142:143], 0, s[0:1]
	v_mfma_f32_16x16x32_bf16 v[76:79], v[194:197], v[236:239], v[76:79]
	ds_read_b128 v[220:223], v167 offset:1024
	v_mfma_f32_16x16x32_bf16 v[40:43], v[202:205], v[236:239], v[40:43]
	ds_read_b128 v[224:227], v167 offset:2048
	s_waitcnt lgkmcnt(5)
	v_mfma_f32_16x16x32_bf16 v[116:119], v[186:189], v[240:243], v[116:119]
	ds_read_b128 v[236:239], v148 offset:54272
	global_load_lds_dwordx4 v[182:183], off
	s_mov_b32 m0, s11
	v_mfma_f32_16x16x32_bf16 v[100:103], v[190:193], v[240:243], v[100:103]
	ds_read_b128 v[228:231], v167 offset:3072
	v_mfma_f32_16x16x32_bf16 v[68:71], v[194:197], v[240:243], v[68:71]
	v_mfma_f32_16x16x32_bf16 v[36:39], v[202:205], v[240:243], v[36:39]
	global_load_lds_dwordx4 v[168:169], off
	s_waitcnt lgkmcnt(6)
	v_mfma_f32_16x16x32_bf16 v[112:115], v[186:189], v[244:247], v[112:115]
	ds_read_b128 v[240:243], v148 offset:55296
	v_mfma_f32_16x16x32_bf16 v[96:99], v[190:193], v[244:247], v[96:99]
	v_mfma_f32_16x16x32_bf16 v[64:67], v[194:197], v[244:247], v[64:67]
	v_mfma_f32_16x16x32_bf16 v[32:35], v[202:205], v[244:247], v[32:35]
	v_or_b32_e32 v168, 0x10000, v149
	s_waitcnt lgkmcnt(6)
	v_mfma_f32_16x16x32_bf16 v[92:95], v[186:189], v[232:235], v[92:95]
	ds_read_b128 v[244:247], v148 offset:56320
	v_mfma_f32_16x16x32_bf16 v[60:63], v[190:193], v[232:235], v[60:63]
	v_mfma_f32_16x16x32_bf16 v[28:31], v[194:197], v[232:235], v[28:31]
	v_mfma_f32_16x16x32_bf16 v[12:15], v[202:205], v[232:235], v[12:15]
	s_waitcnt lgkmcnt(3)
	v_mfma_f32_16x16x32_bf16 v[84:87], v[186:189], v[236:239], v[84:87]
	ds_read_b128 v[232:235], v168
	v_mfma_f32_16x16x32_bf16 v[56:59], v[190:193], v[236:239], v[56:59]
	v_mfma_f32_16x16x32_bf16 v[24:27], v[194:197], v[236:239], v[24:27]
	v_mfma_f32_16x16x32_bf16 v[8:11], v[202:205], v[236:239], v[8:11]
	s_waitcnt lgkmcnt(2)
	v_mfma_f32_16x16x32_bf16 v[80:83], v[186:189], v[240:243], v[80:83]
	ds_read_b128 v[236:239], v168 offset:1024
	v_mfma_f32_16x16x32_bf16 v[52:55], v[190:193], v[240:243], v[52:55]
	v_mfma_f32_16x16x32_bf16 v[20:23], v[194:197], v[240:243], v[20:23]
	v_mfma_f32_16x16x32_bf16 v[4:7], v[202:205], v[240:243], v[4:7]
	s_waitcnt lgkmcnt(2)
	v_mfma_f32_16x16x32_bf16 v[72:75], v[186:189], v[244:247], v[72:75]
	ds_read_b128 v[240:243], v168 offset:2048
	v_mfma_f32_16x16x32_bf16 v[48:51], v[190:193], v[244:247], v[48:51]
	v_mfma_f32_16x16x32_bf16 v[16:19], v[194:197], v[244:247], v[16:19]
	v_mfma_f32_16x16x32_bf16 v[0:3], v[202:205], v[244:247], v[0:3]
	ds_read_b128 v[244:247], v168 offset:3072
	v_add_u32_e32 v167, 0x10000, v147
	v_or_b32_e32 v168, 0x10000, v149
	v_add_u32_e32 v169, 0x10400, v149
	v_add_u32_e32 v170, 0x10800, v149
	v_add_u32_e32 v172, 0x10c00, v149
	v_readfirstlane_b32 s11, v155
	v_lshl_add_u64 v[174:175], v[144:145], 0, s[2:3]
	s_mov_b32 m0, s11
	v_readfirstlane_b32 s11, v156
	s_waitcnt lgkmcnt(3)
	v_mfma_f32_16x16x32_bf16 v[124:127], v[216:219], v[232:235], v[124:127]
	v_lshl_add_u64 v[178:179], v[142:143], 0, s[2:3]
	v_mfma_f32_16x16x32_bf16 v[108:111], v[220:223], v[232:235], v[108:111]
	v_mfma_f32_16x16x32_bf16 v[88:91], v[224:227], v[232:235], v[88:91]
	s_waitcnt vmcnt(4)
	s_barrier
	global_load_lds_dwordx4 v[174:175], off
	v_lshl_add_u64 v[174:175], v[144:145], 0, s[52:53]
	s_mov_b32 m0, s11
	v_readfirstlane_b32 s11, v157
	v_mfma_f32_16x16x32_bf16 v[44:47], v[228:231], v[232:235], v[44:47]
	s_waitcnt lgkmcnt(2)
	v_mfma_f32_16x16x32_bf16 v[120:123], v[216:219], v[236:239], v[120:123]
	ds_read_b128 v[232:235], v168 offset:4096
	v_mfma_f32_16x16x32_bf16 v[104:107], v[220:223], v[236:239], v[104:107]
	v_add_u32_e32 v167, 0x10000, v147
	ds_read_b128 v[186:189], v167 offset:32768
	global_load_lds_dwordx4 v[174:175], off
	s_mov_b32 m0, s11
	v_readfirstlane_b32 s11, v158
	v_lshl_add_u64 v[174:175], v[142:143], 0, s[52:53]
	v_mfma_f32_16x16x32_bf16 v[76:79], v[224:227], v[236:239], v[76:79]
	ds_read_b128 v[190:193], v167 offset:33792
	v_mfma_f32_16x16x32_bf16 v[40:43], v[228:231], v[236:239], v[40:43]
	ds_read_b128 v[194:197], v167 offset:34816
	s_waitcnt lgkmcnt(5)
	v_mfma_f32_16x16x32_bf16 v[116:119], v[216:219], v[240:243], v[116:119]
	ds_read_b128 v[236:239], v168 offset:5120
	global_load_lds_dwordx4 v[178:179], off
	s_mov_b32 m0, s11
	v_mfma_f32_16x16x32_bf16 v[100:103], v[220:223], v[240:243], v[100:103]
	ds_read_b128 v[202:205], v167 offset:35840
	v_mfma_f32_16x16x32_bf16 v[68:71], v[224:227], v[240:243], v[68:71]
	v_mfma_f32_16x16x32_bf16 v[36:39], v[228:231], v[240:243], v[36:39]
	global_load_lds_dwordx4 v[174:175], off
	s_waitcnt lgkmcnt(6)
	v_mfma_f32_16x16x32_bf16 v[112:115], v[216:219], v[244:247], v[112:115]
	ds_read_b128 v[240:243], v168 offset:6144
	v_mfma_f32_16x16x32_bf16 v[96:99], v[220:223], v[244:247], v[96:99]
	v_mfma_f32_16x16x32_bf16 v[64:67], v[224:227], v[244:247], v[64:67]
	v_mfma_f32_16x16x32_bf16 v[32:35], v[228:231], v[244:247], v[32:35]
	v_add_u32_e32 v173, 0x11000, v149
	v_add_u32_e32 v174, 0x11400, v149
	v_add_u32_e32 v175, 0x11800, v149
	v_add_u32_e32 v178, 0x11c00, v149
	v_or_b32_e32 v168, 0x10000, v149
	s_waitcnt lgkmcnt(6)
; #define BIG_SYNC(N)                                              \
;   asm volatile("s_waitcnt vmcnt(%0)" ::"n"(N) : "memory");       \
;   __builtin_amdgcn_s_barrier();                                  \
;   asm volatile("" ::: "memory");                                 \
;   __builtin_amdgcn_sched_barrier(0);
; template <int NK, bool BNT = false> ...
;     ...
;   auto kstep = [&](int T, int cur, int nxt, bool do_stage) {
;     const unsigned char* sa = smem + cur * BIG_STAGE;
;     bf16x8 af[4], bfr[4];
; #pragma unroll
;     for (int m = 0; m < 4; ++m) af[m] = *reinterpret_cast<const bf16x8*>(sa + aoff + m * 1024);
; #pragma unroll
;     for (int n = 0; n < 4; ++n) bfr[n] = *reinterpret_cast<const bf16x8*>(sa + boff + n * 1024);
;     __builtin_amdgcn_sched_barrier(0);
;     if (do_stage) stage(T + 3, nxt);
; #pragma unroll
;     for (int m = 0; m < 4; ++m)
; #pragma unroll
;       for (int n = 0; n < 4; ++n) acc[m][n] = __builtin_amdgcn_mfma_f32_16x16x32_bf16(af[m], bfr[n], acc[m][n], 0, 0, 0);
;     if (do_stage) {
; #pragma unroll
;       for (int q = 0; q < NG; ++q) {
;         __builtin_amdgcn_sched_group_barrier(0x008, 3, 0);
;         __builtin_amdgcn_sched_group_barrier(0x010, 1, 0);
;       }
;       __builtin_amdgcn_sched_group_barrier(0x008, 16 - 3 * NG, 0);
;     }
;     __builtin_amdgcn_sched_barrier(0);
; #pragma unroll
;     for (int n = 0; n < 4; ++n) bfr[n] = *reinterpret_cast<const bf16x8*>(sa + boff + (4 + n) * 1024);
; #pragma unroll
;     for (int m = 0; m < 4; ++m)
; #pragma unroll
;       for (int n = 0; n < 4; ++n)
;         acc[m][4 + n] = __builtin_amdgcn_mfma_f32_16x16x32_bf16(af[m], bfr[n], acc[m][4 + n], 0, 0, 0);
;     __builtin_amdgcn_sched_barrier(0);
;   };
;     ...
;   for (int it = 0; it < NK / 4 - 1; ++it) {
;     const int t = it * 4;
;     BIG_SYNC(2 * NG); kstep(t, 0, 3, true);
;     BIG_SYNC(2 * NG); kstep(t + 1, 1, 0, true);
;     BIG_SYNC(2 * NG); kstep(t + 2, 2, 1, true);
;     BIG_SYNC(2 * NG); kstep(t + 3, 3, 2, true);
;   }
	v_mfma_f32_16x16x32_bf16 v[92:95], v[216:219], v[232:235], v[92:95]
	ds_read_b128 v[244:247], v168 offset:7168
	v_mfma_f32_16x16x32_bf16 v[60:63], v[220:223], v[232:235], v[60:63]
	v_mfma_f32_16x16x32_bf16 v[28:31], v[224:227], v[232:235], v[28:31]
	v_mfma_f32_16x16x32_bf16 v[12:15], v[228:231], v[232:235], v[12:15]
	s_waitcnt lgkmcnt(3)
	v_mfma_f32_16x16x32_bf16 v[84:87], v[216:219], v[236:239], v[84:87]
	ds_read_b128 v[232:235], v168 offset:32768
	v_mfma_f32_16x16x32_bf16 v[56:59], v[220:223], v[236:239], v[56:59]
	v_mfma_f32_16x16x32_bf16 v[24:27], v[224:227], v[236:239], v[24:27]
	v_mfma_f32_16x16x32_bf16 v[8:11], v[228:231], v[236:239], v[8:11]
	s_waitcnt lgkmcnt(2)
	v_mfma_f32_16x16x32_bf16 v[80:83], v[216:219], v[240:243], v[80:83]
	ds_read_b128 v[236:239], v168 offset:33792
	v_mfma_f32_16x16x32_bf16 v[52:55], v[220:223], v[240:243], v[52:55]
	v_mfma_f32_16x16x32_bf16 v[20:23], v[224:227], v[240:243], v[20:23]
	v_mfma_f32_16x16x32_bf16 v[4:7], v[228:231], v[240:243], v[4:7]
	s_waitcnt lgkmcnt(2)
	v_mfma_f32_16x16x32_bf16 v[72:75], v[216:219], v[244:247], v[72:75]
	ds_read_b128 v[240:243], v168 offset:34816
	v_mfma_f32_16x16x32_bf16 v[48:51], v[220:223], v[244:247], v[48:51]
	v_mfma_f32_16x16x32_bf16 v[16:19], v[224:227], v[244:247], v[16:19]
	v_mfma_f32_16x16x32_bf16 v[0:3], v[228:231], v[244:247], v[0:3]
	ds_read_b128 v[244:247], v168 offset:35840
	v_add_u32_e32 v176, 0x18000, v147
	v_or_b32_e32 v179, 0x18000, v149
	v_add_u32_e32 v180, 0x18400, v149
	v_add_u32_e32 v181, 0x18800, v149
	v_add_u32_e32 v182, 0x18c00, v149
	v_readfirstlane_b32 s11, v159
	v_lshl_add_u64 v[248:249], v[144:145], 0, s[54:55]
	s_mov_b32 m0, s11
	v_readfirstlane_b32 s11, v160
	v_lshl_add_u64 v[144:145], v[144:145], 0, s[56:57]
	s_waitcnt lgkmcnt(3)
	v_mfma_f32_16x16x32_bf16 v[124:127], v[186:189], v[232:235], v[124:127]
	v_lshl_add_u64 v[250:251], v[142:143], 0, s[54:55]
	v_lshl_add_u64 v[142:143], v[142:143], 0, s[56:57]
	v_mfma_f32_16x16x32_bf16 v[108:111], v[190:193], v[232:235], v[108:111]
	v_mfma_f32_16x16x32_bf16 v[88:91], v[194:197], v[232:235], v[88:91]
	s_waitcnt vmcnt(4)
	s_barrier
	global_load_lds_dwordx4 v[248:249], off
	s_mov_b32 m0, s11
	v_readfirstlane_b32 s11, v161
	v_mfma_f32_16x16x32_bf16 v[44:47], v[202:205], v[232:235], v[44:47]
	s_waitcnt lgkmcnt(2)
	v_mfma_f32_16x16x32_bf16 v[120:123], v[186:189], v[236:239], v[120:123]
	ds_read_b128 v[232:235], v168 offset:36864
	v_mfma_f32_16x16x32_bf16 v[104:107], v[190:193], v[236:239], v[104:107]
	ds_read_b128 v[216:219], v147
	global_load_lds_dwordx4 v[144:145], off
	s_mov_b32 m0, s11
	v_readfirstlane_b32 s11, v162
	v_mfma_f32_16x16x32_bf16 v[76:79], v[194:197], v[236:239], v[76:79]
	ds_read_b128 v[220:223], v147 offset:1024
	v_mfma_f32_16x16x32_bf16 v[40:43], v[202:205], v[236:239], v[40:43]
	ds_read_b128 v[224:227], v147 offset:2048
	s_waitcnt lgkmcnt(5)
	v_mfma_f32_16x16x32_bf16 v[116:119], v[186:189], v[240:243], v[116:119]
	ds_read_b128 v[236:239], v168 offset:37888
	global_load_lds_dwordx4 v[250:251], off
	s_mov_b32 m0, s11
	v_mfma_f32_16x16x32_bf16 v[100:103], v[190:193], v[240:243], v[100:103]
	ds_read_b128 v[228:231], v147 offset:3072
	v_mfma_f32_16x16x32_bf16 v[68:71], v[194:197], v[240:243], v[68:71]
	v_mfma_f32_16x16x32_bf16 v[36:39], v[202:205], v[240:243], v[36:39]
	global_load_lds_dwordx4 v[142:143], off
	s_waitcnt lgkmcnt(6)
	v_mfma_f32_16x16x32_bf16 v[112:115], v[186:189], v[244:247], v[112:115]
	ds_read_b128 v[240:243], v168 offset:38912
	v_mfma_f32_16x16x32_bf16 v[96:99], v[190:193], v[244:247], v[96:99]
	v_mfma_f32_16x16x32_bf16 v[64:67], v[194:197], v[244:247], v[64:67]
	v_mfma_f32_16x16x32_bf16 v[32:35], v[202:205], v[244:247], v[32:35]
	v_add_u32_e32 v142, 0x19000, v149
	v_add_u32_e32 v143, 0x19400, v149
	v_add_u32_e32 v144, 0x19800, v149
	v_add_u32_e32 v145, 0x19c00, v149
	s_waitcnt lgkmcnt(6)
	v_mfma_f32_16x16x32_bf16 v[92:95], v[186:189], v[232:235], v[92:95]
	ds_read_b128 v[244:247], v168 offset:39936
	v_mfma_f32_16x16x32_bf16 v[60:63], v[190:193], v[232:235], v[60:63]
	v_mfma_f32_16x16x32_bf16 v[28:31], v[194:197], v[232:235], v[28:31]
	v_mfma_f32_16x16x32_bf16 v[12:15], v[202:205], v[232:235], v[12:15]
	s_waitcnt lgkmcnt(3)
	v_mfma_f32_16x16x32_bf16 v[84:87], v[186:189], v[236:239], v[84:87]
	ds_read_b128 v[232:235], v148 offset:16384
	v_mfma_f32_16x16x32_bf16 v[56:59], v[190:193], v[236:239], v[56:59]
	v_mfma_f32_16x16x32_bf16 v[24:27], v[194:197], v[236:239], v[24:27]
	v_mfma_f32_16x16x32_bf16 v[8:11], v[202:205], v[236:239], v[8:11]
	s_waitcnt lgkmcnt(2)
	v_mfma_f32_16x16x32_bf16 v[80:83], v[186:189], v[240:243], v[80:83]
	ds_read_b128 v[236:239], v148 offset:17408
	v_mfma_f32_16x16x32_bf16 v[52:55], v[190:193], v[240:243], v[52:55]
	v_mfma_f32_16x16x32_bf16 v[20:23], v[194:197], v[240:243], v[20:23]
	v_mfma_f32_16x16x32_bf16 v[4:7], v[202:205], v[240:243], v[4:7]
	s_waitcnt lgkmcnt(2)
	v_mfma_f32_16x16x32_bf16 v[72:75], v[186:189], v[244:247], v[72:75]
	ds_read_b128 v[240:243], v148 offset:18432
	v_mfma_f32_16x16x32_bf16 v[48:51], v[190:193], v[244:247], v[48:51]
	v_mfma_f32_16x16x32_bf16 v[16:19], v[194:197], v[244:247], v[16:19]
	v_mfma_f32_16x16x32_bf16 v[0:3], v[202:205], v[244:247], v[0:3]
	ds_read_b128 v[244:247], v148 offset:19456
	s_add_u32 s12, s12, 0x8000
	s_addc_u32 s13, s13, 0
	s_cmp_lg_u32 s12, 0x38000
	s_cbranch_scc1 .LBB0_290
	s_mov_b64 s[12:13], 0x3e000
	v_readfirstlane_b32 s11, v163
	v_lshl_add_u64 v[198:199], v[136:137], 0, s[12:13]
	v_lshl_add_u64 v[200:201], v[134:135], 0, s[12:13]
	s_mov_b32 m0, s11
	s_mov_b64 s[12:13], 0x7e000
	v_readfirstlane_b32 s11, v164
	v_lshl_add_u64 v[136:137], v[136:137], 0, s[12:13]
	s_waitcnt lgkmcnt(3)
	v_mfma_f32_16x16x32_bf16 v[124:127], v[216:219], v[232:235], v[124:127]
	v_lshl_add_u64 v[134:135], v[134:135], 0, s[12:13]
	v_mfma_f32_16x16x32_bf16 v[108:111], v[220:223], v[232:235], v[108:111]
	v_mfma_f32_16x16x32_bf16 v[88:91], v[224:227], v[232:235], v[88:91]
	s_waitcnt vmcnt(4)
	s_barrier
; #define BIG_SYNC(N)                                              \
;   asm volatile("s_waitcnt vmcnt(%0)" ::"n"(N) : "memory");       \
;   __builtin_amdgcn_s_barrier();                                  \
;   asm volatile("" ::: "memory");                                 \
;   __builtin_amdgcn_sched_barrier(0);
; template <int NK, bool BNT = false> ...
;     ...
;   auto kstep = [&](int T, int cur, int nxt, bool do_stage) {
;     const unsigned char* sa = smem + cur * BIG_STAGE;
;     bf16x8 af[4], bfr[4];
; #pragma unroll
;     for (int m = 0; m < 4; ++m) af[m] = *reinterpret_cast<const bf16x8*>(sa + aoff + m * 1024);
; #pragma unroll
;     for (int n = 0; n < 4; ++n) bfr[n] = *reinterpret_cast<const bf16x8*>(sa + boff + n * 1024);
;     __builtin_amdgcn_sched_barrier(0);
;     if (do_stage) stage(T + 3, nxt);
; #pragma unroll
;     for (int m = 0; m < 4; ++m)
; #pragma unroll
;       for (int n = 0; n < 4; ++n) acc[m][n] = __builtin_amdgcn_mfma_f32_16x16x32_bf16(af[m], bfr[n], acc[m][n], 0, 0, 0);
;     if (do_stage) {
; #pragma unroll
;       for (int q = 0; q < NG; ++q) {
;         __builtin_amdgcn_sched_group_barrier(0x008, 3, 0);
;         __builtin_amdgcn_sched_group_barrier(0x010, 1, 0);
;       }
;       __builtin_amdgcn_sched_group_barrier(0x008, 16 - 3 * NG, 0);
;     }
;     __builtin_amdgcn_sched_barrier(0);
; #pragma unroll
;     for (int n = 0; n < 4; ++n) bfr[n] = *reinterpret_cast<const bf16x8*>(sa + boff + (4 + n) * 1024);
; #pragma unroll
;     for (int m = 0; m < 4; ++m)
; #pragma unroll
;       for (int n = 0; n < 4; ++n)
;         acc[m][4 + n] = __builtin_amdgcn_mfma_f32_16x16x32_bf16(af[m], bfr[n], acc[m][4 + n], 0, 0, 0);
;     __builtin_amdgcn_sched_barrier(0);
;   };
;     ...
;   BIG_SYNC(2 * NG); kstep(NK - 4, 0, 3, true);
;   BIG_SYNC(2 * NG); kstep(NK - 3, 1, 0, false);
;   BIG_SYNC(NG);     kstep(NK - 2, 2, 0, false);
	global_load_lds_dwordx4 v[198:199], off
	s_mov_b32 m0, s11
	v_readfirstlane_b32 s11, v165
	v_mfma_f32_16x16x32_bf16 v[44:47], v[228:231], v[232:235], v[44:47]
	s_waitcnt lgkmcnt(2)
	v_mfma_f32_16x16x32_bf16 v[120:123], v[216:219], v[236:239], v[120:123]
	ds_read_b128 v[232:235], v148 offset:20480
	v_mfma_f32_16x16x32_bf16 v[104:107], v[220:223], v[236:239], v[104:107]
	ds_read_b128 v[186:189], v147 offset:32768
	global_load_lds_dwordx4 v[136:137], off
	s_mov_b32 m0, s11
	v_readfirstlane_b32 s11, v166
	v_mfma_f32_16x16x32_bf16 v[76:79], v[224:227], v[236:239], v[76:79]
	ds_read_b128 v[190:193], v147 offset:33792
	v_mfma_f32_16x16x32_bf16 v[40:43], v[228:231], v[236:239], v[40:43]
	ds_read_b128 v[194:197], v147 offset:34816
	s_waitcnt lgkmcnt(5)
	v_mfma_f32_16x16x32_bf16 v[116:119], v[216:219], v[240:243], v[116:119]
	ds_read_b128 v[236:239], v148 offset:21504
	global_load_lds_dwordx4 v[200:201], off
	s_mov_b32 m0, s11
	v_mfma_f32_16x16x32_bf16 v[100:103], v[220:223], v[240:243], v[100:103]
	ds_read_b128 v[202:205], v147 offset:35840
	v_mfma_f32_16x16x32_bf16 v[68:71], v[224:227], v[240:243], v[68:71]
	v_mfma_f32_16x16x32_bf16 v[36:39], v[228:231], v[240:243], v[36:39]
	global_load_lds_dwordx4 v[134:135], off
	s_waitcnt lgkmcnt(6)
	v_mfma_f32_16x16x32_bf16 v[112:115], v[216:219], v[244:247], v[112:115]
	ds_read_b128 v[240:243], v148 offset:22528
	v_mfma_f32_16x16x32_bf16 v[96:99], v[220:223], v[244:247], v[96:99]
	v_mfma_f32_16x16x32_bf16 v[64:67], v[224:227], v[244:247], v[64:67]
	v_mfma_f32_16x16x32_bf16 v[32:35], v[228:231], v[244:247], v[32:35]
	s_waitcnt lgkmcnt(6)
	v_mfma_f32_16x16x32_bf16 v[92:95], v[216:219], v[232:235], v[92:95]
	ds_read_b128 v[244:247], v148 offset:23552
	v_mfma_f32_16x16x32_bf16 v[60:63], v[220:223], v[232:235], v[60:63]
	v_mfma_f32_16x16x32_bf16 v[28:31], v[224:227], v[232:235], v[28:31]
	v_mfma_f32_16x16x32_bf16 v[12:15], v[228:231], v[232:235], v[12:15]
	s_waitcnt lgkmcnt(3)
	v_mfma_f32_16x16x32_bf16 v[84:87], v[216:219], v[236:239], v[84:87]
	ds_read_b128 v[232:235], v148 offset:49152
	v_mfma_f32_16x16x32_bf16 v[56:59], v[220:223], v[236:239], v[56:59]
	v_mfma_f32_16x16x32_bf16 v[24:27], v[224:227], v[236:239], v[24:27]
	v_mfma_f32_16x16x32_bf16 v[8:11], v[228:231], v[236:239], v[8:11]
	s_waitcnt lgkmcnt(2)
	v_mfma_f32_16x16x32_bf16 v[80:83], v[216:219], v[240:243], v[80:83]
	ds_read_b128 v[236:239], v148 offset:50176
	v_mfma_f32_16x16x32_bf16 v[52:55], v[220:223], v[240:243], v[52:55]
	v_mfma_f32_16x16x32_bf16 v[20:23], v[224:227], v[240:243], v[20:23]
	v_mfma_f32_16x16x32_bf16 v[4:7], v[228:231], v[240:243], v[4:7]
	s_waitcnt lgkmcnt(2)
	v_mfma_f32_16x16x32_bf16 v[72:75], v[216:219], v[244:247], v[72:75]
	ds_read_b128 v[240:243], v148 offset:51200
	v_mfma_f32_16x16x32_bf16 v[48:51], v[220:223], v[244:247], v[48:51]
	v_mfma_f32_16x16x32_bf16 v[16:19], v[224:227], v[244:247], v[16:19]
	v_mfma_f32_16x16x32_bf16 v[0:3], v[228:231], v[244:247], v[0:3]
	ds_read_b128 v[244:247], v148 offset:52224
	s_waitcnt lgkmcnt(3)
	v_mfma_f32_16x16x32_bf16 v[124:127], v[186:189], v[232:235], v[124:127]
	v_mfma_f32_16x16x32_bf16 v[108:111], v[190:193], v[232:235], v[108:111]
	v_mfma_f32_16x16x32_bf16 v[88:91], v[194:197], v[232:235], v[88:91]
	v_mfma_f32_16x16x32_bf16 v[44:47], v[202:205], v[232:235], v[44:47]
	s_waitcnt vmcnt(4)
	s_barrier
	s_waitcnt lgkmcnt(2)
	v_mfma_f32_16x16x32_bf16 v[120:123], v[186:189], v[236:239], v[120:123]
	ds_read_b128 v[232:235], v148 offset:53248
	v_mfma_f32_16x16x32_bf16 v[104:107], v[190:193], v[236:239], v[104:107]
	v_mfma_f32_16x16x32_bf16 v[76:79], v[194:197], v[236:239], v[76:79]
	v_mfma_f32_16x16x32_bf16 v[40:43], v[202:205], v[236:239], v[40:43]
	s_waitcnt lgkmcnt(2)
	v_mfma_f32_16x16x32_bf16 v[116:119], v[186:189], v[240:243], v[116:119]
	ds_read_b128 v[236:239], v148 offset:54272
	v_mfma_f32_16x16x32_bf16 v[100:103], v[190:193], v[240:243], v[100:103]
	v_mfma_f32_16x16x32_bf16 v[68:71], v[194:197], v[240:243], v[68:71]
	v_mfma_f32_16x16x32_bf16 v[36:39], v[202:205], v[240:243], v[36:39]
	s_waitcnt lgkmcnt(2)
	v_mfma_f32_16x16x32_bf16 v[112:115], v[186:189], v[244:247], v[112:115]
	ds_read_b128 v[240:243], v148 offset:55296
	v_mfma_f32_16x16x32_bf16 v[96:99], v[190:193], v[244:247], v[96:99]
	v_mfma_f32_16x16x32_bf16 v[64:67], v[194:197], v[244:247], v[64:67]
	v_mfma_f32_16x16x32_bf16 v[32:35], v[202:205], v[244:247], v[32:35]
	s_waitcnt lgkmcnt(2)
	v_mfma_f32_16x16x32_bf16 v[92:95], v[186:189], v[232:235], v[92:95]
	ds_read_b128 v[244:247], v148 offset:56320
	v_mfma_f32_16x16x32_bf16 v[60:63], v[190:193], v[232:235], v[60:63]
	v_mfma_f32_16x16x32_bf16 v[28:31], v[194:197], v[232:235], v[28:31]
	v_mfma_f32_16x16x32_bf16 v[12:15], v[202:205], v[232:235], v[12:15]
	s_waitcnt lgkmcnt(2)
	v_mfma_f32_16x16x32_bf16 v[84:87], v[186:189], v[236:239], v[84:87]
	v_mfma_f32_16x16x32_bf16 v[56:59], v[190:193], v[236:239], v[56:59]
	v_mfma_f32_16x16x32_bf16 v[24:27], v[194:197], v[236:239], v[24:27]
	v_mfma_f32_16x16x32_bf16 v[8:11], v[202:205], v[236:239], v[8:11]
	s_waitcnt lgkmcnt(1)
	v_mfma_f32_16x16x32_bf16 v[80:83], v[186:189], v[240:243], v[80:83]
	v_mfma_f32_16x16x32_bf16 v[52:55], v[190:193], v[240:243], v[52:55]
	v_mfma_f32_16x16x32_bf16 v[20:23], v[194:197], v[240:243], v[20:23]
	v_mfma_f32_16x16x32_bf16 v[4:7], v[202:205], v[240:243], v[4:7]
	s_waitcnt lgkmcnt(0)
	v_mfma_f32_16x16x32_bf16 v[72:75], v[186:189], v[244:247], v[72:75]
	v_mfma_f32_16x16x32_bf16 v[48:51], v[190:193], v[244:247], v[48:51]
	v_mfma_f32_16x16x32_bf16 v[16:19], v[194:197], v[244:247], v[16:19]
	v_mfma_f32_16x16x32_bf16 v[0:3], v[202:205], v[244:247], v[0:3]
	v_mov_b32_e32 v186, 0xf149f2ca
	v_mov_b32_e32 v187, 0x3c0881c4
	v_mov_b32_e32 v188, 0xbab64f3b
	v_mov_b32_e32 v189, 0x24800
	v_mov_b32_e32 v190, 1
	v_mov_b32_e32 v191, 0x24804
	v_mov_b32_e32 v192, 0xfcf
	v_mov_b32_e32 v193, 0x7cf
	v_mov_b32_e32 v194, 0xfdf
	v_mov_b32_e32 v195, 0x7df
	v_mov_b32_e32 v196, 0xfef
	v_mov_b32_e32 v197, 0x7ef
	v_mov_b32_e32 v198, 0xfff
	v_mov_b32_e32 v199, 0x7ff
	v_mov_b32_e32 v200, 0x20000
	v_mov_b32_e32 v201, 0xf8f
	v_mov_b32_e32 v202, 0x78f
	v_mov_b32_e32 v203, 0xf9f
	v_mov_b32_e32 v204, 0x79f
	v_mov_b32_e32 v205, 0xfaf
	s_waitcnt vmcnt(4)
	s_barrier
; template <int NK, bool BNT = false> ...
;     ...
;   auto kstep = [&](int T, int cur, int nxt, bool do_stage) {
;     const unsigned char* sa = smem + cur * BIG_STAGE;
;     bf16x8 af[4], bfr[4];
; #pragma unroll
;     for (int m = 0; m < 4; ++m) af[m] = *reinterpret_cast<const bf16x8*>(sa + aoff + m * 1024);
; #pragma unroll
;     for (int n = 0; n < 4; ++n) bfr[n] = *reinterpret_cast<const bf16x8*>(sa + boff + n * 1024);
;     __builtin_amdgcn_sched_barrier(0);
;     if (do_stage) stage(T + 3, nxt);
; #pragma unroll
;     for (int m = 0; m < 4; ++m)
; #pragma unroll
;       for (int n = 0; n < 4; ++n) acc[m][n] = __builtin_amdgcn_mfma_f32_16x16x32_bf16(af[m], bfr[n], acc[m][n], 0, 0, 0);
;     if (do_stage) {
; #pragma unroll
;       for (int q = 0; q < NG; ++q) {
;         __builtin_amdgcn_sched_group_barrier(0x008, 3, 0);
;         __builtin_amdgcn_sched_group_barrier(0x010, 1, 0);
;       }
;       __builtin_amdgcn_sched_group_barrier(0x008, 16 - 3 * NG, 0);
;     }
;     __builtin_amdgcn_sched_barrier(0);
; #pragma unroll
;     for (int n = 0; n < 4; ++n) bfr[n] = *reinterpret_cast<const bf16x8*>(sa + boff + (4 + n) * 1024);
; #pragma unroll
;     for (int m = 0; m < 4; ++m)
; #pragma unroll
;       for (int n = 0; n < 4; ++n)
;         acc[m][4 + n] = __builtin_amdgcn_mfma_f32_16x16x32_bf16(af[m], bfr[n], acc[m][4 + n], 0, 0, 0);
;     __builtin_amdgcn_sched_barrier(0);
;   };
;     ...
;   stage(0, 0);
;   stage(1, 1);
;   stage(2, 2);
;   for (int it = 0; it < NK / 4 - 1; ++it) {
;     const int t = it * 4;
;     BIG_SYNC(2 * NG); kstep(t, 0, 3, true);
;     BIG_SYNC(2 * NG); kstep(t + 1, 1, 0, true);
;     BIG_SYNC(2 * NG); kstep(t + 2, 2, 1, true);
;     BIG_SYNC(2 * NG); kstep(t + 3, 3, 2, true);
;   }
;   BIG_SYNC(2 * NG); kstep(NK - 4, 0, 3, true);
;   BIG_SYNC(2 * NG); kstep(NK - 3, 1, 0, false);
;   BIG_SYNC(NG);     kstep(NK - 2, 2, 0, false);
;   BIG_SYNC(0);      kstep(NK - 1, 3, 0, false);
; template <int MODE, int NSUB>
; __device__ __forceinline__ void epilogue(const Params& p, int layer, f32x4 (&acc)[4][NSUB], int tm, int tn, int g,
;                                          const float* s_rstd, const int tid_in) {
;     ...
;   } else if constexpr (MODE == EPI_UP) {
;     const int woff = widen_off(fq);
; #pragma unroll
;     for (int n = 0; n < NSUB; ++n) {
;       const int nl = wc * (NSUB * 16) + n * 16 + fr;
;       const int t = tn * (NSUB * 32) + nl;
	ds_read_b128 v[134:137], v167
	ds_read_b128 v[138:141], v167 offset:1024
	ds_read_b128 v[154:157], v167 offset:2048
	ds_read_b128 v[158:161], v167 offset:3072
	ds_read_b128 v[162:165], v168
	ds_read_b128 v[166:169], v169
	ds_read_b128 v[216:219], v170
	ds_read_b128 v[220:223], v172
	s_waitcnt lgkmcnt(0)
	v_mfma_f32_16x16x32_bf16 v[124:127], v[134:137], v[162:165], v[124:127]
	v_mfma_f32_16x16x32_bf16 v[120:123], v[134:137], v[166:169], v[120:123]
	v_mfma_f32_16x16x32_bf16 v[116:119], v[134:137], v[216:219], v[116:119]
	v_mfma_f32_16x16x32_bf16 v[112:115], v[134:137], v[220:223], v[112:115]
	v_mfma_f32_16x16x32_bf16 v[224:227], v[138:141], v[162:165], v[108:111]
	v_mfma_f32_16x16x32_bf16 v[104:107], v[138:141], v[166:169], v[104:107]
	v_mfma_f32_16x16x32_bf16 v[100:103], v[138:141], v[216:219], v[100:103]
	v_mfma_f32_16x16x32_bf16 v[96:99], v[138:141], v[220:223], v[96:99]
	v_mfma_f32_16x16x32_bf16 v[228:231], v[154:157], v[162:165], v[88:91]
	v_mfma_f32_16x16x32_bf16 v[232:235], v[154:157], v[166:169], v[76:79]
	v_mfma_f32_16x16x32_bf16 v[68:71], v[154:157], v[216:219], v[68:71]
	v_mfma_f32_16x16x32_bf16 v[64:67], v[154:157], v[220:223], v[64:67]
	v_mfma_f32_16x16x32_bf16 v[44:47], v[158:161], v[162:165], v[44:47]
	v_mfma_f32_16x16x32_bf16 v[40:43], v[158:161], v[166:169], v[40:43]
	v_mfma_f32_16x16x32_bf16 v[36:39], v[158:161], v[216:219], v[36:39]
	v_mfma_f32_16x16x32_bf16 v[32:35], v[158:161], v[220:223], v[32:35]
	ds_read_b128 v[76:79], v173
	ds_read_b128 v[88:91], v174
	s_waitcnt lgkmcnt(0)
	v_mfma_f32_16x16x32_bf16 v[162:165], v[134:137], v[76:79], v[92:95]
	s_nop 2
	ds_read_b128 v[92:95], v178
	v_mfma_f32_16x16x32_bf16 v[166:169], v[134:137], v[88:91], v[84:87]
	s_nop 2
	ds_read_b128 v[84:87], v175
	s_waitcnt lgkmcnt(0)
	v_mfma_f32_16x16x32_bf16 v[172:175], v[134:137], v[84:87], v[80:83]
	v_mfma_f32_16x16x32_bf16 v[134:137], v[134:137], v[92:95], v[72:75]
	v_mfma_f32_16x16x32_bf16 v[216:219], v[138:141], v[76:79], v[60:63]
	v_mfma_f32_16x16x32_bf16 v[220:223], v[138:141], v[88:91], v[56:59]
	v_mfma_f32_16x16x32_bf16 v[52:55], v[138:141], v[84:87], v[52:55]
	v_mfma_f32_16x16x32_bf16 v[48:51], v[138:141], v[92:95], v[48:51]
	v_mfma_f32_16x16x32_bf16 v[138:141], v[154:157], v[76:79], v[28:31]
	v_mfma_f32_16x16x32_bf16 v[236:239], v[154:157], v[88:91], v[24:27]
	v_mfma_f32_16x16x32_bf16 v[20:23], v[154:157], v[84:87], v[20:23]
	v_mfma_f32_16x16x32_bf16 v[16:19], v[154:157], v[92:95], v[16:19]
	v_mfma_f32_16x16x32_bf16 v[154:157], v[158:161], v[76:79], v[12:15]
	v_mfma_f32_16x16x32_bf16 v[240:243], v[158:161], v[88:91], v[8:11]
	v_mfma_f32_16x16x32_bf16 v[244:247], v[158:161], v[84:87], v[4:7]
	v_mfma_f32_16x16x32_bf16 v[0:3], v[158:161], v[92:95], v[0:3]
	s_waitcnt vmcnt(0)
	s_barrier
	s_nop 0
	ds_read_b128 v[4:7], v176
	ds_read_b128 v[8:11], v176 offset:1024
	ds_read_b128 v[158:161], v176 offset:2048
	ds_read_b128 v[248:251], v176 offset:3072
	ds_read_b128 v[12:15], v179
	ds_read_b128 v[24:27], v180
	ds_read_b128 v[28:31], v181
	ds_read_b128 v[56:59], v182
	s_waitcnt lgkmcnt(0)
	v_mfma_f32_16x16x32_bf16 v[124:127], v[4:7], v[12:15], v[124:127]
	v_mfma_f32_16x16x32_bf16 v[108:111], v[4:7], v[24:27], v[120:123]
	v_mfma_f32_16x16x32_bf16 v[92:95], v[4:7], v[28:31], v[116:119]
	v_mfma_f32_16x16x32_bf16 v[76:79], v[4:7], v[56:59], v[112:115]
	v_mfma_f32_16x16x32_bf16 v[112:115], v[8:11], v[12:15], v[224:227]
	v_mfma_f32_16x16x32_bf16 v[104:107], v[8:11], v[24:27], v[104:107]
	v_mfma_f32_16x16x32_bf16 v[88:91], v[8:11], v[28:31], v[100:103]
	v_mfma_f32_16x16x32_bf16 v[72:75], v[8:11], v[56:59], v[96:99]
	v_mfma_f32_16x16x32_bf16 v[120:123], v[158:161], v[12:15], v[228:231]
	v_mfma_f32_16x16x32_bf16 v[100:103], v[158:161], v[24:27], v[232:235]
	v_mfma_f32_16x16x32_bf16 v[84:87], v[158:161], v[28:31], v[68:71]
	v_mfma_f32_16x16x32_bf16 v[68:71], v[158:161], v[56:59], v[64:67]
	v_mfma_f32_16x16x32_bf16 v[178:181], v[248:251], v[12:15], v[44:47]
	v_mfma_f32_16x16x32_bf16 v[96:99], v[248:251], v[24:27], v[40:43]
	v_mfma_f32_16x16x32_bf16 v[80:83], v[248:251], v[28:31], v[36:39]
	v_mfma_f32_16x16x32_bf16 v[64:67], v[248:251], v[56:59], v[32:35]
	s_nop 2
	ds_read_b128 v[32:35], v142
	ds_read_b128 v[116:119], v143
	s_waitcnt lgkmcnt(0)
	v_mfma_f32_16x16x32_bf16 v[60:63], v[4:7], v[32:35], v[162:165]
	s_nop 2
	ds_read_b128 v[162:165], v144
	ds_read_b128 v[142:145], v145
	v_mfma_f32_16x16x32_bf16 v[44:47], v[4:7], v[116:119], v[166:169]
	s_waitcnt lgkmcnt(0)
	v_mfma_f32_16x16x32_bf16 v[28:31], v[4:7], v[162:165], v[172:175]
	v_mfma_f32_16x16x32_bf16 v[12:15], v[4:7], v[142:145], v[134:137]
	v_mfma_f32_16x16x32_bf16 v[56:59], v[8:11], v[32:35], v[216:219]
	v_mfma_f32_16x16x32_bf16 v[40:43], v[8:11], v[116:119], v[220:223]
	v_mfma_f32_16x16x32_bf16 v[24:27], v[8:11], v[162:165], v[52:55]
	v_mfma_f32_16x16x32_bf16 v[8:11], v[8:11], v[142:145], v[48:51]
	v_mfma_f32_16x16x32_bf16 v[52:55], v[158:161], v[32:35], v[138:141]
	v_mfma_f32_16x16x32_bf16 v[36:39], v[158:161], v[116:119], v[236:239]
	v_mfma_f32_16x16x32_bf16 v[20:23], v[158:161], v[162:165], v[20:23]
	v_mfma_f32_16x16x32_bf16 v[4:7], v[158:161], v[142:145], v[16:19]
	v_mfma_f32_16x16x32_bf16 v[48:51], v[248:251], v[32:35], v[154:157]
	v_mfma_f32_16x16x32_bf16 v[32:35], v[248:251], v[116:119], v[240:243]
	v_mfma_f32_16x16x32_bf16 v[16:19], v[248:251], v[162:165], v[244:247]
	v_mfma_f32_16x16x32_bf16 v[0:3], v[248:251], v[142:145], v[0:3]
	v_mov_b32_e32 v116, v215
	s_lshl_b32 s10, s10, 8
	v_and_b32_e32 v117, 16, v116
	v_lshrrev_b32_e32 v118, 2, v116
	v_and_or_b32 v136, v118, 8, v117
	v_lshlrev_b32_e32 v117, 1, v116
	v_and_b32_e32 v119, 15, v116
	v_and_b32_e32 v117, 0x80, v117
	v_lshl_or_b32 v134, s15, 8, v117
	v_or_b32_e32 v117, v117, v119
	v_ashrrev_i32_e32 v116, 1, v116
	v_lshlrev_b32_e32 v118, 2, v117
	v_and_b32_e32 v116, 0xffffffc0, v116
	v_add3_u32 v135, s10, v150, v116
	v_or_b32_e32 v116, 0x20000, v118
	ds_read_b32 v137, v116
	v_lshlrev_b32_e32 v152, 6, v119
	v_or_b32_e32 v119, 0x20040, v118
	v_readlane_b32 s64, v252, 4
	ds_read_b32 v119, v119
	s_waitcnt lgkmcnt(0)
; __device__ __forceinline__ int widen_off(int fq) { return ((fq & 1) << 4) + ((fq >> 1) << 3); }
; template <int MODE, int NSUB>
; __device__ __forceinline__ void epilogue(const Params& p, int layer, f32x4 (&acc)[4][NSUB], int tm, int tn, int g,
;                                          const float* s_rstd, const int tid_in) {
;     ...
;   } else if constexpr (MODE == EPI_UP) {
;     const int woff = widen_off(fq);
; #pragma unroll
;     for (int n = 0; n < NSUB; ++n) {
;       const int nl = wc * (NSUB * 16) + n * 16 + fr;
;       const int t = tn * (NSUB * 32) + nl;
;       const float rs = s_rstd[nl];
; #pragma unroll
;       for (int mp = 0; mp < 2; ++mp) {
;         bf16x4 pk[2];
; #pragma unroll
;         for (int h2 = 0; h2 < 2; ++h2) {
;           const int m = mp * 2 + h2;
;           float v[4];
; #pragma unroll
;           for (int j = 0; j < 4; ++j) {
;             float a = fmaxf(acc[m][n][j] * rs, 0.f);
;             v[j] = a * a;
;           }
;           pk[h2] = pack4(v[0], v[1], v[2], v[3]);
;         }
;         const int f = tm * 128 + wr * 64 + mp * 32 + woff;
;         __builtin_nontemporal_store(widen_pair(pk[0], pk[1]), reinterpret_cast<u32x4*>(p.hm + blk(t, f, 128)));
;       }
;     }
	v_mul_f32_e32 v116, v124, v137
	v_mul_f32_e32 v117, v125, v137
	v_mul_f32_e32 v124, v126, v137
	v_mul_f32_e32 v125, v127, v137
	v_mul_f32_e32 v112, v112, v137
	v_mul_f32_e32 v113, v113, v137
	v_max_f32_e32 v124, 0, v124
	v_max_f32_e32 v125, 0, v125
	v_max_f32_e32 v112, 0, v112
	v_max_f32_e32 v113, 0, v113
	v_mul_f32_e32 v114, v114, v137
	v_mul_f32_e32 v115, v115, v137
	v_pk_mul_f32 v[126:127], v[124:125], v[124:125]
	v_pk_mul_f32 v[112:113], v[112:113], v[112:113]
	v_max_f32_e32 v114, 0, v114
	v_max_f32_e32 v115, 0, v115
	v_cvt_pk_bf16_f32 v125, v126, v127
	v_pk_mul_f32 v[114:115], v[114:115], v[114:115]
	v_cvt_pk_bf16_f32 v126, v112, v113
	v_ashrrev_i32_e32 v112, 5, v135
	v_cvt_pk_bf16_f32 v127, v114, v115
	v_add_u32_e32 v114, v112, v134
	v_ashrrev_i32_e32 v115, 31, v114
	v_lshlrev_b64 v[112:113], 13, v[114:115]
	v_mul_f32_e32 v115, v120, v137
	v_max_f32_e32 v120, 0, v115
	v_mul_f32_e32 v115, v121, v137
	v_max_f32_e32 v121, 0, v115
	v_mul_f32_e32 v115, v122, v137
	v_max_f32_e32 v116, 0, v116
	v_max_f32_e32 v117, 0, v117
	v_max_f32_e32 v122, 0, v115
	v_mul_f32_e32 v115, v123, v137
	v_pk_mul_f32 v[116:117], v[116:117], v[116:117]
	v_readlane_b32 s78, v252, 18
	v_readlane_b32 s79, v252, 19
	v_max_f32_e32 v123, 0, v115
	v_cvt_pk_bf16_f32 v124, v116, v117
	v_lshl_add_u64 v[116:117], s[78:79], 0, v[112:113]
	v_pk_mul_f32 v[120:121], v[120:121], v[120:121]
	v_pk_mul_f32 v[122:123], v[122:123], v[122:123]
	v_mul_f32_e32 v115, v178, v137
	v_lshl_add_u64 v[134:135], v[116:117], 0, v[152:153]
	v_lshlrev_b32_e32 v112, 1, v136
	v_mov_b32_e32 v113, v153
	v_cvt_pk_bf16_f32 v120, v120, v121
	v_cvt_pk_bf16_f32 v121, v122, v123
	v_max_f32_e32 v122, 0, v115
	v_mul_f32_e32 v115, v179, v137
	v_permlane16_swap_b32_e32 v124, v126
	v_permlane16_swap_b32_e32 v125, v127
	v_lshl_add_u64 v[134:135], v[134:135], 0, v[112:113]
	v_max_f32_e32 v123, 0, v115
	v_mul_f32_e32 v115, v180, v137
	global_store_dwordx4 v[134:135], v[124:127], off nt
	v_add_u32_e32 v114, 1, v114
	v_mul_f32_e32 v108, v108, v119
	v_max_f32_e32 v124, 0, v115
	v_mul_f32_e32 v115, v181, v137
	v_mul_f32_e32 v109, v109, v119
	v_mul_f32_e32 v110, v110, v119
	v_mul_f32_e32 v111, v111, v119
	v_mul_f32_e32 v104, v104, v119
	v_mul_f32_e32 v105, v105, v119
	v_max_f32_e32 v125, 0, v115
	v_ashrrev_i32_e32 v115, 31, v114
	v_max_f32_e32 v108, 0, v108
	v_max_f32_e32 v109, 0, v109
	v_max_f32_e32 v110, 0, v110
	v_max_f32_e32 v111, 0, v111
	v_max_f32_e32 v104, 0, v104
	v_max_f32_e32 v105, 0, v105
	v_mul_f32_e32 v100, v100, v119
	v_mul_f32_e32 v101, v101, v119
	v_mul_f32_e32 v102, v102, v119
	v_mul_f32_e32 v103, v103, v119
	v_mul_f32_e32 v96, v96, v119
	v_mul_f32_e32 v97, v97, v119
	v_mul_f32_e32 v98, v98, v119
	v_mul_f32_e32 v99, v99, v119
	v_lshlrev_b64 v[114:115], 13, v[114:115]
	v_pk_mul_f32 v[108:109], v[108:109], v[108:109]
	v_pk_mul_f32 v[110:111], v[110:111], v[110:111]
	v_pk_mul_f32 v[104:105], v[104:105], v[104:105]
	v_max_f32_e32 v100, 0, v100
	v_max_f32_e32 v101, 0, v101
	v_max_f32_e32 v102, 0, v102
	v_max_f32_e32 v103, 0, v103
	v_max_f32_e32 v96, 0, v96
	v_max_f32_e32 v97, 0, v97
	v_max_f32_e32 v98, 0, v98
	v_max_f32_e32 v99, 0, v99
	v_lshl_add_u64 v[114:115], s[78:79], 0, v[114:115]
	v_cvt_pk_bf16_f32 v108, v108, v109
	v_cvt_pk_bf16_f32 v109, v110, v111
	v_cvt_pk_bf16_f32 v110, v104, v105
	v_or_b32_e32 v104, 0x400, v152
	v_mov_b32_e32 v105, v153
	v_pk_mul_f32 v[100:101], v[100:101], v[100:101]
	v_pk_mul_f32 v[102:103], v[102:103], v[102:103]
	v_pk_mul_f32 v[96:97], v[96:97], v[96:97]
	v_pk_mul_f32 v[98:99], v[98:99], v[98:99]
	v_cvt_pk_bf16_f32 v100, v100, v101
	v_cvt_pk_bf16_f32 v101, v102, v103
	v_cvt_pk_bf16_f32 v102, v96, v97
	v_cvt_pk_bf16_f32 v103, v98, v99
	v_lshl_add_u64 v[96:97], v[114:115], 0, v[104:105]
	v_permlane16_swap_b32_e32 v100, v102
	v_permlane16_swap_b32_e32 v101, v103
	v_lshl_add_u64 v[96:97], v[96:97], 0, v[112:113]
	global_store_dwordx4 v[96:97], v[100:103], off nt
	v_or_b32_e32 v96, 0x20080, v118
	ds_read_b32 v96, v96
	v_mul_f32_e32 v106, v106, v119
	v_mul_f32_e32 v107, v107, v119
	v_pk_mul_f32 v[122:123], v[122:123], v[122:123]
	v_pk_mul_f32 v[124:125], v[124:125], v[124:125]
	s_waitcnt lgkmcnt(0)
	v_mul_f32_e32 v92, v92, v96
	v_mul_f32_e32 v93, v93, v96
	v_mul_f32_e32 v94, v94, v96
	v_mul_f32_e32 v95, v95, v96
	v_mul_f32_e32 v88, v88, v96
	v_mul_f32_e32 v89, v89, v96
	v_max_f32_e32 v92, 0, v92
	v_max_f32_e32 v93, 0, v93
	v_max_f32_e32 v94, 0, v94
	v_max_f32_e32 v95, 0, v95
	v_max_f32_e32 v88, 0, v88
	v_max_f32_e32 v89, 0, v89
	v_mul_f32_e32 v84, v84, v96
	v_mul_f32_e32 v85, v85, v96
	v_mul_f32_e32 v86, v86, v96
	v_mul_f32_e32 v87, v87, v96
	v_mul_f32_e32 v80, v80, v96
	v_mul_f32_e32 v81, v81, v96
	v_mul_f32_e32 v82, v82, v96
	v_mul_f32_e32 v83, v83, v96
	v_pk_mul_f32 v[92:93], v[92:93], v[92:93]
	v_pk_mul_f32 v[94:95], v[94:95], v[94:95]
	v_pk_mul_f32 v[88:89], v[88:89], v[88:89]
	v_max_f32_e32 v84, 0, v84
	v_max_f32_e32 v85, 0, v85
	v_max_f32_e32 v86, 0, v86
	v_max_f32_e32 v87, 0, v87
	v_max_f32_e32 v80, 0, v80
	v_max_f32_e32 v81, 0, v81
	v_max_f32_e32 v82, 0, v82
	v_max_f32_e32 v83, 0, v83
	v_cvt_pk_bf16_f32 v92, v92, v93
	v_cvt_pk_bf16_f32 v93, v94, v95
	v_cvt_pk_bf16_f32 v94, v88, v89
	v_or_b32_e32 v88, 0x800, v152
	v_mov_b32_e32 v89, v153
	v_pk_mul_f32 v[84:85], v[84:85], v[84:85]
	v_pk_mul_f32 v[86:87], v[86:87], v[86:87]
	v_pk_mul_f32 v[80:81], v[80:81], v[80:81]
	v_pk_mul_f32 v[82:83], v[82:83], v[82:83]
	v_cvt_pk_bf16_f32 v84, v84, v85
	v_cvt_pk_bf16_f32 v85, v86, v87
	v_cvt_pk_bf16_f32 v86, v80, v81
	v_cvt_pk_bf16_f32 v87, v82, v83
	v_lshl_add_u64 v[80:81], v[114:115], 0, v[88:89]
	v_permlane16_swap_b32_e32 v84, v86
	v_permlane16_swap_b32_e32 v85, v87
	v_lshl_add_u64 v[80:81], v[80:81], 0, v[112:113]
	global_store_dwordx4 v[80:81], v[84:87], off nt
	v_or_b32_e32 v80, 0x200c0, v118
	ds_read_b32 v80, v80
	v_mul_f32_e32 v90, v90, v96
	v_mul_f32_e32 v91, v91, v96
	v_max_f32_e32 v106, 0, v106
	v_max_f32_e32 v107, 0, v107
	s_waitcnt lgkmcnt(0)
; __device__ __forceinline__ int widen_off(int fq) { return ((fq & 1) << 4) + ((fq >> 1) << 3); }
; template <int MODE, int NSUB>
; __device__ __forceinline__ void epilogue(const Params& p, int layer, f32x4 (&acc)[4][NSUB], int tm, int tn, int g,
;                                          const float* s_rstd, const int tid_in) {
;     ...
;   } else if constexpr (MODE == EPI_UP) {
;     const int woff = widen_off(fq);
; #pragma unroll
;     for (int n = 0; n < NSUB; ++n) {
;       const int nl = wc * (NSUB * 16) + n * 16 + fr;
;       const int t = tn * (NSUB * 32) + nl;
;       const float rs = s_rstd[nl];
; #pragma unroll
;       for (int mp = 0; mp < 2; ++mp) {
;         bf16x4 pk[2];
; #pragma unroll
;         for (int h2 = 0; h2 < 2; ++h2) {
;           const int m = mp * 2 + h2;
;           float v[4];
; #pragma unroll
;           for (int j = 0; j < 4; ++j) {
;             float a = fmaxf(acc[m][n][j] * rs, 0.f);
;             v[j] = a * a;
;           }
;           pk[h2] = pack4(v[0], v[1], v[2], v[3]);
;         }
;         const int f = tm * 128 + wr * 64 + mp * 32 + woff;
;         __builtin_nontemporal_store(widen_pair(pk[0], pk[1]), reinterpret_cast<u32x4*>(p.hm + blk(t, f, 128)));
;       }
;     }
	v_mul_f32_e32 v76, v76, v80
	v_mul_f32_e32 v77, v77, v80
	v_mul_f32_e32 v78, v78, v80
	v_mul_f32_e32 v79, v79, v80
	v_mul_f32_e32 v72, v72, v80
	v_mul_f32_e32 v73, v73, v80
	v_max_f32_e32 v76, 0, v76
	v_max_f32_e32 v77, 0, v77
	v_max_f32_e32 v78, 0, v78
	v_max_f32_e32 v79, 0, v79
	v_max_f32_e32 v72, 0, v72
	v_max_f32_e32 v73, 0, v73
	v_mul_f32_e32 v68, v68, v80
	v_mul_f32_e32 v69, v69, v80
	v_mul_f32_e32 v70, v70, v80
	v_mul_f32_e32 v71, v71, v80
	v_mul_f32_e32 v64, v64, v80
	v_mul_f32_e32 v65, v65, v80
	v_mul_f32_e32 v66, v66, v80
	v_mul_f32_e32 v67, v67, v80
	v_pk_mul_f32 v[76:77], v[76:77], v[76:77]
	v_pk_mul_f32 v[78:79], v[78:79], v[78:79]
	v_pk_mul_f32 v[72:73], v[72:73], v[72:73]
	v_max_f32_e32 v68, 0, v68
	v_max_f32_e32 v69, 0, v69
	v_max_f32_e32 v70, 0, v70
	v_max_f32_e32 v71, 0, v71
	v_max_f32_e32 v64, 0, v64
	v_max_f32_e32 v65, 0, v65
	v_max_f32_e32 v66, 0, v66
	v_max_f32_e32 v67, 0, v67
	v_cvt_pk_bf16_f32 v76, v76, v77
	v_cvt_pk_bf16_f32 v77, v78, v79
	v_cvt_pk_bf16_f32 v78, v72, v73
	v_or_b32_e32 v72, 0xc00, v152
	v_mov_b32_e32 v73, v153
	v_pk_mul_f32 v[68:69], v[68:69], v[68:69]
	v_pk_mul_f32 v[70:71], v[70:71], v[70:71]
	v_pk_mul_f32 v[64:65], v[64:65], v[64:65]
	v_pk_mul_f32 v[66:67], v[66:67], v[66:67]
	v_cvt_pk_bf16_f32 v68, v68, v69
	v_cvt_pk_bf16_f32 v69, v70, v71
	v_cvt_pk_bf16_f32 v70, v64, v65
	v_cvt_pk_bf16_f32 v71, v66, v67
	v_lshl_add_u64 v[64:65], v[114:115], 0, v[72:73]
	v_permlane16_swap_b32_e32 v68, v70
	v_permlane16_swap_b32_e32 v69, v71
	v_lshl_add_u64 v[64:65], v[64:65], 0, v[112:113]
	global_store_dwordx4 v[64:65], v[68:71], off nt
	v_or_b32_e32 v64, 0x20100, v118
	ds_read_b32 v64, v64
	v_mul_f32_e32 v74, v74, v80
	v_mul_f32_e32 v75, v75, v80
	v_max_f32_e32 v90, 0, v90
	v_max_f32_e32 v91, 0, v91
	s_waitcnt lgkmcnt(0)
	v_mul_f32_e32 v60, v60, v64
	v_mul_f32_e32 v61, v61, v64
	v_mul_f32_e32 v62, v62, v64
	v_mul_f32_e32 v63, v63, v64
	v_mul_f32_e32 v56, v56, v64
	v_mul_f32_e32 v57, v57, v64
	v_max_f32_e32 v60, 0, v60
	v_max_f32_e32 v61, 0, v61
	v_max_f32_e32 v62, 0, v62
	v_max_f32_e32 v63, 0, v63
	v_max_f32_e32 v56, 0, v56
	v_max_f32_e32 v57, 0, v57
	v_mul_f32_e32 v52, v52, v64
	v_mul_f32_e32 v53, v53, v64
	v_mul_f32_e32 v54, v54, v64
	v_mul_f32_e32 v55, v55, v64
	v_mul_f32_e32 v48, v48, v64
	v_mul_f32_e32 v49, v49, v64
	v_mul_f32_e32 v50, v50, v64
	v_mul_f32_e32 v51, v51, v64
	v_pk_mul_f32 v[60:61], v[60:61], v[60:61]
	v_pk_mul_f32 v[62:63], v[62:63], v[62:63]
	v_pk_mul_f32 v[56:57], v[56:57], v[56:57]
	v_max_f32_e32 v52, 0, v52
	v_max_f32_e32 v53, 0, v53
	v_max_f32_e32 v54, 0, v54
	v_max_f32_e32 v55, 0, v55
	v_max_f32_e32 v48, 0, v48
	v_max_f32_e32 v49, 0, v49
	v_max_f32_e32 v50, 0, v50
	v_max_f32_e32 v51, 0, v51
	v_cvt_pk_bf16_f32 v60, v60, v61
	v_cvt_pk_bf16_f32 v61, v62, v63
	v_cvt_pk_bf16_f32 v62, v56, v57
	v_or_b32_e32 v56, 0x1000, v152
	v_mov_b32_e32 v57, v153
	v_pk_mul_f32 v[52:53], v[52:53], v[52:53]
	v_pk_mul_f32 v[54:55], v[54:55], v[54:55]
	v_pk_mul_f32 v[48:49], v[48:49], v[48:49]
	v_pk_mul_f32 v[50:51], v[50:51], v[50:51]
	v_cvt_pk_bf16_f32 v52, v52, v53
	v_cvt_pk_bf16_f32 v53, v54, v55
	v_cvt_pk_bf16_f32 v54, v48, v49
	v_cvt_pk_bf16_f32 v55, v50, v51
	v_lshl_add_u64 v[48:49], v[114:115], 0, v[56:57]
	v_permlane16_swap_b32_e32 v52, v54
	v_permlane16_swap_b32_e32 v53, v55
	v_lshl_add_u64 v[48:49], v[48:49], 0, v[112:113]
	global_store_dwordx4 v[48:49], v[52:55], off nt
	v_or_b32_e32 v48, 0x20140, v118
	ds_read_b32 v48, v48
	v_mul_f32_e32 v58, v58, v64
	v_mul_f32_e32 v59, v59, v64
	v_max_f32_e32 v74, 0, v74
	v_max_f32_e32 v75, 0, v75
	s_waitcnt lgkmcnt(0)
	v_mul_f32_e32 v44, v44, v48
	v_mul_f32_e32 v45, v45, v48
	v_mul_f32_e32 v46, v46, v48
	v_mul_f32_e32 v47, v47, v48
	v_mul_f32_e32 v40, v40, v48
	v_mul_f32_e32 v41, v41, v48
	v_max_f32_e32 v44, 0, v44
	v_max_f32_e32 v45, 0, v45
	v_max_f32_e32 v46, 0, v46
	v_max_f32_e32 v47, 0, v47
	v_max_f32_e32 v40, 0, v40
	v_max_f32_e32 v41, 0, v41
	v_mul_f32_e32 v36, v36, v48
	v_mul_f32_e32 v37, v37, v48
	v_mul_f32_e32 v38, v38, v48
	v_mul_f32_e32 v39, v39, v48
	v_mul_f32_e32 v32, v32, v48
	v_mul_f32_e32 v33, v33, v48
	v_mul_f32_e32 v34, v34, v48
	v_mul_f32_e32 v35, v35, v48
	v_pk_mul_f32 v[44:45], v[44:45], v[44:45]
	v_pk_mul_f32 v[46:47], v[46:47], v[46:47]
	v_pk_mul_f32 v[40:41], v[40:41], v[40:41]
	v_max_f32_e32 v36, 0, v36
	v_max_f32_e32 v37, 0, v37
	v_max_f32_e32 v38, 0, v38
	v_max_f32_e32 v39, 0, v39
	v_max_f32_e32 v32, 0, v32
	v_max_f32_e32 v33, 0, v33
	v_max_f32_e32 v34, 0, v34
	v_max_f32_e32 v35, 0, v35
	v_cvt_pk_bf16_f32 v44, v44, v45
	v_cvt_pk_bf16_f32 v45, v46, v47
	v_cvt_pk_bf16_f32 v46, v40, v41
	v_or_b32_e32 v40, 0x1400, v152
	v_mov_b32_e32 v41, v153
	v_pk_mul_f32 v[36:37], v[36:37], v[36:37]
	v_pk_mul_f32 v[38:39], v[38:39], v[38:39]
	v_pk_mul_f32 v[32:33], v[32:33], v[32:33]
	v_pk_mul_f32 v[34:35], v[34:35], v[34:35]
	v_cvt_pk_bf16_f32 v36, v36, v37
	v_cvt_pk_bf16_f32 v37, v38, v39
	v_cvt_pk_bf16_f32 v38, v32, v33
	v_cvt_pk_bf16_f32 v39, v34, v35
	v_lshl_add_u64 v[32:33], v[114:115], 0, v[40:41]
	v_permlane16_swap_b32_e32 v36, v38
	v_permlane16_swap_b32_e32 v37, v39
	v_lshl_add_u64 v[32:33], v[32:33], 0, v[112:113]
	global_store_dwordx4 v[32:33], v[36:39], off nt
	v_or_b32_e32 v32, 0x20180, v118
	ds_read_b32 v32, v32
	v_mul_f32_e32 v42, v42, v48
	v_mul_f32_e32 v43, v43, v48
	v_max_f32_e32 v58, 0, v58
	v_max_f32_e32 v59, 0, v59
	s_waitcnt lgkmcnt(0)
; __device__ __forceinline__ int widen_off(int fq) { return ((fq & 1) << 4) + ((fq >> 1) << 3); }
; template <int MODE, int NSUB>
; __device__ __forceinline__ void epilogue(const Params& p, int layer, f32x4 (&acc)[4][NSUB], int tm, int tn, int g,
;                                          const float* s_rstd, const int tid_in) {
;     ...
;   } else if constexpr (MODE == EPI_UP) {
;     const int woff = widen_off(fq);
; #pragma unroll
;     for (int n = 0; n < NSUB; ++n) {
;       const int nl = wc * (NSUB * 16) + n * 16 + fr;
;       const int t = tn * (NSUB * 32) + nl;
;       const float rs = s_rstd[nl];
; #pragma unroll
;       for (int mp = 0; mp < 2; ++mp) {
;         bf16x4 pk[2];
; #pragma unroll
;         for (int h2 = 0; h2 < 2; ++h2) {
;           const int m = mp * 2 + h2;
;           float v[4];
; #pragma unroll
;           for (int j = 0; j < 4; ++j) {
;             float a = fmaxf(acc[m][n][j] * rs, 0.f);
;             v[j] = a * a;
;           }
;           pk[h2] = pack4(v[0], v[1], v[2], v[3]);
;         }
;         const int f = tm * 128 + wr * 64 + mp * 32 + woff;
;         __builtin_nontemporal_store(widen_pair(pk[0], pk[1]), reinterpret_cast<u32x4*>(p.hm + blk(t, f, 128)));
;       }
;     }
; __global__ void __launch_bounds__(NTHREADS) fwd_megakernel(Params p) {
;     ...
;           for (int id = rvid; id < 16 * CHUNK_TT; id += Greal) {
;             int ftb, ttl;
;             tile_decode_fb(id, 16, 4, ftb, ttl);
;             compute_rstd(p.part, 16, 1.0f / 1024.f, (chunk * CHUNK_TT + ttl) * 256, 256, s_rstd_b, tid_full);
;             f32x4 acc[4][8];
;             gemm_big<32>(acc, W + (long)ftb * 256 * 1024, 128 * 1024, p.xb + (long)(chunk * CHUNK_TT + ttl) * 256 * 1024, 128 * 1024, smem_all, tid_full);
;             const int ft = ftb * 2 + (widf >> 2);
;             epilogue<EPI_UP, 8>(p, l, acc, ft, ttl, 0, s_rstd_b, tid_e);
;             __syncthreads();
;           }
	v_mul_f32_e32 v28, v28, v32
	v_mul_f32_e32 v29, v29, v32
	v_mul_f32_e32 v30, v30, v32
	v_mul_f32_e32 v31, v31, v32
	v_mul_f32_e32 v24, v24, v32
	v_mul_f32_e32 v25, v25, v32
	v_max_f32_e32 v28, 0, v28
	v_max_f32_e32 v29, 0, v29
	v_max_f32_e32 v30, 0, v30
	v_max_f32_e32 v31, 0, v31
	v_max_f32_e32 v24, 0, v24
	v_max_f32_e32 v25, 0, v25
	v_mul_f32_e32 v20, v20, v32
	v_mul_f32_e32 v21, v21, v32
	v_mul_f32_e32 v22, v22, v32
	v_mul_f32_e32 v23, v23, v32
	v_mul_f32_e32 v16, v16, v32
	v_mul_f32_e32 v17, v17, v32
	v_mul_f32_e32 v18, v18, v32
	v_mul_f32_e32 v19, v19, v32
	v_pk_mul_f32 v[28:29], v[28:29], v[28:29]
	v_pk_mul_f32 v[30:31], v[30:31], v[30:31]
	v_pk_mul_f32 v[24:25], v[24:25], v[24:25]
	v_max_f32_e32 v20, 0, v20
	v_max_f32_e32 v21, 0, v21
	v_max_f32_e32 v22, 0, v22
	v_max_f32_e32 v23, 0, v23
	v_max_f32_e32 v16, 0, v16
	v_max_f32_e32 v17, 0, v17
	v_max_f32_e32 v18, 0, v18
	v_max_f32_e32 v19, 0, v19
	v_cvt_pk_bf16_f32 v28, v28, v29
	v_cvt_pk_bf16_f32 v29, v30, v31
	v_cvt_pk_bf16_f32 v30, v24, v25
	v_or_b32_e32 v24, 0x1800, v152
	v_mov_b32_e32 v25, v153
	v_pk_mul_f32 v[20:21], v[20:21], v[20:21]
	v_pk_mul_f32 v[22:23], v[22:23], v[22:23]
	v_pk_mul_f32 v[16:17], v[16:17], v[16:17]
	v_pk_mul_f32 v[18:19], v[18:19], v[18:19]
	v_cvt_pk_bf16_f32 v20, v20, v21
	v_cvt_pk_bf16_f32 v21, v22, v23
	v_cvt_pk_bf16_f32 v22, v16, v17
	v_cvt_pk_bf16_f32 v23, v18, v19
	v_lshl_add_u64 v[16:17], v[114:115], 0, v[24:25]
	v_permlane16_swap_b32_e32 v20, v22
	v_permlane16_swap_b32_e32 v21, v23
	v_lshl_add_u64 v[16:17], v[16:17], 0, v[112:113]
	global_store_dwordx4 v[16:17], v[20:23], off nt
	v_or_b32_e32 v16, 0x201c0, v118
	ds_read_b32 v16, v16
	v_mul_f32_e32 v26, v26, v32
	v_mul_f32_e32 v27, v27, v32
	v_max_f32_e32 v42, 0, v42
	v_max_f32_e32 v43, 0, v43
	s_waitcnt lgkmcnt(0)
	v_mul_f32_e32 v12, v12, v16
	v_mul_f32_e32 v13, v13, v16
	v_mul_f32_e32 v14, v14, v16
	v_mul_f32_e32 v15, v15, v16
	v_mul_f32_e32 v8, v8, v16
	v_mul_f32_e32 v9, v9, v16
	v_mul_f32_e32 v10, v10, v16
	v_mul_f32_e32 v11, v11, v16
	v_mul_f32_e32 v4, v4, v16
	v_mul_f32_e32 v5, v5, v16
	v_mul_f32_e32 v6, v6, v16
	v_mul_f32_e32 v7, v7, v16
	v_mul_f32_e32 v0, v0, v16
	v_mul_f32_e32 v1, v1, v16
	v_mul_f32_e32 v2, v2, v16
	v_mul_f32_e32 v3, v3, v16
	v_max_f32_e32 v26, 0, v26
	v_max_f32_e32 v27, 0, v27
	v_max_f32_e32 v12, 0, v12
	v_max_f32_e32 v13, 0, v13
	v_max_f32_e32 v14, 0, v14
	v_max_f32_e32 v15, 0, v15
	v_max_f32_e32 v8, 0, v8
	v_max_f32_e32 v9, 0, v9
	v_max_f32_e32 v10, 0, v10
	v_max_f32_e32 v11, 0, v11
	v_max_f32_e32 v4, 0, v4
	v_max_f32_e32 v5, 0, v5
	v_max_f32_e32 v6, 0, v6
	v_max_f32_e32 v7, 0, v7
	v_max_f32_e32 v0, 0, v0
	v_max_f32_e32 v1, 0, v1
	v_max_f32_e32 v2, 0, v2
	v_max_f32_e32 v3, 0, v3
	v_cvt_pk_bf16_f32 v122, v122, v123
	v_cvt_pk_bf16_f32 v123, v124, v125
	v_lshl_add_u64 v[124:125], v[114:115], 0, v[152:153]
	v_pk_mul_f32 v[106:107], v[106:107], v[106:107]
	v_pk_mul_f32 v[90:91], v[90:91], v[90:91]
	v_pk_mul_f32 v[74:75], v[74:75], v[74:75]
	v_pk_mul_f32 v[58:59], v[58:59], v[58:59]
	v_pk_mul_f32 v[42:43], v[42:43], v[42:43]
	v_pk_mul_f32 v[26:27], v[26:27], v[26:27]
	v_pk_mul_f32 v[12:13], v[12:13], v[12:13]
	v_pk_mul_f32 v[14:15], v[14:15], v[14:15]
	v_pk_mul_f32 v[8:9], v[8:9], v[8:9]
	v_pk_mul_f32 v[10:11], v[10:11], v[10:11]
	v_or_b32_e32 v152, 0x1c00, v152
	v_pk_mul_f32 v[4:5], v[4:5], v[4:5]
	v_pk_mul_f32 v[6:7], v[6:7], v[6:7]
	v_pk_mul_f32 v[0:1], v[0:1], v[0:1]
	v_pk_mul_f32 v[2:3], v[2:3], v[2:3]
	v_cvt_pk_bf16_f32 v111, v106, v107
	v_lshl_add_u64 v[106:107], v[116:117], 0, v[104:105]
	v_cvt_pk_bf16_f32 v95, v90, v91
	v_lshl_add_u64 v[90:91], v[116:117], 0, v[88:89]
	v_cvt_pk_bf16_f32 v79, v74, v75
	v_lshl_add_u64 v[74:75], v[116:117], 0, v[72:73]
	v_cvt_pk_bf16_f32 v63, v58, v59
	v_lshl_add_u64 v[58:59], v[116:117], 0, v[56:57]
	v_cvt_pk_bf16_f32 v47, v42, v43
	v_lshl_add_u64 v[42:43], v[116:117], 0, v[40:41]
	v_cvt_pk_bf16_f32 v31, v26, v27
	v_lshl_add_u64 v[26:27], v[116:117], 0, v[24:25]
	v_cvt_pk_bf16_f32 v12, v12, v13
	v_cvt_pk_bf16_f32 v13, v14, v15
	v_cvt_pk_bf16_f32 v14, v8, v9
	v_cvt_pk_bf16_f32 v15, v10, v11
	v_lshl_add_u64 v[8:9], v[116:117], 0, v[152:153]
	v_cvt_pk_bf16_f32 v4, v4, v5
	v_cvt_pk_bf16_f32 v5, v6, v7
	v_cvt_pk_bf16_f32 v6, v0, v1
	v_cvt_pk_bf16_f32 v7, v2, v3
	v_lshl_add_u64 v[0:1], v[114:115], 0, v[152:153]
	s_add_i32 s9, s9, s26
	v_permlane16_swap_b32_e32 v120, v122
	v_permlane16_swap_b32_e32 v121, v123
	v_lshl_add_u64 v[124:125], v[124:125], 0, v[112:113]
	v_permlane16_swap_b32_e32 v108, v110
	v_permlane16_swap_b32_e32 v109, v111
	v_lshl_add_u64 v[106:107], v[106:107], 0, v[112:113]
	v_permlane16_swap_b32_e32 v92, v94
	v_permlane16_swap_b32_e32 v93, v95
	v_lshl_add_u64 v[90:91], v[90:91], 0, v[112:113]
	v_permlane16_swap_b32_e32 v76, v78
	v_permlane16_swap_b32_e32 v77, v79
	v_lshl_add_u64 v[74:75], v[74:75], 0, v[112:113]
	v_permlane16_swap_b32_e32 v60, v62
	v_permlane16_swap_b32_e32 v61, v63
	v_lshl_add_u64 v[58:59], v[58:59], 0, v[112:113]
	v_permlane16_swap_b32_e32 v44, v46
	v_permlane16_swap_b32_e32 v45, v47
	v_lshl_add_u64 v[42:43], v[42:43], 0, v[112:113]
	v_permlane16_swap_b32_e32 v28, v30
	v_permlane16_swap_b32_e32 v29, v31
	v_lshl_add_u64 v[26:27], v[26:27], 0, v[112:113]
	v_permlane16_swap_b32_e32 v12, v14
	v_permlane16_swap_b32_e32 v13, v15
	v_lshl_add_u64 v[8:9], v[8:9], 0, v[112:113]
	v_permlane16_swap_b32_e32 v4, v6
	v_permlane16_swap_b32_e32 v5, v7
	v_lshl_add_u64 v[0:1], v[0:1], 0, v[112:113]
	s_cmpk_gt_i32 s9, 0x13ff
	v_readlane_b32 s65, v252, 5
	v_readlane_b32 s66, v252, 6
	v_readlane_b32 s67, v252, 7
	v_readlane_b32 s68, v252, 8
	v_readlane_b32 s69, v252, 9
	v_readlane_b32 s70, v252, 10
	v_readlane_b32 s71, v252, 11
	v_readlane_b32 s72, v252, 12
	v_readlane_b32 s73, v252, 13
	v_readlane_b32 s74, v252, 14
	v_readlane_b32 s75, v252, 15
	v_readlane_b32 s76, v252, 16
	v_readlane_b32 s77, v252, 17
	global_store_dwordx4 v[124:125], v[120:123], off nt
	global_store_dwordx4 v[106:107], v[108:111], off nt
	global_store_dwordx4 v[90:91], v[92:95], off nt
	global_store_dwordx4 v[74:75], v[76:79], off nt
	global_store_dwordx4 v[58:59], v[60:63], off nt
	global_store_dwordx4 v[42:43], v[44:47], off nt
	global_store_dwordx4 v[26:27], v[28:31], off nt
	global_store_dwordx4 v[8:9], v[12:15], off nt
	global_store_dwordx4 v[0:1], v[4:7], off nt
	s_barrier
	s_cbranch_scc0 .LBB0_287

; #define BIG_SYNC(N)                                              \
;   asm volatile("s_waitcnt vmcnt(%0)" ::"n"(N) : "memory");       \
;   __builtin_amdgcn_s_barrier();                                  \
;   asm volatile("" ::: "memory");                                 \
;   __builtin_amdgcn_sched_barrier(0);
; template <int NK, bool BNT = false> ...
;     ...
;   auto kstep = [&](int T, int cur, int nxt, bool do_stage) {
;     const unsigned char* sa = smem + cur * BIG_STAGE;
;     bf16x8 af[4], bfr[4];
; #pragma unroll
;     for (int m = 0; m < 4; ++m) af[m] = *reinterpret_cast<const bf16x8*>(sa + aoff + m * 1024);
; #pragma unroll
;     for (int n = 0; n < 4; ++n) bfr[n] = *reinterpret_cast<const bf16x8*>(sa + boff + n * 1024);
;     __builtin_amdgcn_sched_barrier(0);
;     if (do_stage) stage(T + 3, nxt);
; #pragma unroll
;     for (int m = 0; m < 4; ++m)
; #pragma unroll
;       for (int n = 0; n < 4; ++n) acc[m][n] = __builtin_amdgcn_mfma_f32_16x16x32_bf16(af[m], bfr[n], acc[m][n], 0, 0, 0);
;     if (do_stage) {
; #pragma unroll
;       for (int q = 0; q < NG; ++q) {
;         __builtin_amdgcn_sched_group_barrier(0x008, 3, 0);
;         __builtin_amdgcn_sched_group_barrier(0x010, 1, 0);
;       }
;       __builtin_amdgcn_sched_group_barrier(0x008, 16 - 3 * NG, 0);
;     }
;     __builtin_amdgcn_sched_barrier(0);
; #pragma unroll
;     for (int n = 0; n < 4; ++n) bfr[n] = *reinterpret_cast<const bf16x8*>(sa + boff + (4 + n) * 1024);
; #pragma unroll
;     for (int m = 0; m < 4; ++m)
; #pragma unroll
;       for (int n = 0; n < 4; ++n)
;         acc[m][4 + n] = __builtin_amdgcn_mfma_f32_16x16x32_bf16(af[m], bfr[n], acc[m][4 + n], 0, 0, 0);
;     __builtin_amdgcn_sched_barrier(0);
;   };
;     ...
;   for (int it = 0; it < NK / 4 - 1; ++it) {
;     const int t = it * 4;
;     BIG_SYNC(2 * NG); kstep(t, 0, 3, true);
;     BIG_SYNC(2 * NG); kstep(t + 1, 1, 0, true);
;     BIG_SYNC(2 * NG); kstep(t + 2, 2, 1, true);
;     BIG_SYNC(2 * NG); kstep(t + 3, 3, 2, true);
;   }
.LBB0_302:
	v_add_u32_e32 v163, 0x18000, v147
	v_lshl_add_u64 v[144:145], v[138:139], 0, s[6:7]
	v_readfirstlane_b32 s5, v163
	v_lshl_add_u64 v[164:165], v[144:145], 0, s[60:61]
	s_mov_b32 m0, s5
	s_waitcnt lgkmcnt(3)
	v_mfma_f32_16x16x32_bf16 v[56:59], v[216:219], v[232:235], v[56:59]
	v_lshl_add_u64 v[142:143], v[140:141], 0, s[6:7]
	v_lshl_add_u64 v[168:169], v[144:145], 0, s[80:81]
	v_lshl_add_u64 v[166:167], v[142:143], 0, s[60:61]
	v_mfma_f32_16x16x32_bf16 v[100:103], v[220:223], v[232:235], v[100:103]
	v_mfma_f32_16x16x32_bf16 v[104:107], v[224:227], v[232:235], v[104:107]
	s_waitcnt vmcnt(4)
	s_barrier
	global_load_lds_dwordx4 v[164:165], off
	v_add_u32_e32 v164, 0x1a000, v147
	v_add_u32_e32 v165, 0x1c000, v147
	v_readfirstlane_b32 s5, v164
	s_mov_b32 m0, s5
	v_readfirstlane_b32 s5, v165
	v_mfma_f32_16x16x32_bf16 v[112:115], v[228:231], v[232:235], v[112:115]
	s_waitcnt lgkmcnt(2)
	v_mfma_f32_16x16x32_bf16 v[64:67], v[216:219], v[236:239], v[64:67]
	ds_read_b128 v[232:235], v149 offset:20480
	v_mfma_f32_16x16x32_bf16 v[80:83], v[220:223], v[236:239], v[80:83]
	ds_read_b128 v[186:189], v148 offset:32768
	global_load_lds_dwordx4 v[168:169], off
	s_mov_b32 m0, s5
	v_mfma_f32_16x16x32_bf16 v[96:99], v[224:227], v[236:239], v[96:99]
	ds_read_b128 v[190:193], v148 offset:33792
	v_lshl_add_u64 v[168:169], v[142:143], 0, s[80:81]
	v_mfma_f32_16x16x32_bf16 v[116:119], v[228:231], v[236:239], v[116:119]
	ds_read_b128 v[194:197], v148 offset:34816
	s_waitcnt lgkmcnt(5)
	v_mfma_f32_16x16x32_bf16 v[52:55], v[216:219], v[240:243], v[52:55]
	ds_read_b128 v[236:239], v149 offset:21504
	global_load_lds_dwordx4 v[166:167], off
	v_add_u32_e32 v166, 0x1e000, v147
	v_mfma_f32_16x16x32_bf16 v[68:71], v[220:223], v[240:243], v[68:71]
	ds_read_b128 v[202:205], v148 offset:35840
	v_readfirstlane_b32 s5, v166
	s_mov_b32 m0, s5
	v_mfma_f32_16x16x32_bf16 v[108:111], v[224:227], v[240:243], v[108:111]
	v_mfma_f32_16x16x32_bf16 v[120:123], v[228:231], v[240:243], v[120:123]
	global_load_lds_dwordx4 v[168:169], off
	s_waitcnt lgkmcnt(6)
	v_mfma_f32_16x16x32_bf16 v[48:51], v[216:219], v[244:247], v[48:51]
	ds_read_b128 v[240:243], v149 offset:22528
	v_mfma_f32_16x16x32_bf16 v[72:75], v[220:223], v[244:247], v[72:75]
	v_mfma_f32_16x16x32_bf16 v[88:91], v[224:227], v[244:247], v[88:91]
	v_mfma_f32_16x16x32_bf16 v[124:127], v[228:231], v[244:247], v[124:127]
	s_waitcnt lgkmcnt(6)
	v_mfma_f32_16x16x32_bf16 v[0:3], v[216:219], v[232:235], v[0:3]
	ds_read_b128 v[244:247], v149 offset:23552
	v_mfma_f32_16x16x32_bf16 v[16:19], v[220:223], v[232:235], v[16:19]
	v_mfma_f32_16x16x32_bf16 v[32:35], v[224:227], v[232:235], v[32:35]
	v_mfma_f32_16x16x32_bf16 v[60:63], v[228:231], v[232:235], v[60:63]
	s_waitcnt lgkmcnt(3)
	v_mfma_f32_16x16x32_bf16 v[4:7], v[216:219], v[236:239], v[4:7]
	ds_read_b128 v[232:235], v149 offset:49152
	v_mfma_f32_16x16x32_bf16 v[20:23], v[220:223], v[236:239], v[20:23]
	v_mfma_f32_16x16x32_bf16 v[36:39], v[224:227], v[236:239], v[36:39]
	v_mfma_f32_16x16x32_bf16 v[76:79], v[228:231], v[236:239], v[76:79]
	s_waitcnt lgkmcnt(2)
	v_mfma_f32_16x16x32_bf16 v[8:11], v[216:219], v[240:243], v[8:11]
	ds_read_b128 v[236:239], v149 offset:50176
	v_mfma_f32_16x16x32_bf16 v[24:27], v[220:223], v[240:243], v[24:27]
	v_mfma_f32_16x16x32_bf16 v[40:43], v[224:227], v[240:243], v[40:43]
	v_mfma_f32_16x16x32_bf16 v[84:87], v[228:231], v[240:243], v[84:87]
	s_waitcnt lgkmcnt(2)
	v_mfma_f32_16x16x32_bf16 v[12:15], v[216:219], v[244:247], v[12:15]
	ds_read_b128 v[240:243], v149 offset:51200
	v_mfma_f32_16x16x32_bf16 v[28:31], v[220:223], v[244:247], v[28:31]
	v_mfma_f32_16x16x32_bf16 v[44:47], v[224:227], v[244:247], v[44:47]
	v_mfma_f32_16x16x32_bf16 v[92:95], v[228:231], v[244:247], v[92:95]
	ds_read_b128 v[244:247], v149 offset:52224
	v_readfirstlane_b32 s5, v147
	v_lshl_add_u64 v[168:169], v[144:145], 0, s[62:63]
	s_mov_b32 m0, s5
	v_readfirstlane_b32 s5, v146
	s_waitcnt lgkmcnt(3)
	v_mfma_f32_16x16x32_bf16 v[56:59], v[186:189], v[232:235], v[56:59]
	v_lshl_add_u64 v[182:183], v[142:143], 0, s[62:63]
	v_mfma_f32_16x16x32_bf16 v[100:103], v[190:193], v[232:235], v[100:103]
	v_mfma_f32_16x16x32_bf16 v[104:107], v[194:197], v[232:235], v[104:107]
	s_waitcnt vmcnt(4)
	s_barrier
	global_load_lds_dwordx4 v[168:169], off
	v_lshl_add_u64 v[168:169], v[144:145], 0, s[0:1]
	s_mov_b32 m0, s5
	v_readfirstlane_b32 s5, v152
	v_mfma_f32_16x16x32_bf16 v[112:115], v[202:205], v[232:235], v[112:115]
	s_waitcnt lgkmcnt(2)
	v_mfma_f32_16x16x32_bf16 v[64:67], v[186:189], v[236:239], v[64:67]
	ds_read_b128 v[232:235], v149 offset:53248
	v_mfma_f32_16x16x32_bf16 v[80:83], v[190:193], v[236:239], v[80:83]
	v_add_u32_e32 v167, 0x10000, v148
	ds_read_b128 v[216:219], v167
	global_load_lds_dwordx4 v[168:169], off
	s_mov_b32 m0, s5
	v_readfirstlane_b32 s5, v154
	v_lshl_add_u64 v[168:169], v[142:143], 0, s[0:1]
	v_mfma_f32_16x16x32_bf16 v[96:99], v[194:197], v[236:239], v[96:99]
	ds_read_b128 v[220:223], v167 offset:1024
	v_mfma_f32_16x16x32_bf16 v[116:119], v[202:205], v[236:239], v[116:119]
	ds_read_b128 v[224:227], v167 offset:2048
	s_waitcnt lgkmcnt(5)
	v_mfma_f32_16x16x32_bf16 v[52:55], v[186:189], v[240:243], v[52:55]
	ds_read_b128 v[236:239], v149 offset:54272
	global_load_lds_dwordx4 v[182:183], off
	s_mov_b32 m0, s5
	v_mfma_f32_16x16x32_bf16 v[68:71], v[190:193], v[240:243], v[68:71]
	ds_read_b128 v[228:231], v167 offset:3072
	v_mfma_f32_16x16x32_bf16 v[108:111], v[194:197], v[240:243], v[108:111]
	v_mfma_f32_16x16x32_bf16 v[120:123], v[202:205], v[240:243], v[120:123]
	global_load_lds_dwordx4 v[168:169], off
	s_waitcnt lgkmcnt(6)
; #define BIG_SYNC(N)                                              \
;   asm volatile("s_waitcnt vmcnt(%0)" ::"n"(N) : "memory");       \
;   __builtin_amdgcn_s_barrier();                                  \
;   asm volatile("" ::: "memory");                                 \
;   __builtin_amdgcn_sched_barrier(0);
; template <int NK, bool BNT = false> ...
;     ...
;   auto kstep = [&](int T, int cur, int nxt, bool do_stage) {
;     const unsigned char* sa = smem + cur * BIG_STAGE;
;     bf16x8 af[4], bfr[4];
; #pragma unroll
;     for (int m = 0; m < 4; ++m) af[m] = *reinterpret_cast<const bf16x8*>(sa + aoff + m * 1024);
; #pragma unroll
;     for (int n = 0; n < 4; ++n) bfr[n] = *reinterpret_cast<const bf16x8*>(sa + boff + n * 1024);
;     __builtin_amdgcn_sched_barrier(0);
;     if (do_stage) stage(T + 3, nxt);
; #pragma unroll
;     for (int m = 0; m < 4; ++m)
; #pragma unroll
;       for (int n = 0; n < 4; ++n) acc[m][n] = __builtin_amdgcn_mfma_f32_16x16x32_bf16(af[m], bfr[n], acc[m][n], 0, 0, 0);
;     if (do_stage) {
; #pragma unroll
;       for (int q = 0; q < NG; ++q) {
;         __builtin_amdgcn_sched_group_barrier(0x008, 3, 0);
;         __builtin_amdgcn_sched_group_barrier(0x010, 1, 0);
;       }
;       __builtin_amdgcn_sched_group_barrier(0x008, 16 - 3 * NG, 0);
;     }
;     __builtin_amdgcn_sched_barrier(0);
; #pragma unroll
;     for (int n = 0; n < 4; ++n) bfr[n] = *reinterpret_cast<const bf16x8*>(sa + boff + (4 + n) * 1024);
; #pragma unroll
;     for (int m = 0; m < 4; ++m)
; #pragma unroll
;       for (int n = 0; n < 4; ++n)
;         acc[m][4 + n] = __builtin_amdgcn_mfma_f32_16x16x32_bf16(af[m], bfr[n], acc[m][4 + n], 0, 0, 0);
;     __builtin_amdgcn_sched_barrier(0);
;   };
;     ...
;   for (int it = 0; it < NK / 4 - 1; ++it) {
;     const int t = it * 4;
;     BIG_SYNC(2 * NG); kstep(t, 0, 3, true);
;     BIG_SYNC(2 * NG); kstep(t + 1, 1, 0, true);
;     BIG_SYNC(2 * NG); kstep(t + 2, 2, 1, true);
;     BIG_SYNC(2 * NG); kstep(t + 3, 3, 2, true);
;   }
	v_mfma_f32_16x16x32_bf16 v[48:51], v[186:189], v[244:247], v[48:51]
	ds_read_b128 v[240:243], v149 offset:55296
	v_mfma_f32_16x16x32_bf16 v[72:75], v[190:193], v[244:247], v[72:75]
	v_mfma_f32_16x16x32_bf16 v[88:91], v[194:197], v[244:247], v[88:91]
	v_mfma_f32_16x16x32_bf16 v[124:127], v[202:205], v[244:247], v[124:127]
	v_or_b32_e32 v168, 0x10000, v150
	s_waitcnt lgkmcnt(6)
	v_mfma_f32_16x16x32_bf16 v[0:3], v[186:189], v[232:235], v[0:3]
	ds_read_b128 v[244:247], v149 offset:56320
	v_mfma_f32_16x16x32_bf16 v[16:19], v[190:193], v[232:235], v[16:19]
	v_mfma_f32_16x16x32_bf16 v[32:35], v[194:197], v[232:235], v[32:35]
	v_mfma_f32_16x16x32_bf16 v[60:63], v[202:205], v[232:235], v[60:63]
	s_waitcnt lgkmcnt(3)
	v_mfma_f32_16x16x32_bf16 v[4:7], v[186:189], v[236:239], v[4:7]
	ds_read_b128 v[232:235], v168
	v_mfma_f32_16x16x32_bf16 v[20:23], v[190:193], v[236:239], v[20:23]
	v_mfma_f32_16x16x32_bf16 v[36:39], v[194:197], v[236:239], v[36:39]
	v_mfma_f32_16x16x32_bf16 v[76:79], v[202:205], v[236:239], v[76:79]
	s_waitcnt lgkmcnt(2)
	v_mfma_f32_16x16x32_bf16 v[8:11], v[186:189], v[240:243], v[8:11]
	ds_read_b128 v[236:239], v168 offset:1024
	v_mfma_f32_16x16x32_bf16 v[24:27], v[190:193], v[240:243], v[24:27]
	v_mfma_f32_16x16x32_bf16 v[40:43], v[194:197], v[240:243], v[40:43]
	v_mfma_f32_16x16x32_bf16 v[84:87], v[202:205], v[240:243], v[84:87]
	s_waitcnt lgkmcnt(2)
	v_mfma_f32_16x16x32_bf16 v[12:15], v[186:189], v[244:247], v[12:15]
	ds_read_b128 v[240:243], v168 offset:2048
	v_mfma_f32_16x16x32_bf16 v[28:31], v[190:193], v[244:247], v[28:31]
	v_mfma_f32_16x16x32_bf16 v[44:47], v[194:197], v[244:247], v[44:47]
	v_mfma_f32_16x16x32_bf16 v[92:95], v[202:205], v[244:247], v[92:95]
	ds_read_b128 v[244:247], v168 offset:3072
	v_add_u32_e32 v167, 0x10000, v148
	v_or_b32_e32 v168, 0x10000, v150
	v_add_u32_e32 v169, 0x10400, v150
	v_add_u32_e32 v170, 0x10800, v150
	v_add_u32_e32 v172, 0x10c00, v150
	v_readfirstlane_b32 s5, v155
	v_lshl_add_u64 v[174:175], v[144:145], 0, s[2:3]
	s_mov_b32 m0, s5
	v_readfirstlane_b32 s5, v156
	s_waitcnt lgkmcnt(3)
	v_mfma_f32_16x16x32_bf16 v[56:59], v[216:219], v[232:235], v[56:59]
	v_lshl_add_u64 v[178:179], v[142:143], 0, s[2:3]
	v_mfma_f32_16x16x32_bf16 v[100:103], v[220:223], v[232:235], v[100:103]
	v_mfma_f32_16x16x32_bf16 v[104:107], v[224:227], v[232:235], v[104:107]
	s_waitcnt vmcnt(4)
	s_barrier
	global_load_lds_dwordx4 v[174:175], off
	v_lshl_add_u64 v[174:175], v[144:145], 0, s[52:53]
	s_mov_b32 m0, s5
	v_readfirstlane_b32 s5, v157
	v_mfma_f32_16x16x32_bf16 v[112:115], v[228:231], v[232:235], v[112:115]
	s_waitcnt lgkmcnt(2)
	v_mfma_f32_16x16x32_bf16 v[64:67], v[216:219], v[236:239], v[64:67]
	ds_read_b128 v[232:235], v168 offset:4096
	v_mfma_f32_16x16x32_bf16 v[80:83], v[220:223], v[236:239], v[80:83]
	v_add_u32_e32 v167, 0x10000, v148
	ds_read_b128 v[186:189], v167 offset:32768
	global_load_lds_dwordx4 v[174:175], off
	s_mov_b32 m0, s5
	v_readfirstlane_b32 s5, v158
	v_lshl_add_u64 v[174:175], v[142:143], 0, s[52:53]
	v_mfma_f32_16x16x32_bf16 v[96:99], v[224:227], v[236:239], v[96:99]
	ds_read_b128 v[190:193], v167 offset:33792
	v_mfma_f32_16x16x32_bf16 v[116:119], v[228:231], v[236:239], v[116:119]
	ds_read_b128 v[194:197], v167 offset:34816
	s_waitcnt lgkmcnt(5)
	v_mfma_f32_16x16x32_bf16 v[52:55], v[216:219], v[240:243], v[52:55]
	ds_read_b128 v[236:239], v168 offset:5120
	global_load_lds_dwordx4 v[178:179], off
	s_mov_b32 m0, s5
	v_mfma_f32_16x16x32_bf16 v[68:71], v[220:223], v[240:243], v[68:71]
	ds_read_b128 v[202:205], v167 offset:35840
	v_mfma_f32_16x16x32_bf16 v[108:111], v[224:227], v[240:243], v[108:111]
	v_mfma_f32_16x16x32_bf16 v[120:123], v[228:231], v[240:243], v[120:123]
	global_load_lds_dwordx4 v[174:175], off
	s_waitcnt lgkmcnt(6)
	v_mfma_f32_16x16x32_bf16 v[48:51], v[216:219], v[244:247], v[48:51]
	ds_read_b128 v[240:243], v168 offset:6144
	v_mfma_f32_16x16x32_bf16 v[72:75], v[220:223], v[244:247], v[72:75]
	v_mfma_f32_16x16x32_bf16 v[88:91], v[224:227], v[244:247], v[88:91]
	v_mfma_f32_16x16x32_bf16 v[124:127], v[228:231], v[244:247], v[124:127]
	v_add_u32_e32 v173, 0x11000, v150
	v_add_u32_e32 v174, 0x11400, v150
	v_add_u32_e32 v175, 0x11800, v150
	v_add_u32_e32 v178, 0x11c00, v150
	v_or_b32_e32 v168, 0x10000, v150
	s_waitcnt lgkmcnt(6)
	v_mfma_f32_16x16x32_bf16 v[0:3], v[216:219], v[232:235], v[0:3]
	ds_read_b128 v[244:247], v168 offset:7168
	v_mfma_f32_16x16x32_bf16 v[16:19], v[220:223], v[232:235], v[16:19]
	v_mfma_f32_16x16x32_bf16 v[32:35], v[224:227], v[232:235], v[32:35]
	v_mfma_f32_16x16x32_bf16 v[60:63], v[228:231], v[232:235], v[60:63]
	s_waitcnt lgkmcnt(3)
	v_mfma_f32_16x16x32_bf16 v[4:7], v[216:219], v[236:239], v[4:7]
	ds_read_b128 v[232:235], v168 offset:32768
	v_mfma_f32_16x16x32_bf16 v[20:23], v[220:223], v[236:239], v[20:23]
	v_mfma_f32_16x16x32_bf16 v[36:39], v[224:227], v[236:239], v[36:39]
	v_mfma_f32_16x16x32_bf16 v[76:79], v[228:231], v[236:239], v[76:79]
	s_waitcnt lgkmcnt(2)
	v_mfma_f32_16x16x32_bf16 v[8:11], v[216:219], v[240:243], v[8:11]
	ds_read_b128 v[236:239], v168 offset:33792
	v_mfma_f32_16x16x32_bf16 v[24:27], v[220:223], v[240:243], v[24:27]
	v_mfma_f32_16x16x32_bf16 v[40:43], v[224:227], v[240:243], v[40:43]
	v_mfma_f32_16x16x32_bf16 v[84:87], v[228:231], v[240:243], v[84:87]
	s_waitcnt lgkmcnt(2)
	v_mfma_f32_16x16x32_bf16 v[12:15], v[216:219], v[244:247], v[12:15]
	ds_read_b128 v[240:243], v168 offset:34816
	v_mfma_f32_16x16x32_bf16 v[28:31], v[220:223], v[244:247], v[28:31]
	v_mfma_f32_16x16x32_bf16 v[44:47], v[224:227], v[244:247], v[44:47]
	v_mfma_f32_16x16x32_bf16 v[92:95], v[228:231], v[244:247], v[92:95]
	ds_read_b128 v[244:247], v168 offset:35840
	v_add_u32_e32 v176, 0x18000, v148
	v_or_b32_e32 v179, 0x18000, v150
	v_add_u32_e32 v180, 0x18400, v150
	v_add_u32_e32 v181, 0x18800, v150
	v_add_u32_e32 v182, 0x18c00, v150
	v_readfirstlane_b32 s5, v159
	v_lshl_add_u64 v[248:249], v[144:145], 0, s[54:55]
	s_mov_b32 m0, s5
	v_readfirstlane_b32 s5, v160
	v_lshl_add_u64 v[144:145], v[144:145], 0, s[56:57]
	s_waitcnt lgkmcnt(3)
	v_mfma_f32_16x16x32_bf16 v[56:59], v[186:189], v[232:235], v[56:59]
	v_lshl_add_u64 v[250:251], v[142:143], 0, s[54:55]
	v_lshl_add_u64 v[142:143], v[142:143], 0, s[56:57]
	v_mfma_f32_16x16x32_bf16 v[100:103], v[190:193], v[232:235], v[100:103]
	v_mfma_f32_16x16x32_bf16 v[104:107], v[194:197], v[232:235], v[104:107]
	s_waitcnt vmcnt(4)
	s_barrier
; #define BIG_SYNC(N)                                              \
;   asm volatile("s_waitcnt vmcnt(%0)" ::"n"(N) : "memory");       \
;   __builtin_amdgcn_s_barrier();                                  \
;   asm volatile("" ::: "memory");                                 \
;   __builtin_amdgcn_sched_barrier(0);
; template <int NK, bool BNT = false> ...
;     ...
;   auto kstep = [&](int T, int cur, int nxt, bool do_stage) {
;     const unsigned char* sa = smem + cur * BIG_STAGE;
;     bf16x8 af[4], bfr[4];
; #pragma unroll
;     for (int m = 0; m < 4; ++m) af[m] = *reinterpret_cast<const bf16x8*>(sa + aoff + m * 1024);
; #pragma unroll
;     for (int n = 0; n < 4; ++n) bfr[n] = *reinterpret_cast<const bf16x8*>(sa + boff + n * 1024);
;     __builtin_amdgcn_sched_barrier(0);
;     if (do_stage) stage(T + 3, nxt);
; #pragma unroll
;     for (int m = 0; m < 4; ++m)
; #pragma unroll
;       for (int n = 0; n < 4; ++n) acc[m][n] = __builtin_amdgcn_mfma_f32_16x16x32_bf16(af[m], bfr[n], acc[m][n], 0, 0, 0);
;     if (do_stage) {
; #pragma unroll
;       for (int q = 0; q < NG; ++q) {
;         __builtin_amdgcn_sched_group_barrier(0x008, 3, 0);
;         __builtin_amdgcn_sched_group_barrier(0x010, 1, 0);
;       }
;       __builtin_amdgcn_sched_group_barrier(0x008, 16 - 3 * NG, 0);
;     }
;     __builtin_amdgcn_sched_barrier(0);
; #pragma unroll
;     for (int n = 0; n < 4; ++n) bfr[n] = *reinterpret_cast<const bf16x8*>(sa + boff + (4 + n) * 1024);
; #pragma unroll
;     for (int m = 0; m < 4; ++m)
; #pragma unroll
;       for (int n = 0; n < 4; ++n)
;         acc[m][4 + n] = __builtin_amdgcn_mfma_f32_16x16x32_bf16(af[m], bfr[n], acc[m][4 + n], 0, 0, 0);
;     __builtin_amdgcn_sched_barrier(0);
;   };
;     ...
;   for (int it = 0; it < NK / 4 - 1; ++it) {
;     const int t = it * 4;
;     BIG_SYNC(2 * NG); kstep(t, 0, 3, true);
;     BIG_SYNC(2 * NG); kstep(t + 1, 1, 0, true);
;     BIG_SYNC(2 * NG); kstep(t + 2, 2, 1, true);
;     BIG_SYNC(2 * NG); kstep(t + 3, 3, 2, true);
;   }
;   BIG_SYNC(2 * NG); kstep(NK - 4, 0, 3, true);
	global_load_lds_dwordx4 v[248:249], off
	s_mov_b32 m0, s5
	v_readfirstlane_b32 s5, v161
	v_mfma_f32_16x16x32_bf16 v[112:115], v[202:205], v[232:235], v[112:115]
	s_waitcnt lgkmcnt(2)
	v_mfma_f32_16x16x32_bf16 v[64:67], v[186:189], v[236:239], v[64:67]
	ds_read_b128 v[232:235], v168 offset:36864
	v_mfma_f32_16x16x32_bf16 v[80:83], v[190:193], v[236:239], v[80:83]
	ds_read_b128 v[216:219], v148
	global_load_lds_dwordx4 v[144:145], off
	s_mov_b32 m0, s5
	v_readfirstlane_b32 s5, v162
	v_mfma_f32_16x16x32_bf16 v[96:99], v[194:197], v[236:239], v[96:99]
	ds_read_b128 v[220:223], v148 offset:1024
	v_mfma_f32_16x16x32_bf16 v[116:119], v[202:205], v[236:239], v[116:119]
	ds_read_b128 v[224:227], v148 offset:2048
	s_waitcnt lgkmcnt(5)
	v_mfma_f32_16x16x32_bf16 v[52:55], v[186:189], v[240:243], v[52:55]
	ds_read_b128 v[236:239], v168 offset:37888
	global_load_lds_dwordx4 v[250:251], off
	s_mov_b32 m0, s5
	v_mfma_f32_16x16x32_bf16 v[68:71], v[190:193], v[240:243], v[68:71]
	ds_read_b128 v[228:231], v148 offset:3072
	v_mfma_f32_16x16x32_bf16 v[108:111], v[194:197], v[240:243], v[108:111]
	v_mfma_f32_16x16x32_bf16 v[120:123], v[202:205], v[240:243], v[120:123]
	global_load_lds_dwordx4 v[142:143], off
	s_waitcnt lgkmcnt(6)
	v_mfma_f32_16x16x32_bf16 v[48:51], v[186:189], v[244:247], v[48:51]
	ds_read_b128 v[240:243], v168 offset:38912
	v_mfma_f32_16x16x32_bf16 v[72:75], v[190:193], v[244:247], v[72:75]
	v_mfma_f32_16x16x32_bf16 v[88:91], v[194:197], v[244:247], v[88:91]
	v_mfma_f32_16x16x32_bf16 v[124:127], v[202:205], v[244:247], v[124:127]
	v_add_u32_e32 v142, 0x19000, v150
	v_add_u32_e32 v143, 0x19400, v150
	v_add_u32_e32 v144, 0x19800, v150
	v_add_u32_e32 v145, 0x19c00, v150
	s_waitcnt lgkmcnt(6)
	v_mfma_f32_16x16x32_bf16 v[0:3], v[186:189], v[232:235], v[0:3]
	ds_read_b128 v[244:247], v168 offset:39936
	v_mfma_f32_16x16x32_bf16 v[16:19], v[190:193], v[232:235], v[16:19]
	v_mfma_f32_16x16x32_bf16 v[32:35], v[194:197], v[232:235], v[32:35]
	v_mfma_f32_16x16x32_bf16 v[60:63], v[202:205], v[232:235], v[60:63]
	s_waitcnt lgkmcnt(3)
	v_mfma_f32_16x16x32_bf16 v[4:7], v[186:189], v[236:239], v[4:7]
	ds_read_b128 v[232:235], v149 offset:16384
	v_mfma_f32_16x16x32_bf16 v[20:23], v[190:193], v[236:239], v[20:23]
	v_mfma_f32_16x16x32_bf16 v[36:39], v[194:197], v[236:239], v[36:39]
	v_mfma_f32_16x16x32_bf16 v[76:79], v[202:205], v[236:239], v[76:79]
	s_waitcnt lgkmcnt(2)
	v_mfma_f32_16x16x32_bf16 v[8:11], v[186:189], v[240:243], v[8:11]
	ds_read_b128 v[236:239], v149 offset:17408
	v_mfma_f32_16x16x32_bf16 v[24:27], v[190:193], v[240:243], v[24:27]
	v_mfma_f32_16x16x32_bf16 v[40:43], v[194:197], v[240:243], v[40:43]
	v_mfma_f32_16x16x32_bf16 v[84:87], v[202:205], v[240:243], v[84:87]
	s_waitcnt lgkmcnt(2)
	v_mfma_f32_16x16x32_bf16 v[12:15], v[186:189], v[244:247], v[12:15]
	ds_read_b128 v[240:243], v149 offset:18432
	v_mfma_f32_16x16x32_bf16 v[28:31], v[190:193], v[244:247], v[28:31]
	v_mfma_f32_16x16x32_bf16 v[44:47], v[194:197], v[244:247], v[44:47]
	v_mfma_f32_16x16x32_bf16 v[92:95], v[202:205], v[244:247], v[92:95]
	ds_read_b128 v[244:247], v149 offset:19456
	s_add_u32 s6, s6, 0x8000
	s_addc_u32 s7, s7, 0
	s_cmp_lg_u32 s6, 0x38000
	s_cbranch_scc1 .LBB0_302
	s_sext_i32_i8 s4, s4
	s_mov_b64 s[6:7], 0x3e000
	v_readfirstlane_b32 s5, v163
	v_lshl_add_u64 v[198:199], v[136:137], 0, s[6:7]
	v_lshl_add_u64 v[200:201], v[134:135], 0, s[6:7]
	s_mov_b32 m0, s5
	s_mov_b64 s[6:7], 0x7e000
	v_readfirstlane_b32 s5, v164
	v_lshl_add_u64 v[136:137], v[136:137], 0, s[6:7]
	s_waitcnt lgkmcnt(3)
	v_mfma_f32_16x16x32_bf16 v[56:59], v[216:219], v[232:235], v[56:59]
	v_lshl_add_u64 v[134:135], v[134:135], 0, s[6:7]
	v_mfma_f32_16x16x32_bf16 v[100:103], v[220:223], v[232:235], v[100:103]
	v_mfma_f32_16x16x32_bf16 v[104:107], v[224:227], v[232:235], v[104:107]
	s_waitcnt vmcnt(4)
	s_barrier
	global_load_lds_dwordx4 v[198:199], off
	s_mov_b32 m0, s5
	v_readfirstlane_b32 s5, v165
	v_mfma_f32_16x16x32_bf16 v[112:115], v[228:231], v[232:235], v[112:115]
	s_waitcnt lgkmcnt(2)
	v_mfma_f32_16x16x32_bf16 v[64:67], v[216:219], v[236:239], v[64:67]
	ds_read_b128 v[232:235], v149 offset:20480
	v_mfma_f32_16x16x32_bf16 v[80:83], v[220:223], v[236:239], v[80:83]
	ds_read_b128 v[186:189], v148 offset:32768
	global_load_lds_dwordx4 v[136:137], off
	s_mov_b32 m0, s5
	v_readfirstlane_b32 s5, v166
	v_mfma_f32_16x16x32_bf16 v[96:99], v[224:227], v[236:239], v[96:99]
	ds_read_b128 v[190:193], v148 offset:33792
	v_mfma_f32_16x16x32_bf16 v[116:119], v[228:231], v[236:239], v[116:119]
	ds_read_b128 v[194:197], v148 offset:34816
	s_waitcnt lgkmcnt(5)
	v_mfma_f32_16x16x32_bf16 v[52:55], v[216:219], v[240:243], v[52:55]
	ds_read_b128 v[236:239], v149 offset:21504
	global_load_lds_dwordx4 v[200:201], off
	s_mov_b32 m0, s5
	v_mfma_f32_16x16x32_bf16 v[68:71], v[220:223], v[240:243], v[68:71]
	ds_read_b128 v[202:205], v148 offset:35840
	v_mfma_f32_16x16x32_bf16 v[108:111], v[224:227], v[240:243], v[108:111]
	v_mfma_f32_16x16x32_bf16 v[120:123], v[228:231], v[240:243], v[120:123]
	global_load_lds_dwordx4 v[134:135], off
	s_waitcnt lgkmcnt(6)
	v_mfma_f32_16x16x32_bf16 v[48:51], v[216:219], v[244:247], v[48:51]
	ds_read_b128 v[240:243], v149 offset:22528
	v_mfma_f32_16x16x32_bf16 v[72:75], v[220:223], v[244:247], v[72:75]
	v_mfma_f32_16x16x32_bf16 v[88:91], v[224:227], v[244:247], v[88:91]
	v_mfma_f32_16x16x32_bf16 v[124:127], v[228:231], v[244:247], v[124:127]
	s_waitcnt lgkmcnt(6)
	v_mfma_f32_16x16x32_bf16 v[0:3], v[216:219], v[232:235], v[0:3]
	ds_read_b128 v[244:247], v149 offset:23552
	v_mfma_f32_16x16x32_bf16 v[16:19], v[220:223], v[232:235], v[16:19]
	v_mfma_f32_16x16x32_bf16 v[32:35], v[224:227], v[232:235], v[32:35]
	v_mfma_f32_16x16x32_bf16 v[60:63], v[228:231], v[232:235], v[60:63]
	s_waitcnt lgkmcnt(3)
; #define BIG_SYNC(N)                                              \
;   asm volatile("s_waitcnt vmcnt(%0)" ::"n"(N) : "memory");       \
;   __builtin_amdgcn_s_barrier();                                  \
;   asm volatile("" ::: "memory");                                 \
;   __builtin_amdgcn_sched_barrier(0);
; template <int NK, bool BNT = false> ...
;     ...
;   auto kstep = [&](int T, int cur, int nxt, bool do_stage) {
;     const unsigned char* sa = smem + cur * BIG_STAGE;
;     bf16x8 af[4], bfr[4];
; #pragma unroll
;     for (int m = 0; m < 4; ++m) af[m] = *reinterpret_cast<const bf16x8*>(sa + aoff + m * 1024);
; #pragma unroll
;     for (int n = 0; n < 4; ++n) bfr[n] = *reinterpret_cast<const bf16x8*>(sa + boff + n * 1024);
;     __builtin_amdgcn_sched_barrier(0);
;     if (do_stage) stage(T + 3, nxt);
; #pragma unroll
;     for (int m = 0; m < 4; ++m)
; #pragma unroll
;       for (int n = 0; n < 4; ++n) acc[m][n] = __builtin_amdgcn_mfma_f32_16x16x32_bf16(af[m], bfr[n], acc[m][n], 0, 0, 0);
;     if (do_stage) {
; #pragma unroll
;       for (int q = 0; q < NG; ++q) {
;         __builtin_amdgcn_sched_group_barrier(0x008, 3, 0);
;         __builtin_amdgcn_sched_group_barrier(0x010, 1, 0);
;       }
;       __builtin_amdgcn_sched_group_barrier(0x008, 16 - 3 * NG, 0);
;     }
;     __builtin_amdgcn_sched_barrier(0);
; #pragma unroll
;     for (int n = 0; n < 4; ++n) bfr[n] = *reinterpret_cast<const bf16x8*>(sa + boff + (4 + n) * 1024);
; #pragma unroll
;     for (int m = 0; m < 4; ++m)
; #pragma unroll
;       for (int n = 0; n < 4; ++n)
;         acc[m][4 + n] = __builtin_amdgcn_mfma_f32_16x16x32_bf16(af[m], bfr[n], acc[m][4 + n], 0, 0, 0);
;     __builtin_amdgcn_sched_barrier(0);
;   };
;     ...
;   stage(0, 0);
;   stage(1, 1);
;   stage(2, 2);
;   for (int it = 0; it < NK / 4 - 1; ++it) {
;     const int t = it * 4;
;     BIG_SYNC(2 * NG); kstep(t, 0, 3, true);
;     BIG_SYNC(2 * NG); kstep(t + 1, 1, 0, true);
;     BIG_SYNC(2 * NG); kstep(t + 2, 2, 1, true);
;     BIG_SYNC(2 * NG); kstep(t + 3, 3, 2, true);
;   }
;   BIG_SYNC(2 * NG); kstep(NK - 4, 0, 3, true);
;   BIG_SYNC(2 * NG); kstep(NK - 3, 1, 0, false);
;   BIG_SYNC(NG);     kstep(NK - 2, 2, 0, false);
;   BIG_SYNC(0);      kstep(NK - 1, 3, 0, false);
	v_mfma_f32_16x16x32_bf16 v[4:7], v[216:219], v[236:239], v[4:7]
	ds_read_b128 v[232:235], v149 offset:49152
	v_mfma_f32_16x16x32_bf16 v[20:23], v[220:223], v[236:239], v[20:23]
	v_mfma_f32_16x16x32_bf16 v[36:39], v[224:227], v[236:239], v[36:39]
	v_mfma_f32_16x16x32_bf16 v[76:79], v[228:231], v[236:239], v[76:79]
	s_waitcnt lgkmcnt(2)
	v_mfma_f32_16x16x32_bf16 v[8:11], v[216:219], v[240:243], v[8:11]
	ds_read_b128 v[236:239], v149 offset:50176
	v_mfma_f32_16x16x32_bf16 v[24:27], v[220:223], v[240:243], v[24:27]
	v_mfma_f32_16x16x32_bf16 v[40:43], v[224:227], v[240:243], v[40:43]
	v_mfma_f32_16x16x32_bf16 v[84:87], v[228:231], v[240:243], v[84:87]
	s_waitcnt lgkmcnt(2)
	v_mfma_f32_16x16x32_bf16 v[12:15], v[216:219], v[244:247], v[12:15]
	ds_read_b128 v[240:243], v149 offset:51200
	v_mfma_f32_16x16x32_bf16 v[28:31], v[220:223], v[244:247], v[28:31]
	v_mfma_f32_16x16x32_bf16 v[44:47], v[224:227], v[244:247], v[44:47]
	v_mfma_f32_16x16x32_bf16 v[92:95], v[228:231], v[244:247], v[92:95]
	ds_read_b128 v[244:247], v149 offset:52224
	s_waitcnt lgkmcnt(3)
	v_mfma_f32_16x16x32_bf16 v[56:59], v[186:189], v[232:235], v[56:59]
	v_mfma_f32_16x16x32_bf16 v[100:103], v[190:193], v[232:235], v[100:103]
	v_mfma_f32_16x16x32_bf16 v[104:107], v[194:197], v[232:235], v[104:107]
	v_mfma_f32_16x16x32_bf16 v[112:115], v[202:205], v[232:235], v[112:115]
	s_waitcnt vmcnt(4)
	s_barrier
	s_waitcnt lgkmcnt(2)
	v_mfma_f32_16x16x32_bf16 v[64:67], v[186:189], v[236:239], v[64:67]
	ds_read_b128 v[232:235], v149 offset:53248
	v_mfma_f32_16x16x32_bf16 v[80:83], v[190:193], v[236:239], v[80:83]
	v_mfma_f32_16x16x32_bf16 v[96:99], v[194:197], v[236:239], v[96:99]
	v_mfma_f32_16x16x32_bf16 v[116:119], v[202:205], v[236:239], v[116:119]
	s_waitcnt lgkmcnt(2)
	v_mfma_f32_16x16x32_bf16 v[52:55], v[186:189], v[240:243], v[52:55]
	ds_read_b128 v[236:239], v149 offset:54272
	v_mfma_f32_16x16x32_bf16 v[68:71], v[190:193], v[240:243], v[68:71]
	v_mfma_f32_16x16x32_bf16 v[108:111], v[194:197], v[240:243], v[108:111]
	v_mfma_f32_16x16x32_bf16 v[120:123], v[202:205], v[240:243], v[120:123]
	s_waitcnt lgkmcnt(2)
	v_mfma_f32_16x16x32_bf16 v[48:51], v[186:189], v[244:247], v[48:51]
	ds_read_b128 v[240:243], v149 offset:55296
	v_mfma_f32_16x16x32_bf16 v[72:75], v[190:193], v[244:247], v[72:75]
	v_mfma_f32_16x16x32_bf16 v[88:91], v[194:197], v[244:247], v[88:91]
	v_mfma_f32_16x16x32_bf16 v[124:127], v[202:205], v[244:247], v[124:127]
	s_waitcnt lgkmcnt(2)
	v_mfma_f32_16x16x32_bf16 v[0:3], v[186:189], v[232:235], v[0:3]
	ds_read_b128 v[244:247], v149 offset:56320
	v_mfma_f32_16x16x32_bf16 v[16:19], v[190:193], v[232:235], v[16:19]
	v_mfma_f32_16x16x32_bf16 v[32:35], v[194:197], v[232:235], v[32:35]
	v_mfma_f32_16x16x32_bf16 v[60:63], v[202:205], v[232:235], v[60:63]
	s_waitcnt lgkmcnt(2)
	v_mfma_f32_16x16x32_bf16 v[4:7], v[186:189], v[236:239], v[4:7]
	v_mfma_f32_16x16x32_bf16 v[20:23], v[190:193], v[236:239], v[20:23]
	v_mfma_f32_16x16x32_bf16 v[36:39], v[194:197], v[236:239], v[36:39]
	v_mfma_f32_16x16x32_bf16 v[76:79], v[202:205], v[236:239], v[76:79]
	s_waitcnt lgkmcnt(1)
	v_mfma_f32_16x16x32_bf16 v[8:11], v[186:189], v[240:243], v[8:11]
	v_mfma_f32_16x16x32_bf16 v[24:27], v[190:193], v[240:243], v[24:27]
	v_mfma_f32_16x16x32_bf16 v[40:43], v[194:197], v[240:243], v[40:43]
	v_mfma_f32_16x16x32_bf16 v[84:87], v[202:205], v[240:243], v[84:87]
	s_waitcnt lgkmcnt(0)
	v_mfma_f32_16x16x32_bf16 v[12:15], v[186:189], v[244:247], v[12:15]
	v_mfma_f32_16x16x32_bf16 v[28:31], v[190:193], v[244:247], v[28:31]
	v_mfma_f32_16x16x32_bf16 v[44:47], v[194:197], v[244:247], v[44:47]
	v_mfma_f32_16x16x32_bf16 v[92:95], v[202:205], v[244:247], v[92:95]
	v_mov_b32_e32 v186, 0xf149f2ca
	v_mov_b32_e32 v187, 0x3c0881c4
	v_mov_b32_e32 v188, 0xbab64f3b
	v_mov_b32_e32 v189, 0x24800
	v_mov_b32_e32 v190, 1
	v_mov_b32_e32 v191, 0x24804
	v_mov_b32_e32 v192, 0xfcf
	v_mov_b32_e32 v193, 0x7cf
	v_mov_b32_e32 v194, 0xfdf
	v_mov_b32_e32 v195, 0x7df
	v_mov_b32_e32 v196, 0xfef
	v_mov_b32_e32 v197, 0x7ef
	v_mov_b32_e32 v198, 0xfff
	v_mov_b32_e32 v199, 0x7ff
	v_mov_b32_e32 v200, 0x20000
	v_mov_b32_e32 v201, 0xf8f
	v_mov_b32_e32 v202, 0x78f
	v_mov_b32_e32 v203, 0xf9f
	v_mov_b32_e32 v204, 0x79f
	v_mov_b32_e32 v205, 0xfaf
	s_waitcnt vmcnt(4)
	s_barrier
	ds_read_b128 v[134:137], v167
	ds_read_b128 v[138:141], v167 offset:1024
	ds_read_b128 v[154:157], v167 offset:2048
	ds_read_b128 v[158:161], v167 offset:3072
	ds_read_b128 v[162:165], v168
	ds_read_b128 v[166:169], v169
	ds_read_b128 v[216:219], v170
	ds_read_b128 v[220:223], v172
	s_waitcnt lgkmcnt(0)
	v_mfma_f32_16x16x32_bf16 v[56:59], v[134:137], v[162:165], v[56:59]
	v_mfma_f32_16x16x32_bf16 v[64:67], v[134:137], v[166:169], v[64:67]
	v_mfma_f32_16x16x32_bf16 v[52:55], v[134:137], v[216:219], v[52:55]
	v_mfma_f32_16x16x32_bf16 v[48:51], v[134:137], v[220:223], v[48:51]
	v_mfma_f32_16x16x32_bf16 v[100:103], v[138:141], v[162:165], v[100:103]
	v_mfma_f32_16x16x32_bf16 v[80:83], v[138:141], v[166:169], v[80:83]
	v_mfma_f32_16x16x32_bf16 v[68:71], v[138:141], v[216:219], v[68:71]
	v_mfma_f32_16x16x32_bf16 v[72:75], v[138:141], v[220:223], v[72:75]
	v_mfma_f32_16x16x32_bf16 v[96:99], v[154:157], v[166:169], v[96:99]
	v_mfma_f32_16x16x32_bf16 v[112:115], v[158:161], v[162:165], v[112:115]
	v_mfma_f32_16x16x32_bf16 v[224:227], v[154:157], v[162:165], v[104:107]
	v_mfma_f32_16x16x32_bf16 v[228:231], v[154:157], v[216:219], v[108:111]
	v_mfma_f32_16x16x32_bf16 v[232:235], v[154:157], v[220:223], v[88:91]
	v_mfma_f32_16x16x32_bf16 v[162:165], v[158:161], v[166:169], v[116:119]
	v_mfma_f32_16x16x32_bf16 v[166:169], v[158:161], v[216:219], v[120:123]
	v_mfma_f32_16x16x32_bf16 v[216:219], v[158:161], v[220:223], v[124:127]
	ds_read_b128 v[88:91], v173
	ds_read_b128 v[104:107], v174
	ds_read_b128 v[108:111], v175
	ds_read_b128 v[116:119], v178
	s_waitcnt lgkmcnt(0)
	v_mfma_f32_16x16x32_bf16 v[0:3], v[134:137], v[88:91], v[0:3]
	v_mfma_f32_16x16x32_bf16 v[4:7], v[134:137], v[104:107], v[4:7]
	v_mfma_f32_16x16x32_bf16 v[8:11], v[134:137], v[108:111], v[8:11]
	v_mfma_f32_16x16x32_bf16 v[12:15], v[134:137], v[116:119], v[12:15]
	v_mfma_f32_16x16x32_bf16 v[16:19], v[138:141], v[88:91], v[16:19]
	v_mfma_f32_16x16x32_bf16 v[20:23], v[138:141], v[104:107], v[20:23]
	v_mfma_f32_16x16x32_bf16 v[24:27], v[138:141], v[108:111], v[24:27]
	v_mfma_f32_16x16x32_bf16 v[134:137], v[138:141], v[116:119], v[28:31]
	v_mfma_f32_16x16x32_bf16 v[32:35], v[154:157], v[88:91], v[32:35]
	v_mfma_f32_16x16x32_bf16 v[36:39], v[154:157], v[104:107], v[36:39]
	v_mfma_f32_16x16x32_bf16 v[138:141], v[154:157], v[108:111], v[40:43]
	v_mfma_f32_16x16x32_bf16 v[154:157], v[154:157], v[116:119], v[44:47]
	v_mfma_f32_16x16x32_bf16 v[172:175], v[158:161], v[88:91], v[60:63]
	v_mfma_f32_16x16x32_bf16 v[220:223], v[158:161], v[104:107], v[76:79]
	v_mfma_f32_16x16x32_bf16 v[236:239], v[158:161], v[108:111], v[84:87]
	v_mfma_f32_16x16x32_bf16 v[158:161], v[158:161], v[116:119], v[92:95]
	s_waitcnt vmcnt(0)
	s_barrier
; template <int NK, bool BNT = false> ...
;     ...
;     for (int n = 0; n < 4; ++n) bfr[n] = *reinterpret_cast<const bf16x8*>(sa + boff + (4 + n) * 1024);
; #pragma unroll
;     for (int m = 0; m < 4; ++m)
; #pragma unroll
;       for (int n = 0; n < 4; ++n)
;         acc[m][4 + n] = __builtin_amdgcn_mfma_f32_16x16x32_bf16(af[m], bfr[n], acc[m][4 + n], 0, 0, 0);
;     __builtin_amdgcn_sched_barrier(0);
;   };
;     ...
;   stage(0, 0);
;   stage(1, 1);
;   stage(2, 2);
;   for (int it = 0; it < NK / 4 - 1; ++it) {
;     const int t = it * 4;
;     BIG_SYNC(2 * NG); kstep(t, 0, 3, true);
;     BIG_SYNC(2 * NG); kstep(t + 1, 1, 0, true);
;     BIG_SYNC(2 * NG); kstep(t + 2, 2, 1, true);
;     BIG_SYNC(2 * NG); kstep(t + 3, 3, 2, true);
;   }
;   BIG_SYNC(2 * NG); kstep(NK - 4, 0, 3, true);
;   BIG_SYNC(2 * NG); kstep(NK - 3, 1, 0, false);
;   BIG_SYNC(NG);     kstep(NK - 2, 2, 0, false);
;   BIG_SYNC(0);      kstep(NK - 1, 3, 0, false);
; template <int MODE, int NSUB>
; __device__ __forceinline__ void epilogue(const Params& p, int layer, f32x4 (&acc)[4][NSUB], int tm, int tn, int g,
;                                          const float* s_rstd, const int tid_in) {
;     ...
;   if constexpr (MODE == EPI_G1) {
;     const int ft = tm;
; #pragma unroll
;     for (int n = 0; n < NSUB; ++n) {
;       const int nl = wc * (NSUB * 16) + n * 16 + fr;
;       const int t = tn * (NSUB * 32) + nl;
;       const float rs = s_rstd[nl];
;       if (ft < 2) {
; #pragma unroll
;         for (int m = 0; m < 4; ++m) {
;           int gg = ft * 8 + wr * 4 + m;
;           bf16x4 v = pack4(acc[m][n][0] * rs, acc[m][n][1] * rs, acc[m][n][2] * rs, acc[m][n][3] * rs);
;           *reinterpret_cast<bf16x4*>(p.ug + (long)gg * NT * 16 + blk(t >> 5, (t & 31) * 16 + fq * 4, 16)) = v;
;         }
;       } else if (ft < 4) {
; #pragma unroll
;         for (int mp = 0; mp < 2; ++mp) {
;           const int f = (ft - 2) * 128 + wr * 64 + mp * 32 + widen_off(fq);
;           *reinterpret_cast<u32x4*>(p.pbuf + (long)t * 256 + f) =
;               widen_pair(pack4(acc[2 * mp][n][0] * rs, acc[2 * mp][n][1] * rs, acc[2 * mp][n][2] * rs, acc[2 * mp][n][3] * rs),
;                          pack4(acc[2 * mp + 1][n][0] * rs, acc[2 * mp + 1][n][1] * rs, acc[2 * mp + 1][n][2] * rs,
;                                acc[2 * mp + 1][n][3] * rs));
;         }
;       } else if (ft < 6) {
;         float ss = 0.f;
; #pragma unroll
	ds_read_b128 v[40:43], v176
	ds_read_b128 v[28:31], v179
	ds_read_b128 v[44:47], v180
	ds_read_b128 v[60:63], v181
	ds_read_b128 v[240:243], v176 offset:1024
	ds_read_b128 v[244:247], v176 offset:2048
	ds_read_b128 v[248:251], v176 offset:3072
	ds_read_b128 v[178:181], v182
	s_waitcnt lgkmcnt(0)
	v_mfma_f32_16x16x32_bf16 v[124:127], v[40:43], v[28:31], v[56:59]
	v_mfma_f32_16x16x32_bf16 v[108:111], v[40:43], v[44:47], v[64:67]
	v_mfma_f32_16x16x32_bf16 v[92:95], v[40:43], v[60:63], v[52:55]
	v_mfma_f32_16x16x32_bf16 v[76:79], v[40:43], v[178:181], v[48:51]
	v_mfma_f32_16x16x32_bf16 v[120:123], v[240:243], v[28:31], v[100:103]
	v_mfma_f32_16x16x32_bf16 v[104:107], v[240:243], v[44:47], v[80:83]
	v_mfma_f32_16x16x32_bf16 v[88:91], v[240:243], v[60:63], v[68:71]
	v_mfma_f32_16x16x32_bf16 v[72:75], v[240:243], v[178:181], v[72:75]
	v_mfma_f32_16x16x32_bf16 v[116:119], v[244:247], v[28:31], v[224:227]
	v_mfma_f32_16x16x32_bf16 v[100:103], v[244:247], v[44:47], v[96:99]
	v_mfma_f32_16x16x32_bf16 v[84:87], v[244:247], v[60:63], v[228:231]
	v_mfma_f32_16x16x32_bf16 v[68:71], v[244:247], v[178:181], v[232:235]
	v_mfma_f32_16x16x32_bf16 v[112:115], v[248:251], v[28:31], v[112:115]
	v_mfma_f32_16x16x32_bf16 v[96:99], v[248:251], v[44:47], v[162:165]
	v_mfma_f32_16x16x32_bf16 v[80:83], v[248:251], v[60:63], v[166:169]
	v_mfma_f32_16x16x32_bf16 v[64:67], v[248:251], v[178:181], v[216:219]
	ds_read_b128 v[48:51], v142
	ds_read_b128 v[162:165], v143
	s_waitcnt lgkmcnt(0)
	v_mfma_f32_16x16x32_bf16 v[60:63], v[40:43], v[48:51], v[0:3]
	s_nop 2
	ds_read_b128 v[0:3], v144
	ds_read_b128 v[142:145], v145
	v_mfma_f32_16x16x32_bf16 v[44:47], v[40:43], v[162:165], v[4:7]
	s_waitcnt lgkmcnt(0)
	v_mfma_f32_16x16x32_bf16 v[28:31], v[40:43], v[0:3], v[8:11]
	v_mfma_f32_16x16x32_bf16 v[12:15], v[40:43], v[142:145], v[12:15]
	v_mfma_f32_16x16x32_bf16 v[56:59], v[240:243], v[48:51], v[16:19]
	v_mfma_f32_16x16x32_bf16 v[40:43], v[240:243], v[162:165], v[20:23]
	v_mfma_f32_16x16x32_bf16 v[24:27], v[240:243], v[0:3], v[24:27]
	v_mfma_f32_16x16x32_bf16 v[8:11], v[240:243], v[142:145], v[134:137]
	v_mfma_f32_16x16x32_bf16 v[52:55], v[244:247], v[48:51], v[32:35]
	v_mfma_f32_16x16x32_bf16 v[36:39], v[244:247], v[162:165], v[36:39]
	v_mfma_f32_16x16x32_bf16 v[20:23], v[244:247], v[0:3], v[138:141]
	v_mfma_f32_16x16x32_bf16 v[4:7], v[244:247], v[142:145], v[154:157]
	v_mfma_f32_16x16x32_bf16 v[48:51], v[248:251], v[48:51], v[172:175]
	v_mfma_f32_16x16x32_bf16 v[32:35], v[248:251], v[162:165], v[220:223]
	v_mfma_f32_16x16x32_bf16 v[16:19], v[248:251], v[0:3], v[236:239]
	v_mfma_f32_16x16x32_bf16 v[0:3], v[248:251], v[142:145], v[158:161]
	v_mov_b32_e32 v141, v215
	v_lshl_add_u32 v142, s4, 1, v151
	v_and_b32_e32 v140, 15, v141
	v_lshlrev_b32_e32 v134, 1, v141
	v_and_or_b32 v155, v134, s34, v140
	v_lshl_or_b32 v139, v155, 2, v200
	v_and_b32_e32 v134, 16, v141
	v_lshrrev_b32_e32 v138, 2, v141
	ds_read_b32 v146, v139
	v_ashrrev_i32_e32 v136, 7, v141
	v_and_or_b32 v134, v138, 8, v134
	v_lshlrev_b32_e32 v138, 7, v142
	v_lshl_add_u32 v138, v136, 6, v138
	v_bfe_u32 v137, v141, 4, 2
	v_add_u32_e32 v154, 0xfffffe00, v138
	v_or_b32_e32 v138, v138, v134
	v_cmp_lt_i32_e64 s[14:15], 1, v142
	v_cmp_lt_u32_e64 s[12:13], 3, v142
	v_cmp_lt_u32_e64 s[10:11], 5, v142
	v_cmp_ne_u32_e64 s[8:9], 6, v142
	v_cmp_gt_u32_e64 s[6:7], s34, v141
	v_lshlrev_b32_e32 v135, 2, v137
	v_cmp_eq_u32_e64 s[4:5], 0, v137
	v_ashrrev_i32_e32 v137, 31, v136
	v_lshlrev_b32_e32 v152, 1, v142
	v_add_u32_e32 v138, 0xffffff00, v138
	v_or_b32_e32 v144, s48, v155
	s_and_saveexec_b64 s[18:19], s[14:15]
	s_xor_b64 s[36:37], exec, s[18:19]
	s_cbranch_execz .LBB0_323
	s_and_saveexec_b64 s[18:19], s[12:13]
	s_xor_b64 s[38:39], exec, s[18:19]
	s_cbranch_execz .LBB0_320
	s_and_saveexec_b64 s[18:19], s[10:11]
	s_xor_b64 s[40:41], exec, s[18:19]
	s_cbranch_execz .LBB0_315
	s_and_saveexec_b64 s[18:19], s[8:9]
	s_xor_b64 s[42:43], exec, s[18:19]
	s_cbranch_execz .LBB0_310
	s_and_saveexec_b64 s[44:45], s[6:7]
	s_cbranch_execz .LBB0_309
; __device__ __forceinline__ int widen_off(int fq) { return ((fq & 1) << 4) + ((fq >> 1) << 3); }
; template <int MODE, int NSUB>
; __device__ __forceinline__ void epilogue(const Params& p, int layer, f32x4 (&acc)[4][NSUB], int tm, int tn, int g,
;                                          const float* s_rstd, const int tid_in) {
;     ...
;         if (wr == 0) {
;           const int pos = tok_pos(t);
;           float o1[4], o2[4];
; #pragma unroll
;           for (int j = 0; j < 4; ++j) {
;             float2 cs = p.rope[pos * 16 + fq * 4 + j];
;             float x1 = acc[0][n][j] * rs, x2 = acc[1][n][j] * rs;
;             o1[j] = x1 * cs.x - x2 * cs.y;
;             o2[j] = x1 * cs.y + x2 * cs.x;
;           }
;           const u32x4 w = widen_pair(pack4(o1[0], o1[1], o1[2], o1[3]), pack4(o2[0], o2[1], o2[2], o2[3]));
; #pragma unroll
;           for (int hh = 0; hh < 8; ++hh)
;             __builtin_nontemporal_store(w, reinterpret_cast<u32x4*>(p.Kb + ((long)hh * NT + t) * 96 + 64 + widen_off(fq)));
;         }
	s_mov_b32 s17, 0x10000
	v_cmp_gt_i32_e32 vcc, s17, v144
	v_lshlrev_b32_e32 v113, 3, v135
	v_readlane_b32 s64, v254, 51
	v_cndmask_b32_e32 v112, v201, v202, vcc
	v_and_b32_e32 v112, v112, v144
	v_lshl_or_b32 v116, v112, 7, v113
	v_readlane_b32 s70, v254, 57
	v_readlane_b32 s71, v254, 58
	s_nop 4
	global_load_dwordx4 v[112:115], v116, s[70:71] offset:16
	s_nop 0
	global_load_dwordx4 v[116:119], v116, s[70:71]
	v_mov_b32_e32 v161, v121
	v_mov_b32_e32 v121, v125
	v_mov_b32_e32 v160, v124
	s_waitcnt lgkmcnt(0)
	v_pk_mul_f32 v[120:121], v[120:121], v[146:147] op_sel_hi:[1,0]
	v_pk_mul_f32 v[160:161], v[160:161], v[146:147] op_sel_hi:[1,0]
	v_readlane_b32 s65, v254, 52
	v_readlane_b32 s66, v254, 53
	v_readlane_b32 s67, v254, 54
	v_readlane_b32 s68, v254, 55
	v_readlane_b32 s69, v254, 56
	v_readlane_b32 s72, v254, 59
	v_readlane_b32 s73, v254, 60
	v_readlane_b32 s74, v254, 61
	v_readlane_b32 s75, v254, 62
	v_readlane_b32 s76, v254, 63
	v_readlane_b32 s77, v252, 0
	v_readlane_b32 s78, v252, 1
	v_readlane_b32 s79, v252, 2
	v_readlane_b32 s64, v252, 4
	v_readlane_b32 s68, v252, 8
	v_readlane_b32 s69, v252, 9
	s_movk_i32 s17, 0xc0
	v_readlane_b32 s65, v252, 5
	v_readlane_b32 s66, v252, 6
	v_readlane_b32 s67, v252, 7
	v_readlane_b32 s70, v252, 10
	v_readlane_b32 s71, v252, 11
	v_readlane_b32 s72, v252, 12
	v_readlane_b32 s73, v252, 13
	v_readlane_b32 s74, v252, 14
	v_readlane_b32 s75, v252, 15
	v_readlane_b32 s76, v252, 16
	v_readlane_b32 s77, v252, 17
	v_readlane_b32 s78, v252, 18
	v_readlane_b32 s79, v252, 19
	s_waitcnt vmcnt(0)
	v_mov_b32_e32 v159, v114
	v_mov_b32_e32 v124, v116
	v_mov_b32_e32 v125, v119
	v_mov_b32_e32 v156, v117
	v_mov_b32_e32 v157, v118
	v_pk_mul_f32 v[124:125], v[120:121], v[124:125]
	v_mov_b32_e32 v163, v118
	v_pk_fma_f32 v[124:125], v[160:161], v[156:157], v[124:125]
	v_mov_b32_e32 v157, v121
	v_mov_b32_e32 v121, v161
	v_mov_b32_e32 v118, v117
	v_mov_b32_e32 v162, v116
	v_pk_mul_f32 v[116:117], v[120:121], v[118:119]
	v_mov_b32_e32 v118, v126
	v_mov_b32_e32 v119, v123
	v_mov_b32_e32 v123, v127
	v_mov_b32_e32 v156, v160
	v_pk_mul_f32 v[118:119], v[118:119], v[146:147] op_sel_hi:[1,0]
	v_pk_mul_f32 v[120:121], v[122:123], v[146:147] op_sel_hi:[1,0]
	v_mov_b32_e32 v122, v112
	v_mov_b32_e32 v123, v115
	v_pk_fma_f32 v[116:117], v[156:157], v[162:163], v[116:117] neg_lo:[0,0,1] neg_hi:[0,0,1]
	v_pk_mul_f32 v[122:123], v[120:121], v[122:123]
	v_mov_b32_e32 v127, v121
	v_mov_b32_e32 v157, v114
	v_mov_b32_e32 v121, v119
	v_mov_b32_e32 v114, v113
	v_mov_b32_e32 v158, v113
	v_mov_b32_e32 v126, v118
	v_mov_b32_e32 v156, v112
	v_pk_mul_f32 v[112:113], v[120:121], v[114:115]
	v_pk_fma_f32 v[122:123], v[118:119], v[158:159], v[122:123]
	v_pk_fma_f32 v[114:115], v[126:127], v[156:157], v[112:113] neg_lo:[0,0,1] neg_hi:[0,0,1]
	v_cvt_pk_bf16_f32 v112, v116, v117
	v_mov_b64_e32 v[116:117], s[68:69]
	v_mad_i64_i32 v[116:117], s[18:19], v144, s17, v[116:117]
	v_lshlrev_b32_e32 v118, 1, v134
	v_mov_b32_e32 v119, v153
	v_lshl_add_u64 v[116:117], v[116:117], 0, v[118:119]
	s_mov_b32 s17, 0xf00000
	v_cvt_pk_bf16_f32 v113, v114, v115
	v_cvt_pk_bf16_f32 v114, v124, v125
	v_cvt_pk_bf16_f32 v115, v122, v123
	v_add_co_u32_e32 v118, vcc, s17, v116
	v_permlane16_swap_b32_e32 v112, v114
	v_permlane16_swap_b32_e32 v113, v115
	v_addc_co_u32_e32 v119, vcc, 0, v117, vcc
	s_mov_b32 s17, 0x1e00000
	global_store_dwordx4 v[118:119], v[112:115], off offset:128 nt
	v_add_co_u32_e32 v118, vcc, s17, v116
	s_mov_b32 s17, 0x2d00000
	s_nop 0
	v_addc_co_u32_e32 v119, vcc, 0, v117, vcc
	global_store_dwordx4 v[118:119], v[112:115], off offset:128 nt
	v_add_co_u32_e32 v118, vcc, s17, v116
	global_store_dwordx4 v[116:117], v[112:115], off offset:128 nt
	s_nop 0
	v_addc_co_u32_e32 v119, vcc, 0, v117, vcc
	global_store_dwordx4 v[118:119], v[112:115], off offset:128 nt
	v_add_co_u32_e32 v118, vcc, 0x3c00000, v116
	s_nop 1
	v_addc_co_u32_e32 v119, vcc, 0, v117, vcc
	global_store_dwordx4 v[118:119], v[112:115], off offset:128 nt
	v_add_co_u32_e32 v118, vcc, 0x4b00000, v116
	s_nop 1
	v_addc_co_u32_e32 v119, vcc, 0, v117, vcc
	global_store_dwordx4 v[118:119], v[112:115], off offset:128 nt
	v_add_co_u32_e32 v118, vcc, 0x5a00000, v116
	s_nop 1
	v_addc_co_u32_e32 v119, vcc, 0, v117, vcc
	v_add_co_u32_e32 v116, vcc, 0x6900000, v116
	global_store_dwordx4 v[118:119], v[112:115], off offset:128 nt
	s_nop 0
	v_addc_co_u32_e32 v117, vcc, 0, v117, vcc
	global_store_dwordx4 v[116:117], v[112:115], off offset:128 nt
